# static s_setprio 1 for workgroups 256..511 (the co-resident second workgroup of each CU); dead SGPR reloads dropped in PEER value pass
# baseline (speedup 1.0000x reference)
; extern "C" __global__ void __launch_bounds__(NTHREADS, 2) mega(Params p) {
;   cg::grid_group grid = cg::this_grid();
;   extern __shared__ __attribute__((aligned(16))) unsigned char smem[];
;   volatile unsigned* st = (volatile unsigned*)(smem + SMEM_BYTES - 16);
;   if (threadIdx.x < 2) st[threadIdx.x] = 0u;
;   __syncthreads();
mega:
	s_load_dword s52, s[0:1], 0x9f0
	s_add_u32 s54, s0, 0x9f0
	v_and_b32_e32 v248, 0x3ff, v0
	v_writelane_b32 v252, s2, 0
	s_cmpk_ge_u32 s2, 0x100
	s_cbranch_scc0 .Lnoprio
	s_setprio 1
.Lnoprio:
	s_addc_u32 s55, s1, 0
	v_cmp_gt_u32_e32 vcc, 2, v248
	s_and_saveexec_b64 s[2:3], vcc
	s_cbranch_execz .LBB0_2
	s_mov_b64 s[4:5], src_shared_base
	s_add_i32 s4, 0, 0x10880
	v_lshl_add_u32 v2, v248, 2, s4
	v_mov_b32_e32 v3, s5
	v_mov_b32_e32 v1, 0
	flat_store_dword v[2:3], v1 sc0 sc1
	s_waitcnt vmcnt(0)

; __device__ void phase_experts(const Params& p, int l) {
;     ...
;     const int tokn = min(tok + tstep, T_TOK - 1);
;     const int idn0 = p.pidx[(size_t)tokn * 128 + lane], idn1 = p.pidx[(size_t)tokn * 128 + 64 + lane];
;     f32x4 xn[4];
; #pragma unroll
;     for (int c = 0; c < 4; ++c) xn[c] = *(const f32x4*)(p.xcur + (size_t)tokn * 1024 + lane * 16 + c * 4);
;     const float g0 = p.pgate[(size_t)tok * 128 + lane], g1 = p.pgate[(size_t)tok * 128 + 64 + lane];
;     float hv[16];
;     float ss = 0.f;
; #pragma unroll
;     for (int c = 0; c < 4; ++c)
; #pragma unroll
;       for (int e = 0; e < 4; ++e) ss += xr[c][e] * xr[c][e];
;     ss = wave_sum(ss);
;     const float rstd = rsqrtf(ss * (1.f / 1024.f) + 1e-6f);
; #pragma unroll
;     for (int c = 0; c < 4; ++c) {
;       const f32x4 g = *(const f32x4*)(gf + lane * 16 + c * 4);
; #pragma unroll
;       for (int e = 0; e < 4; ++e) hv[c * 4 + e] = xr[c][e] * rstd * g[e];
;     }
;     float d0 = 0.f, d1 = 0.f;
; #pragma unroll
;     for (int bi = 0; bi < 8; ++bi) {
;       {
;         const int nb = (bi + 1) & 7;
;         const int idv = bi == 7 ? idn0 : (nb < 4 ? id0 : id1);
; #pragma unroll
;         for (int j = 0; j < 16; ++j) {
;           const int row = __builtin_amdgcn_readlane(idv, (nb & 3) * 16 + j);
;           rbuf[(bi + 1) & 1][j] = *(const u32x4*)(U + (size_t)row * 1024 + lane * 16);
;         }
;       }
;       u32x4 (&ru)[16] = rbuf[bi & 1];
;       float sj[16];
; #pragma unroll
;       for (int j = 0; j < 16; ++j) {
;         float acc = 0.f;
; #pragma unroll
;         for (int c = 0; c < 4; ++c) {
;           const f32x2 a = __builtin_amdgcn_cvt_pk_f32_fp8((int)ru[j][c], false), b2 = __builtin_amdgcn_cvt_pk_f32_fp8((int)ru[j][c], true);
;           acc += a.x * hv[c * 4] + a.y * hv[c * 4 + 1] + b2.x * hv[c * 4 + 2] + b2.y * hv[c * 4 + 3];
;         }
.LBB0_1179:
	s_waitcnt vmcnt(1)
	v_mul_f32_e32 v102, v95, v95
	v_fmac_f32_e32 v102, v94, v94
	v_fmac_f32_e32 v102, v96, v96
	v_fmac_f32_e32 v102, v97, v97
	v_fmac_f32_e32 v102, v90, v90
	v_fmac_f32_e32 v102, v91, v91
	v_fmac_f32_e32 v102, v92, v92
	v_readlane_b32 s0, v253, 17
	v_fmac_f32_e32 v102, v93, v93
	v_fmac_f32_e32 v102, v86, v86
	v_add_u32_e32 v178, s0, v178
	v_min_i32_e32 v2, 0x3fff, v178
	v_fmac_f32_e32 v102, v87, v87
	v_ashrrev_i32_e32 v3, 31, v2
	v_fmac_f32_e32 v102, v88, v88
	v_lshlrev_b64 v[4:5], 9, v[2:3]
	v_lshlrev_b64 v[2:3], 12, v[2:3]
	v_fmac_f32_e32 v102, v89, v89
	v_pk_mul_f32 v[100:101], v[78:79], v[78:79]
	v_lshl_add_u64 v[4:5], v[184:185], 0, v[4:5]
	v_lshl_add_u64 v[14:15], v[186:187], 0, v[2:3]
	v_lshl_add_u64 v[98:99], s[66:67], 0, v[180:181]
	v_add_f32_e32 v100, v100, v102
	v_mov_b32_e32 v228, v203
	global_load_dword v203, v[4:5], off
	global_load_dword v0, v[4:5], off offset:256
	s_nop 0
	global_load_dwordx4 v[2:5], v[14:15], off offset:48
	global_load_dwordx4 v[6:9], v[14:15], off offset:32
	global_load_dwordx4 v[10:13], v[14:15], off offset:16
	s_nop 0
	global_load_dwordx4 v[14:17], v[14:15], off
	s_nop 0
	global_load_dword v210, v[98:99], off
	global_load_dword v209, v[98:99], off offset:256
	v_pk_mul_f32 v[98:99], v[80:81], v[80:81]
	v_add_f32_e32 v100, v101, v100
	v_add_f32_e32 v98, v98, v100
	v_add_f32_e32 v98, v99, v98
	ds_bpermute_b32 v99, v179, v98
	v_cvt_pk_f32_fp8_e32 v[118:119], v82
	v_cvt_pk_f32_fp8_sdwa v[120:121], v82 src0_sel:WORD_1
	v_readlane_b32 s0, v228, 16
	s_waitcnt lgkmcnt(0)
	v_add_f32_e32 v98, v98, v99
	ds_bpermute_b32 v99, v204, v98
	s_ashr_i32 s1, s0, 31
	s_lshl_b64 s[0:1], s[0:1], 10
	s_waitcnt lgkmcnt(0)
	v_add_f32_e32 v98, v98, v99
	ds_bpermute_b32 v99, v205, v98
	s_waitcnt lgkmcnt(0)
	v_add_f32_e32 v98, v98, v99
	ds_bpermute_b32 v99, v206, v98
	s_waitcnt lgkmcnt(0)
	v_add_f32_e32 v98, v98, v99
	ds_bpermute_b32 v99, v207, v98
	s_waitcnt lgkmcnt(0)
	v_add_f32_e32 v98, v98, v99
	ds_bpermute_b32 v99, v208, v98
	s_waitcnt lgkmcnt(0)
	v_add_f32_e32 v98, v98, v99
	v_fmamk_f32 v98, v98, 0x3a800000, v190
	v_cmp_gt_f32_e64 s[18:19], s45, v98
	v_mul_f32_e32 v99, 0x4b800000, v98
	s_nop 0
	v_cndmask_b32_e64 v98, v98, v99, s[18:19]
	v_rsq_f32_e32 v98, v98
	s_nop 0
	v_mul_f32_e32 v99, 0x45800000, v98
	v_cndmask_b32_e64 v110, v98, v99, s[18:19]
	global_load_dwordx4 v[98:101], v[188:189], off offset:48
	global_load_dwordx4 v[102:105], v[188:189], off offset:32
	global_load_dwordx4 v[106:109], v[188:189], off offset:16
	global_load_dwordx4 v[112:115], v[188:189], off
	v_mul_f32_e32 v94, v94, v110
	v_mul_f32_e32 v90, v90, v110
	v_mul_f32_e32 v86, v86, v110
	v_mul_f32_e32 v78, v78, v110
	s_waitcnt vmcnt(3)
	v_mul_f32_e32 v219, v98, v78
	s_waitcnt vmcnt(2)
	v_mul_f32_e32 v214, v102, v86
	s_waitcnt vmcnt(1)
	v_mul_f32_e32 v218, v106, v90
	s_waitcnt vmcnt(0)
	v_mul_f32_e32 v225, v112, v94
	v_mul_f32_e32 v94, v95, v110
	v_mul_f32_e32 v226, v113, v94
	v_mul_f32_e32 v94, v96, v110
	v_mul_f32_e32 v82, v226, v119
	v_mul_f32_e32 v220, v114, v94
	v_mul_f32_e32 v94, v97, v110
	v_fmac_f32_e32 v82, v225, v118
	v_mul_f32_e32 v223, v115, v94
	v_fmac_f32_e32 v82, v220, v120
	v_cvt_pk_f32_fp8_e32 v[118:119], v83
	v_fmac_f32_e32 v82, v223, v121
	v_mul_f32_e32 v90, v91, v110
	v_add_f32_e32 v120, 0, v82
	v_cvt_pk_f32_fp8_sdwa v[82:83], v83 src0_sel:WORD_1
	v_mul_f32_e32 v222, v107, v90
	v_mul_f32_e32 v90, v92, v110
	v_mul_f32_e32 v119, v222, v119
	v_mul_f32_e32 v215, v108, v90
	v_mul_f32_e32 v90, v93, v110
	v_fmac_f32_e32 v119, v218, v118
	v_mul_f32_e32 v217, v109, v90
	v_fmac_f32_e32 v119, v215, v82
	v_fmac_f32_e32 v119, v217, v83
	v_cvt_pk_f32_fp8_e32 v[82:83], v84
	v_mul_f32_e32 v86, v87, v110
	v_add_f32_e32 v120, v120, v119
	v_cvt_pk_f32_fp8_sdwa v[118:119], v84 src0_sel:WORD_1
	v_mul_f32_e32 v216, v103, v86
	v_mul_f32_e32 v86, v88, v110
	v_mul_f32_e32 v83, v216, v83
	v_mul_f32_e32 v211, v104, v86
	v_mul_f32_e32 v86, v89, v110
	v_fmac_f32_e32 v83, v214, v82
	v_mul_f32_e32 v224, v105, v86
	v_fmac_f32_e32 v83, v211, v118
	v_fmac_f32_e32 v83, v224, v119
	v_add_f32_e32 v118, v120, v83
	v_cvt_pk_f32_fp8_e32 v[82:83], v85
	v_mul_f32_e32 v78, v79, v110
	v_cvt_pk_f32_fp8_sdwa v[84:85], v85 src0_sel:WORD_1
	v_mul_f32_e32 v221, v99, v78
	v_mul_f32_e32 v78, v80, v110
	v_mul_f32_e32 v83, v221, v83
	v_mul_f32_e32 v212, v100, v78
	v_mul_f32_e32 v78, v81, v110
	v_fmac_f32_e32 v83, v219, v82
	v_mul_f32_e32 v213, v101, v78
	v_fmac_f32_e32 v83, v212, v84
	v_fmac_f32_e32 v83, v213, v85
	v_cvt_pk_f32_fp8_e32 v[84:85], v74
	v_add_f32_e32 v82, v118, v83
	v_cvt_pk_f32_fp8_sdwa v[118:119], v74 src0_sel:WORD_1
	v_lshl_add_u64 v[78:79], v[182:183], 0, s[0:1]
	v_mul_f32_e32 v74, v226, v85
	v_fmac_f32_e32 v74, v225, v84
	v_fmac_f32_e32 v74, v220, v118
	v_cvt_pk_f32_fp8_e32 v[84:85], v75
	v_fmac_f32_e32 v74, v223, v119
	v_add_f32_e32 v83, 0, v74
	v_cvt_pk_f32_fp8_sdwa v[74:75], v75 src0_sel:WORD_1
	v_mul_f32_e32 v85, v222, v85
	v_fmac_f32_e32 v85, v218, v84
	v_readlane_b32 s0, v228, 17
	v_fmac_f32_e32 v85, v215, v74
	v_fmac_f32_e32 v85, v217, v75
	v_cvt_pk_f32_fp8_e32 v[74:75], v76
	v_add_f32_e32 v83, v83, v85
	v_cvt_pk_f32_fp8_sdwa v[84:85], v76 src0_sel:WORD_1
	s_ashr_i32 s1, s0, 31
	v_mul_f32_e32 v75, v216, v75
	v_fmac_f32_e32 v75, v214, v74
	v_fmac_f32_e32 v75, v211, v84
	v_fmac_f32_e32 v75, v224, v85
	v_add_f32_e32 v83, v83, v75
	v_cvt_pk_f32_fp8_e32 v[74:75], v77
	v_cvt_pk_f32_fp8_sdwa v[76:77], v77 src0_sel:WORD_1
	v_cvt_pk_f32_fp8_sdwa v[84:85], v70 src0_sel:WORD_1
	s_lshl_b64 s[0:1], s[0:1], 10
	v_mul_f32_e32 v75, v221, v75
	v_fmac_f32_e32 v75, v219, v74
	v_fmac_f32_e32 v75, v212, v76
	v_fmac_f32_e32 v75, v213, v77
; __device__ void phase_experts(const Params& p, int l) {
;     ...
;     for (int bi = 0; bi < 8; ++bi) {
;       {
;         const int nb = (bi + 1) & 7;
;         const int idv = bi == 7 ? idn0 : (nb < 4 ? id0 : id1);
; #pragma unroll
;         for (int j = 0; j < 16; ++j) {
;           const int row = __builtin_amdgcn_readlane(idv, (nb & 3) * 16 + j);
;           rbuf[(bi + 1) & 1][j] = *(const u32x4*)(U + (size_t)row * 1024 + lane * 16);
;         }
;       }
;       u32x4 (&ru)[16] = rbuf[bi & 1];
;       float sj[16];
; #pragma unroll
;       for (int j = 0; j < 16; ++j) {
;         float acc = 0.f;
; #pragma unroll
;         for (int c = 0; c < 4; ++c) {
;           const f32x2 a = __builtin_amdgcn_cvt_pk_f32_fp8((int)ru[j][c], false), b2 = __builtin_amdgcn_cvt_pk_f32_fp8((int)ru[j][c], true);
;           acc += a.x * hv[c * 4] + a.y * hv[c * 4 + 1] + b2.x * hv[c * 4 + 2] + b2.y * hv[c * 4 + 3];
;         }
;         sj[j] = acc;
	v_cvt_pk_f32_fp8_e32 v[76:77], v70
	v_add_f32_e32 v74, v83, v75
	global_load_dwordx4 v[170:173], v[78:79], off
	v_lshl_add_u64 v[78:79], v[182:183], 0, s[0:1]
	v_mul_f32_e32 v70, v226, v77
	v_fmac_f32_e32 v70, v225, v76
	v_fmac_f32_e32 v70, v220, v84
	v_cvt_pk_f32_fp8_e32 v[76:77], v71
	v_fmac_f32_e32 v70, v223, v85
	v_add_f32_e32 v75, 0, v70
	v_cvt_pk_f32_fp8_sdwa v[70:71], v71 src0_sel:WORD_1
	v_mul_f32_e32 v77, v222, v77
	v_fmac_f32_e32 v77, v218, v76
	v_readlane_b32 s0, v228, 18
	v_fmac_f32_e32 v77, v215, v70
	v_fmac_f32_e32 v77, v217, v71
	v_cvt_pk_f32_fp8_e32 v[70:71], v72
	v_add_f32_e32 v75, v75, v77
	v_cvt_pk_f32_fp8_sdwa v[76:77], v72 src0_sel:WORD_1
	s_ashr_i32 s1, s0, 31
	v_mul_f32_e32 v71, v216, v71
	v_fmac_f32_e32 v71, v214, v70
	v_fmac_f32_e32 v71, v211, v76
	v_fmac_f32_e32 v71, v224, v77
	v_add_f32_e32 v75, v75, v71
	v_cvt_pk_f32_fp8_e32 v[70:71], v73
	v_cvt_pk_f32_fp8_sdwa v[72:73], v73 src0_sel:WORD_1
	v_cvt_pk_f32_fp8_sdwa v[76:77], v66 src0_sel:WORD_1
	s_lshl_b64 s[0:1], s[0:1], 10
	v_mul_f32_e32 v71, v221, v71
	v_fmac_f32_e32 v71, v219, v70
	v_fmac_f32_e32 v71, v212, v72
	v_fmac_f32_e32 v71, v213, v73
	v_cvt_pk_f32_fp8_e32 v[72:73], v66
	v_add_f32_e32 v70, v75, v71
	v_lshl_add_u64 v[86:87], v[182:183], 0, s[0:1]
	v_readlane_b32 s0, v228, 19
	v_mul_f32_e32 v66, v226, v73
	v_fmac_f32_e32 v66, v225, v72
	v_fmac_f32_e32 v66, v220, v76
	v_cvt_pk_f32_fp8_e32 v[72:73], v67
	v_fmac_f32_e32 v66, v223, v77
	v_add_f32_e32 v71, 0, v66
	v_cvt_pk_f32_fp8_sdwa v[66:67], v67 src0_sel:WORD_1
	v_mul_f32_e32 v73, v222, v73
	v_fmac_f32_e32 v73, v218, v72
	s_ashr_i32 s1, s0, 31
	v_fmac_f32_e32 v73, v215, v66
	v_fmac_f32_e32 v73, v217, v67
	v_cvt_pk_f32_fp8_e32 v[66:67], v68
	v_add_f32_e32 v71, v71, v73
	v_cvt_pk_f32_fp8_sdwa v[72:73], v68 src0_sel:WORD_1
	s_lshl_b64 s[0:1], s[0:1], 10
	v_mul_f32_e32 v67, v216, v67
	v_fmac_f32_e32 v67, v214, v66
	v_fmac_f32_e32 v67, v211, v72
	v_fmac_f32_e32 v67, v224, v73
	v_add_f32_e32 v71, v71, v67
	v_cvt_pk_f32_fp8_e32 v[66:67], v69
	v_cvt_pk_f32_fp8_sdwa v[68:69], v69 src0_sel:WORD_1
	v_cvt_pk_f32_fp8_sdwa v[72:73], v62 src0_sel:WORD_1
	global_load_dwordx4 v[162:165], v[86:87], off
	v_mul_f32_e32 v67, v221, v67
	v_fmac_f32_e32 v67, v219, v66
	v_fmac_f32_e32 v67, v212, v68
	v_fmac_f32_e32 v67, v213, v69
	v_cvt_pk_f32_fp8_e32 v[68:69], v62
	v_add_f32_e32 v66, v71, v67
	v_lshl_add_u64 v[86:87], v[182:183], 0, s[0:1]
	v_readlane_b32 s0, v228, 20
	v_mul_f32_e32 v62, v226, v69
	v_fmac_f32_e32 v62, v225, v68
	v_fmac_f32_e32 v62, v220, v72
	v_cvt_pk_f32_fp8_e32 v[68:69], v63
	v_fmac_f32_e32 v62, v223, v73
	v_add_f32_e32 v67, 0, v62
	v_cvt_pk_f32_fp8_sdwa v[62:63], v63 src0_sel:WORD_1
	v_mul_f32_e32 v69, v222, v69
	v_fmac_f32_e32 v69, v218, v68
	s_ashr_i32 s1, s0, 31
	v_fmac_f32_e32 v69, v215, v62
	v_fmac_f32_e32 v69, v217, v63
	v_cvt_pk_f32_fp8_e32 v[62:63], v64
	v_add_f32_e32 v67, v67, v69
	v_cvt_pk_f32_fp8_sdwa v[68:69], v64 src0_sel:WORD_1
	s_lshl_b64 s[0:1], s[0:1], 10
	v_mul_f32_e32 v63, v216, v63
	v_fmac_f32_e32 v63, v214, v62
	v_fmac_f32_e32 v63, v211, v68
	v_fmac_f32_e32 v63, v224, v69
	v_add_f32_e32 v67, v67, v63
	v_cvt_pk_f32_fp8_e32 v[62:63], v65
	v_cvt_pk_f32_fp8_sdwa v[64:65], v65 src0_sel:WORD_1
	v_cvt_pk_f32_fp8_sdwa v[68:69], v58 src0_sel:WORD_1
	global_load_dwordx4 v[154:157], v[86:87], off
	v_mul_f32_e32 v63, v221, v63
	v_fmac_f32_e32 v63, v219, v62
	v_fmac_f32_e32 v63, v212, v64
	v_fmac_f32_e32 v63, v213, v65
	v_cvt_pk_f32_fp8_e32 v[64:65], v58
	v_add_f32_e32 v62, v67, v63
	v_lshl_add_u64 v[86:87], v[182:183], 0, s[0:1]
	v_readlane_b32 s0, v228, 21
	v_mul_f32_e32 v58, v226, v65
	v_fmac_f32_e32 v58, v225, v64
	v_fmac_f32_e32 v58, v220, v68
	v_cvt_pk_f32_fp8_e32 v[64:65], v59
	v_fmac_f32_e32 v58, v223, v69
	v_add_f32_e32 v63, 0, v58
	v_cvt_pk_f32_fp8_sdwa v[58:59], v59 src0_sel:WORD_1
	v_mul_f32_e32 v65, v222, v65
	v_fmac_f32_e32 v65, v218, v64
	s_ashr_i32 s1, s0, 31
	v_fmac_f32_e32 v65, v215, v58
	v_fmac_f32_e32 v65, v217, v59
	v_cvt_pk_f32_fp8_e32 v[58:59], v60
	v_add_f32_e32 v63, v63, v65
	v_cvt_pk_f32_fp8_sdwa v[64:65], v60 src0_sel:WORD_1
	s_lshl_b64 s[0:1], s[0:1], 10
	v_mul_f32_e32 v59, v216, v59
	v_fmac_f32_e32 v59, v214, v58
	v_fmac_f32_e32 v59, v211, v64
	v_fmac_f32_e32 v59, v224, v65
	v_add_f32_e32 v63, v63, v59
	v_cvt_pk_f32_fp8_e32 v[58:59], v61
	v_cvt_pk_f32_fp8_sdwa v[60:61], v61 src0_sel:WORD_1
	v_cvt_pk_f32_fp8_sdwa v[64:65], v54 src0_sel:WORD_1
	global_load_dwordx4 v[146:149], v[86:87], off
	v_mul_f32_e32 v59, v221, v59
	v_fmac_f32_e32 v59, v219, v58
	v_fmac_f32_e32 v59, v212, v60
	v_fmac_f32_e32 v59, v213, v61
	v_cvt_pk_f32_fp8_e32 v[60:61], v54
	v_add_f32_e32 v58, v63, v59
	v_lshl_add_u64 v[86:87], v[182:183], 0, s[0:1]
	v_readlane_b32 s0, v228, 22
	v_mul_f32_e32 v54, v226, v61
	v_fmac_f32_e32 v54, v225, v60
	v_fmac_f32_e32 v54, v220, v64
	v_cvt_pk_f32_fp8_e32 v[60:61], v55
	v_fmac_f32_e32 v54, v223, v65
	v_add_f32_e32 v59, 0, v54
	v_cvt_pk_f32_fp8_sdwa v[54:55], v55 src0_sel:WORD_1
	v_mul_f32_e32 v61, v222, v61
	v_fmac_f32_e32 v61, v218, v60
	s_ashr_i32 s1, s0, 31
	v_fmac_f32_e32 v61, v215, v54
	v_fmac_f32_e32 v61, v217, v55
	v_cvt_pk_f32_fp8_e32 v[54:55], v56
	v_add_f32_e32 v59, v59, v61
	v_cvt_pk_f32_fp8_sdwa v[60:61], v56 src0_sel:WORD_1
	s_lshl_b64 s[0:1], s[0:1], 10
	v_mul_f32_e32 v55, v216, v55
	v_fmac_f32_e32 v55, v214, v54
	v_fmac_f32_e32 v55, v211, v60
	v_fmac_f32_e32 v55, v224, v61
	v_add_f32_e32 v59, v59, v55
	v_cvt_pk_f32_fp8_e32 v[54:55], v57
	v_cvt_pk_f32_fp8_sdwa v[56:57], v57 src0_sel:WORD_1
	v_cvt_pk_f32_fp8_sdwa v[60:61], v50 src0_sel:WORD_1
	global_load_dwordx4 v[138:141], v[86:87], off
	v_mul_f32_e32 v55, v221, v55
	v_fmac_f32_e32 v55, v219, v54
; __device__ void phase_experts(const Params& p, int l) {
;     ...
;     for (int bi = 0; bi < 8; ++bi) {
;       {
;         const int nb = (bi + 1) & 7;
;         const int idv = bi == 7 ? idn0 : (nb < 4 ? id0 : id1);
; #pragma unroll
;         for (int j = 0; j < 16; ++j) {
;           const int row = __builtin_amdgcn_readlane(idv, (nb & 3) * 16 + j);
;           rbuf[(bi + 1) & 1][j] = *(const u32x4*)(U + (size_t)row * 1024 + lane * 16);
;         }
;       }
;       u32x4 (&ru)[16] = rbuf[bi & 1];
;       float sj[16];
; #pragma unroll
;       for (int j = 0; j < 16; ++j) {
;         float acc = 0.f;
; #pragma unroll
;         for (int c = 0; c < 4; ++c) {
;           const f32x2 a = __builtin_amdgcn_cvt_pk_f32_fp8((int)ru[j][c], false), b2 = __builtin_amdgcn_cvt_pk_f32_fp8((int)ru[j][c], true);
;           acc += a.x * hv[c * 4] + a.y * hv[c * 4 + 1] + b2.x * hv[c * 4 + 2] + b2.y * hv[c * 4 + 3];
;         }
;         sj[j] = acc;
	v_fmac_f32_e32 v55, v212, v56
	v_fmac_f32_e32 v55, v213, v57
	v_cvt_pk_f32_fp8_e32 v[56:57], v50
	v_add_f32_e32 v54, v59, v55
	v_lshl_add_u64 v[86:87], v[182:183], 0, s[0:1]
	v_readlane_b32 s0, v228, 23
	v_mul_f32_e32 v50, v226, v57
	v_fmac_f32_e32 v50, v225, v56
	v_fmac_f32_e32 v50, v220, v60
	v_cvt_pk_f32_fp8_e32 v[56:57], v51
	v_fmac_f32_e32 v50, v223, v61
	v_add_f32_e32 v55, 0, v50
	v_cvt_pk_f32_fp8_sdwa v[50:51], v51 src0_sel:WORD_1
	v_mul_f32_e32 v57, v222, v57
	v_fmac_f32_e32 v57, v218, v56
	s_ashr_i32 s1, s0, 31
	v_fmac_f32_e32 v57, v215, v50
	v_fmac_f32_e32 v57, v217, v51
	v_cvt_pk_f32_fp8_e32 v[50:51], v52
	v_add_f32_e32 v55, v55, v57
	v_cvt_pk_f32_fp8_sdwa v[56:57], v52 src0_sel:WORD_1
	s_lshl_b64 s[0:1], s[0:1], 10
	v_mul_f32_e32 v51, v216, v51
	v_fmac_f32_e32 v51, v214, v50
	v_fmac_f32_e32 v51, v211, v56
	v_fmac_f32_e32 v51, v224, v57
	v_add_f32_e32 v55, v55, v51
	v_cvt_pk_f32_fp8_e32 v[50:51], v53
	v_cvt_pk_f32_fp8_sdwa v[52:53], v53 src0_sel:WORD_1
	v_cvt_pk_f32_fp8_sdwa v[56:57], v46 src0_sel:WORD_1
	global_load_dwordx4 v[130:133], v[86:87], off
	v_mul_f32_e32 v51, v221, v51
	v_fmac_f32_e32 v51, v219, v50
	v_fmac_f32_e32 v51, v212, v52
	v_fmac_f32_e32 v51, v213, v53
	v_cvt_pk_f32_fp8_e32 v[52:53], v46
	v_add_f32_e32 v50, v55, v51
	v_lshl_add_u64 v[86:87], v[182:183], 0, s[0:1]
	v_readlane_b32 s0, v228, 24
	v_mul_f32_e32 v46, v226, v53
	v_fmac_f32_e32 v46, v225, v52
	v_fmac_f32_e32 v46, v220, v56
	v_cvt_pk_f32_fp8_e32 v[52:53], v47
	v_fmac_f32_e32 v46, v223, v57
	v_add_f32_e32 v51, 0, v46
	v_cvt_pk_f32_fp8_sdwa v[46:47], v47 src0_sel:WORD_1
	v_mul_f32_e32 v53, v222, v53
	v_fmac_f32_e32 v53, v218, v52
	s_ashr_i32 s1, s0, 31
	v_fmac_f32_e32 v53, v215, v46
	v_fmac_f32_e32 v53, v217, v47
	v_cvt_pk_f32_fp8_e32 v[46:47], v48
	v_add_f32_e32 v51, v51, v53
	v_cvt_pk_f32_fp8_sdwa v[52:53], v48 src0_sel:WORD_1
	s_lshl_b64 s[0:1], s[0:1], 10
	v_mul_f32_e32 v47, v216, v47
	v_fmac_f32_e32 v47, v214, v46
	v_fmac_f32_e32 v47, v211, v52
	v_fmac_f32_e32 v47, v224, v53
	v_add_f32_e32 v51, v51, v47
	v_cvt_pk_f32_fp8_e32 v[46:47], v49
	v_cvt_pk_f32_fp8_sdwa v[48:49], v49 src0_sel:WORD_1
	v_cvt_pk_f32_fp8_sdwa v[52:53], v42 src0_sel:WORD_1
	global_load_dwordx4 v[122:125], v[86:87], off
	v_mul_f32_e32 v47, v221, v47
	v_fmac_f32_e32 v47, v219, v46
	v_fmac_f32_e32 v47, v212, v48
	v_fmac_f32_e32 v47, v213, v49
	v_cvt_pk_f32_fp8_e32 v[48:49], v42
	v_add_f32_e32 v46, v51, v47
	v_lshl_add_u64 v[86:87], v[182:183], 0, s[0:1]
	v_readlane_b32 s0, v228, 25
	v_mul_f32_e32 v42, v226, v49
	v_fmac_f32_e32 v42, v225, v48
	v_fmac_f32_e32 v42, v220, v52
	v_cvt_pk_f32_fp8_e32 v[48:49], v43
	v_fmac_f32_e32 v42, v223, v53
	v_add_f32_e32 v47, 0, v42
	v_cvt_pk_f32_fp8_sdwa v[42:43], v43 src0_sel:WORD_1
	v_mul_f32_e32 v49, v222, v49
	v_fmac_f32_e32 v49, v218, v48
	s_ashr_i32 s1, s0, 31
	v_fmac_f32_e32 v49, v215, v42
	v_fmac_f32_e32 v49, v217, v43
	v_cvt_pk_f32_fp8_e32 v[42:43], v44
	v_add_f32_e32 v47, v47, v49
	v_cvt_pk_f32_fp8_sdwa v[48:49], v44 src0_sel:WORD_1
	s_lshl_b64 s[0:1], s[0:1], 10
	v_mul_f32_e32 v43, v216, v43
	v_fmac_f32_e32 v43, v214, v42
	v_fmac_f32_e32 v43, v211, v48
	v_fmac_f32_e32 v43, v224, v49
	v_add_f32_e32 v47, v47, v43
	v_cvt_pk_f32_fp8_e32 v[42:43], v45
	v_cvt_pk_f32_fp8_sdwa v[44:45], v45 src0_sel:WORD_1
	v_cvt_pk_f32_fp8_sdwa v[48:49], v38 src0_sel:WORD_1
	global_load_dwordx4 v[114:117], v[86:87], off
	v_mul_f32_e32 v43, v221, v43
	v_fmac_f32_e32 v43, v219, v42
	v_fmac_f32_e32 v43, v212, v44
	v_fmac_f32_e32 v43, v213, v45
	v_cvt_pk_f32_fp8_e32 v[44:45], v38
	v_add_f32_e32 v42, v47, v43
	v_lshl_add_u64 v[86:87], v[182:183], 0, s[0:1]
	v_readlane_b32 s0, v228, 26
	v_mul_f32_e32 v38, v226, v45
	v_fmac_f32_e32 v38, v225, v44
	v_fmac_f32_e32 v38, v220, v48
	v_cvt_pk_f32_fp8_e32 v[44:45], v39
	v_fmac_f32_e32 v38, v223, v49
	v_add_f32_e32 v43, 0, v38
	v_cvt_pk_f32_fp8_sdwa v[38:39], v39 src0_sel:WORD_1
	v_mul_f32_e32 v45, v222, v45
	v_fmac_f32_e32 v45, v218, v44
	s_ashr_i32 s1, s0, 31
	v_fmac_f32_e32 v45, v215, v38
	v_fmac_f32_e32 v45, v217, v39
	v_cvt_pk_f32_fp8_e32 v[38:39], v40
	v_add_f32_e32 v43, v43, v45
	v_cvt_pk_f32_fp8_sdwa v[44:45], v40 src0_sel:WORD_1
	s_lshl_b64 s[0:1], s[0:1], 10
	v_mul_f32_e32 v39, v216, v39
	v_fmac_f32_e32 v39, v214, v38
	v_fmac_f32_e32 v39, v211, v44
	v_fmac_f32_e32 v39, v224, v45
	v_add_f32_e32 v43, v43, v39
	v_cvt_pk_f32_fp8_e32 v[38:39], v41
	v_cvt_pk_f32_fp8_sdwa v[40:41], v41 src0_sel:WORD_1
	v_cvt_pk_f32_fp8_sdwa v[44:45], v34 src0_sel:WORD_1
	v_lshl_add_u64 v[90:91], v[182:183], 0, s[0:1]
	v_mul_f32_e32 v39, v221, v39
	v_fmac_f32_e32 v39, v219, v38
	v_fmac_f32_e32 v39, v212, v40
	v_fmac_f32_e32 v39, v213, v41
	v_cvt_pk_f32_fp8_e32 v[40:41], v34
	v_add_f32_e32 v38, v43, v39
	v_readlane_b32 s0, v228, 27
	s_ashr_i32 s1, s0, 31
	v_mul_f32_e32 v34, v226, v41
	v_fmac_f32_e32 v34, v225, v40
	v_fmac_f32_e32 v34, v220, v44
	v_cvt_pk_f32_fp8_e32 v[40:41], v35
	v_fmac_f32_e32 v34, v223, v45
	v_add_f32_e32 v39, 0, v34
	v_cvt_pk_f32_fp8_sdwa v[34:35], v35 src0_sel:WORD_1
	v_mul_f32_e32 v41, v222, v41
	v_fmac_f32_e32 v41, v218, v40
	s_lshl_b64 s[0:1], s[0:1], 10
	v_fmac_f32_e32 v41, v215, v34
	v_fmac_f32_e32 v41, v217, v35
	v_cvt_pk_f32_fp8_e32 v[34:35], v36
	v_add_f32_e32 v39, v39, v41
	v_cvt_pk_f32_fp8_sdwa v[40:41], v36 src0_sel:WORD_1
	global_load_dwordx4 v[110:113], v[90:91], off
	v_mul_f32_e32 v35, v216, v35
	v_fmac_f32_e32 v35, v214, v34
	v_fmac_f32_e32 v35, v211, v40
	v_fmac_f32_e32 v35, v224, v41
	v_add_f32_e32 v39, v39, v35
	v_cvt_pk_f32_fp8_e32 v[34:35], v37
	v_cvt_pk_f32_fp8_sdwa v[36:37], v37 src0_sel:WORD_1
	v_cvt_pk_f32_fp8_sdwa v[40:41], v30 src0_sel:WORD_1
	v_lshl_add_u64 v[90:91], v[182:183], 0, s[0:1]
; __device__ void phase_experts(const Params& p, int l) {
;     ...
;     for (int bi = 0; bi < 8; ++bi) {
;       {
;         const int nb = (bi + 1) & 7;
;         const int idv = bi == 7 ? idn0 : (nb < 4 ? id0 : id1);
; #pragma unroll
;         for (int j = 0; j < 16; ++j) {
;           const int row = __builtin_amdgcn_readlane(idv, (nb & 3) * 16 + j);
;           rbuf[(bi + 1) & 1][j] = *(const u32x4*)(U + (size_t)row * 1024 + lane * 16);
;         }
;       }
;       u32x4 (&ru)[16] = rbuf[bi & 1];
;       float sj[16];
; #pragma unroll
;       for (int j = 0; j < 16; ++j) {
;         float acc = 0.f;
; #pragma unroll
;         for (int c = 0; c < 4; ++c) {
;           const f32x2 a = __builtin_amdgcn_cvt_pk_f32_fp8((int)ru[j][c], false), b2 = __builtin_amdgcn_cvt_pk_f32_fp8((int)ru[j][c], true);
;           acc += a.x * hv[c * 4] + a.y * hv[c * 4 + 1] + b2.x * hv[c * 4 + 2] + b2.y * hv[c * 4 + 3];
;         }
;         sj[j] = acc;
;       }
; #pragma unroll
;       for (int hw = 8; hw >= 1; hw >>= 1) {
;         const bool up = (lane & hw) != 0;
; #pragma unroll
;         for (int k = 0; k < hw; ++k) {
;           const float send = up ? sj[k] : sj[k + hw], keep = up ? sj[k + hw] : sj[k];
;           sj[k] = keep + __shfl_xor(send, hw);
;         }
;       }
	v_mul_f32_e32 v35, v221, v35
	v_fmac_f32_e32 v35, v219, v34
	v_fmac_f32_e32 v35, v212, v36
	v_fmac_f32_e32 v35, v213, v37
	v_cvt_pk_f32_fp8_e32 v[36:37], v30
	v_add_f32_e32 v34, v39, v35
	v_readlane_b32 s0, v228, 28
	s_ashr_i32 s1, s0, 31
	v_mul_f32_e32 v30, v226, v37
	v_fmac_f32_e32 v30, v225, v36
	v_fmac_f32_e32 v30, v220, v40
	v_cvt_pk_f32_fp8_e32 v[36:37], v31
	v_fmac_f32_e32 v30, v223, v41
	v_add_f32_e32 v35, 0, v30
	v_cvt_pk_f32_fp8_sdwa v[30:31], v31 src0_sel:WORD_1
	v_mul_f32_e32 v37, v222, v37
	v_fmac_f32_e32 v37, v218, v36
	s_lshl_b64 s[0:1], s[0:1], 10
	v_fmac_f32_e32 v37, v215, v30
	v_fmac_f32_e32 v37, v217, v31
	v_cvt_pk_f32_fp8_e32 v[30:31], v32
	v_add_f32_e32 v35, v35, v37
	v_cvt_pk_f32_fp8_sdwa v[36:37], v32 src0_sel:WORD_1
	global_load_dwordx4 v[106:109], v[90:91], off
	v_mul_f32_e32 v31, v216, v31
	v_fmac_f32_e32 v31, v214, v30
	v_fmac_f32_e32 v31, v211, v36
	v_fmac_f32_e32 v31, v224, v37
	v_add_f32_e32 v35, v35, v31
	v_cvt_pk_f32_fp8_e32 v[30:31], v33
	v_cvt_pk_f32_fp8_sdwa v[32:33], v33 src0_sel:WORD_1
	v_cvt_pk_f32_fp8_sdwa v[36:37], v26 src0_sel:WORD_1
	v_lshl_add_u64 v[90:91], v[182:183], 0, s[0:1]
	v_mul_f32_e32 v31, v221, v31
	v_fmac_f32_e32 v31, v219, v30
	v_fmac_f32_e32 v31, v212, v32
	v_fmac_f32_e32 v31, v213, v33
	v_cvt_pk_f32_fp8_e32 v[32:33], v26
	v_add_f32_e32 v30, v35, v31
	v_readlane_b32 s0, v228, 29
	s_ashr_i32 s1, s0, 31
	v_mul_f32_e32 v26, v226, v33
	v_fmac_f32_e32 v26, v225, v32
	v_fmac_f32_e32 v26, v220, v36
	v_cvt_pk_f32_fp8_e32 v[32:33], v27
	v_fmac_f32_e32 v26, v223, v37
	v_add_f32_e32 v31, 0, v26
	v_cvt_pk_f32_fp8_sdwa v[26:27], v27 src0_sel:WORD_1
	v_mul_f32_e32 v33, v222, v33
	v_fmac_f32_e32 v33, v218, v32
	s_lshl_b64 s[0:1], s[0:1], 10
	v_fmac_f32_e32 v33, v215, v26
	v_fmac_f32_e32 v33, v217, v27
	v_cvt_pk_f32_fp8_e32 v[26:27], v28
	v_add_f32_e32 v31, v31, v33
	v_cvt_pk_f32_fp8_sdwa v[32:33], v28 src0_sel:WORD_1
	global_load_dwordx4 v[102:105], v[90:91], off
	v_mul_f32_e32 v27, v216, v27
	v_fmac_f32_e32 v27, v214, v26
	v_fmac_f32_e32 v27, v211, v32
	v_fmac_f32_e32 v27, v224, v33
	v_add_f32_e32 v31, v31, v27
	v_cvt_pk_f32_fp8_e32 v[26:27], v29
	v_cvt_pk_f32_fp8_sdwa v[28:29], v29 src0_sel:WORD_1
	v_lshl_add_u64 v[90:91], v[182:183], 0, s[0:1]
	v_readlane_b32 s0, v228, 30
	v_mul_f32_e32 v27, v221, v27
	v_fmac_f32_e32 v27, v219, v26
	v_cndmask_b32_e32 v26, v82, v50, vcc
	ds_bpermute_b32 v26, v205, v26
	v_fmac_f32_e32 v27, v212, v28
	v_fmac_f32_e32 v27, v213, v29
	v_add_f32_e32 v28, v31, v27
	v_cndmask_b32_e32 v27, v50, v82, vcc
	s_waitcnt lgkmcnt(0)
	v_add_f32_e32 v29, v27, v26
	v_cvt_pk_f32_fp8_e32 v[26:27], v22
	s_ashr_i32 s1, s0, 31
	s_lshl_b64 s[0:1], s[0:1], 10
	global_load_dwordx4 v[98:101], v[90:91], off
	v_mul_f32_e32 v31, v226, v27
	v_fmac_f32_e32 v31, v225, v26
	v_cvt_pk_f32_fp8_sdwa v[26:27], v22 src0_sel:WORD_1
	v_lshl_add_u64 v[90:91], v[182:183], 0, s[0:1]
	v_readlane_b32 s0, v228, 31
	s_ashr_i32 s1, s0, 31
	v_fmac_f32_e32 v31, v220, v26
	v_fmac_f32_e32 v31, v223, v27
	v_cvt_pk_f32_fp8_e32 v[26:27], v23
	v_cvt_pk_f32_fp8_sdwa v[22:23], v23 src0_sel:WORD_1
	v_add_f32_e32 v31, 0, v31
	s_lshl_b64 s[0:1], s[0:1], 10
	v_mul_f32_e32 v27, v222, v27
	v_fmac_f32_e32 v27, v218, v26
	v_fmac_f32_e32 v27, v215, v22
	v_fmac_f32_e32 v27, v217, v23
	v_cvt_pk_f32_fp8_e32 v[22:23], v24
	v_add_f32_e32 v26, v31, v27
	global_load_dwordx4 v[94:97], v[90:91], off
	v_lshl_add_u64 v[90:91], v[182:183], 0, s[0:1]
	v_mul_f32_e32 v27, v216, v23
	v_fmac_f32_e32 v27, v214, v22
	v_cvt_pk_f32_fp8_sdwa v[22:23], v24 src0_sel:WORD_1
	v_readlane_b32 s0, v228, 32
	s_ashr_i32 s1, s0, 31
	s_lshl_b64 s[0:1], s[0:1], 10
	v_fmac_f32_e32 v27, v211, v22
	v_fmac_f32_e32 v27, v224, v23
	v_cvt_pk_f32_fp8_e32 v[22:23], v25
	v_add_f32_e32 v24, v26, v27
	global_load_dwordx4 v[78:81], v[78:79], off
	s_waitcnt vmcnt(4)
	v_cvt_pk_f32_fp8_sdwa v[44:45], v106 src0_sel:WORD_1
	v_mul_f32_e32 v26, v221, v23
	v_fmac_f32_e32 v26, v219, v22
	v_cvt_pk_f32_fp8_sdwa v[22:23], v25 src0_sel:WORD_1
	global_load_dwordx4 v[86:89], v[86:87], off
	v_fmac_f32_e32 v26, v212, v22
	v_fmac_f32_e32 v26, v213, v23
	v_cvt_pk_f32_fp8_e32 v[22:23], v18
	v_add_f32_e32 v24, v24, v26
	global_load_dwordx4 v[90:93], v[90:91], off
	v_cvt_pk_f32_fp8_sdwa v[26:27], v170 src0_sel:WORD_1
	v_mul_f32_e32 v25, v226, v23
	v_fmac_f32_e32 v25, v225, v22
	v_cvt_pk_f32_fp8_sdwa v[22:23], v18 src0_sel:WORD_1
	v_fmac_f32_e32 v25, v220, v22
	v_fmac_f32_e32 v25, v223, v23
	v_cvt_pk_f32_fp8_e32 v[22:23], v19
	v_cvt_pk_f32_fp8_sdwa v[18:19], v19 src0_sel:WORD_1
	v_add_f32_e32 v25, 0, v25
	v_mul_f32_e32 v23, v222, v23
	v_fmac_f32_e32 v23, v218, v22
	v_fmac_f32_e32 v23, v215, v18
	v_fmac_f32_e32 v23, v217, v19
	v_cvt_pk_f32_fp8_e32 v[18:19], v20
	v_add_f32_e32 v22, v25, v23
	v_cndmask_b32_e32 v25, v28, v54, vcc
	v_mul_f32_e32 v23, v216, v19
	v_fmac_f32_e32 v23, v214, v18
	v_cvt_pk_f32_fp8_sdwa v[18:19], v20 src0_sel:WORD_1
	v_fmac_f32_e32 v23, v211, v18
	v_fmac_f32_e32 v23, v224, v19
	v_cvt_pk_f32_fp8_e32 v[18:19], v21
	v_add_f32_e32 v20, v22, v23
	v_cndmask_b32_e32 v23, v34, v62, vcc
	v_mul_f32_e32 v22, v221, v19
	v_fmac_f32_e32 v22, v219, v18
	v_cvt_pk_f32_fp8_sdwa v[18:19], v21 src0_sel:WORD_1
	v_cndmask_b32_e32 v21, v42, v70, vcc
	v_fmac_f32_e32 v22, v212, v18
	v_fmac_f32_e32 v22, v213, v19
	v_add_f32_e32 v18, v20, v22
	v_cndmask_b32_e32 v19, v18, v24, vcc
	ds_bpermute_b32 v19, v205, v19
	v_cndmask_b32_e32 v18, v24, v18, vcc
	v_cndmask_b32_e32 v20, v46, v74, vcc
	v_cndmask_b32_e32 v22, v38, v66, vcc
	v_cndmask_b32_e32 v24, v30, v58, vcc
	s_waitcnt lgkmcnt(0)
	v_add_f32_e32 v18, v18, v19
	v_cndmask_b32_e32 v19, v74, v46, vcc
	ds_bpermute_b32 v19, v205, v19
	s_waitcnt lgkmcnt(0)
; __device__ void phase_experts(const Params& p, int l) {
;     ...
;       {
;         const int nb = (bi + 1) & 7;
;         const int idv = bi == 7 ? idn0 : (nb < 4 ? id0 : id1);
; #pragma unroll
;         for (int j = 0; j < 16; ++j) {
;           const int row = __builtin_amdgcn_readlane(idv, (nb & 3) * 16 + j);
;           rbuf[(bi + 1) & 1][j] = *(const u32x4*)(U + (size_t)row * 1024 + lane * 16);
;         }
;     ...
;       for (int hw = 8; hw >= 1; hw >>= 1) {
;         const bool up = (lane & hw) != 0;
; #pragma unroll
;         for (int k = 0; k < hw; ++k) {
;           const float send = up ? sj[k] : sj[k + hw], keep = up ? sj[k + hw] : sj[k];
;           sj[k] = keep + __shfl_xor(send, hw);
;         }
;       }
	v_add_f32_e32 v19, v20, v19
	v_cndmask_b32_e32 v20, v70, v42, vcc
	ds_bpermute_b32 v20, v205, v20
	s_waitcnt lgkmcnt(0)
	v_add_f32_e32 v20, v21, v20
	v_cndmask_b32_e32 v21, v66, v38, vcc
	ds_bpermute_b32 v21, v205, v21
	s_waitcnt lgkmcnt(0)
	v_add_f32_e32 v21, v22, v21
	v_cndmask_b32_e32 v22, v62, v34, vcc
	ds_bpermute_b32 v22, v205, v22
	v_cvt_pk_f32_fp8_sdwa v[34:35], v146 src0_sel:WORD_1
	s_waitcnt lgkmcnt(0)
	v_add_f32_e32 v22, v23, v22
	v_cndmask_b32_e32 v23, v58, v30, vcc
	ds_bpermute_b32 v23, v205, v23
	s_waitcnt lgkmcnt(0)
	v_add_f32_e32 v23, v24, v23
	v_cndmask_b32_e32 v24, v54, v28, vcc
	ds_bpermute_b32 v24, v205, v24
	s_waitcnt lgkmcnt(0)
	v_add_f32_e32 v24, v25, v24
	v_cndmask_b32_e64 v25, v29, v21, s[4:5]
	ds_bpermute_b32 v25, v206, v25
	v_cndmask_b32_e64 v21, v21, v29, s[4:5]
	v_cvt_pk_f32_fp8_sdwa v[28:29], v162 src0_sel:WORD_1
	s_waitcnt lgkmcnt(0)
	v_add_f32_e32 v21, v21, v25
	v_cndmask_b32_e64 v25, v18, v22, s[4:5]
	v_cndmask_b32_e64 v18, v22, v18, s[4:5]
	ds_bpermute_b32 v22, v206, v25
	s_waitcnt lgkmcnt(0)
	v_add_f32_e32 v18, v18, v22
	v_cndmask_b32_e64 v22, v19, v23, s[4:5]
	ds_bpermute_b32 v22, v206, v22
	v_cndmask_b32_e64 v19, v23, v19, s[4:5]
	s_waitcnt lgkmcnt(0)
	v_add_f32_e32 v19, v19, v22
	v_cndmask_b32_e64 v22, v20, v24, s[4:5]
	ds_bpermute_b32 v22, v206, v22
	v_cndmask_b32_e64 v20, v24, v20, s[4:5]
	s_waitcnt lgkmcnt(0)
	v_add_f32_e32 v20, v20, v22
	v_cndmask_b32_e64 v22, v21, v19, s[6:7]
	v_cndmask_b32_e64 v19, v19, v21, s[6:7]
	ds_bpermute_b32 v21, v207, v22
	s_waitcnt lgkmcnt(0)
	v_add_f32_e32 v19, v19, v21
	v_cndmask_b32_e64 v21, v18, v20, s[6:7]
	ds_bpermute_b32 v21, v207, v21
	v_cndmask_b32_e64 v18, v20, v18, s[6:7]
	s_waitcnt lgkmcnt(0)
	v_add_f32_e32 v18, v18, v21
	v_cndmask_b32_e64 v20, v19, v18, s[8:9]
	v_cndmask_b32_e64 v18, v18, v19, s[8:9]
	ds_bpermute_b32 v19, v208, v20
	v_lshl_add_u64 v[20:21], v[182:183], 0, s[0:1]
	v_readlane_b32 s0, v228, 33
	s_ashr_i32 s1, s0, 31
	s_lshl_b64 s[0:1], s[0:1], 10
	global_load_dwordx4 v[174:177], v[20:21], off
	v_lshl_add_u64 v[20:21], v[182:183], 0, s[0:1]
	v_readlane_b32 s0, v228, 34
	s_ashr_i32 s1, s0, 31
	s_lshl_b64 s[0:1], s[0:1], 10
	global_load_dwordx4 v[22:25], v[20:21], off
	v_lshl_add_u64 v[20:21], v[182:183], 0, s[0:1]
	v_readlane_b32 s0, v228, 35
	s_ashr_i32 s1, s0, 31
	s_lshl_b64 s[0:1], s[0:1], 10
	global_load_dwordx4 v[166:169], v[20:21], off
	v_lshl_add_u64 v[20:21], v[182:183], 0, s[0:1]
	v_readlane_b32 s0, v228, 36
	s_ashr_i32 s1, s0, 31
	s_lshl_b64 s[0:1], s[0:1], 10
	global_load_dwordx4 v[158:161], v[20:21], off
	v_lshl_add_u64 v[20:21], v[182:183], 0, s[0:1]
	v_readlane_b32 s0, v228, 37
	s_ashr_i32 s1, s0, 31
	s_lshl_b64 s[0:1], s[0:1], 10
	global_load_dwordx4 v[150:153], v[20:21], off
	v_lshl_add_u64 v[20:21], v[182:183], 0, s[0:1]
	v_readlane_b32 s0, v228, 38
	s_ashr_i32 s1, s0, 31
	s_lshl_b64 s[0:1], s[0:1], 10
	global_load_dwordx4 v[142:145], v[20:21], off
	v_lshl_add_u64 v[20:21], v[182:183], 0, s[0:1]
	v_readlane_b32 s0, v228, 39
	s_ashr_i32 s1, s0, 31
	s_lshl_b64 s[0:1], s[0:1], 10
	global_load_dwordx4 v[134:137], v[20:21], off
	v_lshl_add_u64 v[20:21], v[182:183], 0, s[0:1]
	v_readlane_b32 s0, v228, 40
	s_ashr_i32 s1, s0, 31
	s_lshl_b64 s[0:1], s[0:1], 10
	global_load_dwordx4 v[126:129], v[20:21], off
	v_lshl_add_u64 v[20:21], v[182:183], 0, s[0:1]
	v_readlane_b32 s0, v228, 41
	s_ashr_i32 s1, s0, 31
	s_lshl_b64 s[0:1], s[0:1], 10
	global_load_dwordx4 v[118:121], v[20:21], off
	v_lshl_add_u64 v[20:21], v[182:183], 0, s[0:1]
	v_readlane_b32 s0, v228, 42
	s_ashr_i32 s1, s0, 31
	s_lshl_b64 s[0:1], s[0:1], 10
	global_load_dwordx4 v[30:33], v[20:21], off
	v_lshl_add_u64 v[20:21], v[182:183], 0, s[0:1]
	v_readlane_b32 s0, v228, 43
	s_ashr_i32 s1, s0, 31
	s_lshl_b64 s[0:1], s[0:1], 10
	global_load_dwordx4 v[82:85], v[20:21], off
	v_lshl_add_u64 v[20:21], v[182:183], 0, s[0:1]
	v_readlane_b32 s0, v228, 44
	s_ashr_i32 s1, s0, 31
	s_lshl_b64 s[0:1], s[0:1], 10
	global_load_dwordx4 v[70:73], v[20:21], off
	v_lshl_add_u64 v[20:21], v[182:183], 0, s[0:1]
	v_readlane_b32 s0, v228, 45
	s_ashr_i32 s1, s0, 31
	s_lshl_b64 s[0:1], s[0:1], 10
	global_load_dwordx4 v[62:65], v[20:21], off
	v_lshl_add_u64 v[20:21], v[182:183], 0, s[0:1]
	v_readlane_b32 s0, v228, 46
	s_ashr_i32 s1, s0, 31
	s_lshl_b64 s[0:1], s[0:1], 10
	global_load_dwordx4 v[54:57], v[20:21], off
	v_lshl_add_u64 v[20:21], v[182:183], 0, s[0:1]
	v_readlane_b32 s0, v228, 47
	s_ashr_i32 s1, s0, 31
	s_waitcnt lgkmcnt(0)
; __device__ void phase_experts(const Params& p, int l) {
;     ...
;       for (int j = 0; j < 16; ++j) {
;         float acc = 0.f;
; #pragma unroll
;         for (int c = 0; c < 4; ++c) {
;           const f32x2 a = __builtin_amdgcn_cvt_pk_f32_fp8((int)ru[j][c], false), b2 = __builtin_amdgcn_cvt_pk_f32_fp8((int)ru[j][c], true);
;           acc += a.x * hv[c * 4] + a.y * hv[c * 4 + 1] + b2.x * hv[c * 4 + 2] + b2.y * hv[c * 4 + 3];
;         }
;         sj[j] = acc;
;     ...
;       for (int hw = 8; hw >= 1; hw >>= 1) {
;         const bool up = (lane & hw) != 0;
; #pragma unroll
;         for (int k = 0; k < hw; ++k) {
;           const float send = up ? sj[k] : sj[k + hw], keep = up ? sj[k + hw] : sj[k];
;           sj[k] = keep + __shfl_xor(send, hw);
;         }
;       }
;       float tot = sj[0];
;       tot = xsum_rows(tot);
;       if ((lane >> 4) == (bi & 3)) { if (bi < 4) d0 = tot; else d1 = tot; }
	v_add_f32_e32 v18, v18, v19
	s_lshl_b64 s[0:1], s[0:1], 10
	v_mov_b32_e32 v19, v18
	global_load_dwordx4 v[46:49], v[20:21], off
	v_lshl_add_u64 v[20:21], v[182:183], 0, s[0:1]
	v_permlane16_swap_b32_e32 v18, v19
	global_load_dwordx4 v[38:41], v[20:21], off
	v_cvt_pk_f32_fp8_e32 v[20:21], v170
	v_add_f32_e32 v18, v18, v19
	v_mov_b32_e32 v19, v18
	s_nop 1
	v_permlane32_swap_b32_e32 v18, v19
	v_add_f32_e32 v18, v18, v19
	v_mul_f32_e32 v19, v226, v21
	v_fmac_f32_e32 v19, v225, v20
	v_cvt_pk_f32_fp8_e32 v[20:21], v171
	v_fmac_f32_e32 v19, v220, v26
	v_fmac_f32_e32 v19, v223, v27
	v_cvt_pk_f32_fp8_sdwa v[26:27], v171 src0_sel:WORD_1
	v_mul_f32_e32 v21, v222, v21
	v_fmac_f32_e32 v21, v218, v20
	v_add_f32_e32 v19, 0, v19
	v_fmac_f32_e32 v21, v215, v26
	v_fmac_f32_e32 v21, v217, v27
	v_add_f32_e32 v19, v19, v21
	v_cvt_pk_f32_fp8_e32 v[20:21], v172
	v_cvt_pk_f32_fp8_sdwa v[26:27], v172 src0_sel:WORD_1
	v_readlane_b32 s0, v228, 48
	s_ashr_i32 s1, s0, 31
	v_mul_f32_e32 v21, v216, v21
	v_fmac_f32_e32 v21, v214, v20
	v_fmac_f32_e32 v21, v211, v26
	v_fmac_f32_e32 v21, v224, v27
	v_add_f32_e32 v19, v19, v21
	v_cvt_pk_f32_fp8_e32 v[20:21], v173
	v_cvt_pk_f32_fp8_sdwa v[26:27], v173 src0_sel:WORD_1
	v_cndmask_b32_e64 v18, 0, v18, s[10:11]
	s_lshl_b64 s[0:1], s[0:1], 10
	v_mul_f32_e32 v21, v221, v21
	v_fmac_f32_e32 v21, v219, v20
	v_fmac_f32_e32 v21, v212, v26
	v_fmac_f32_e32 v21, v213, v27
	v_add_f32_e32 v26, v19, v21
	v_cvt_pk_f32_fp8_e32 v[20:21], v162
	v_mul_f32_e32 v19, v226, v21
	v_fmac_f32_e32 v19, v225, v20
	v_cvt_pk_f32_fp8_e32 v[20:21], v163
	v_fmac_f32_e32 v19, v220, v28
	v_fmac_f32_e32 v19, v223, v29
	v_cvt_pk_f32_fp8_sdwa v[28:29], v163 src0_sel:WORD_1
	v_mul_f32_e32 v21, v222, v21
	v_fmac_f32_e32 v21, v218, v20
	v_add_f32_e32 v19, 0, v19
	v_fmac_f32_e32 v21, v215, v28
	v_fmac_f32_e32 v21, v217, v29
	v_add_f32_e32 v19, v19, v21
	v_cvt_pk_f32_fp8_e32 v[20:21], v164
	v_cvt_pk_f32_fp8_sdwa v[28:29], v164 src0_sel:WORD_1
	v_mul_f32_e32 v21, v216, v21
	v_fmac_f32_e32 v21, v214, v20
	v_fmac_f32_e32 v21, v211, v28
	v_fmac_f32_e32 v21, v224, v29
	v_add_f32_e32 v19, v19, v21
	v_cvt_pk_f32_fp8_e32 v[20:21], v165
	v_cvt_pk_f32_fp8_sdwa v[28:29], v165 src0_sel:WORD_1
	v_mul_f32_e32 v21, v221, v21
	v_fmac_f32_e32 v21, v219, v20
	v_fmac_f32_e32 v21, v212, v28
	v_fmac_f32_e32 v21, v213, v29
	v_add_f32_e32 v19, v19, v21
	v_cvt_pk_f32_fp8_e32 v[20:21], v154
	v_cvt_pk_f32_fp8_sdwa v[28:29], v154 src0_sel:WORD_1
	v_mul_f32_e32 v21, v226, v21
	v_fmac_f32_e32 v21, v225, v20
	v_fmac_f32_e32 v21, v220, v28
	v_fmac_f32_e32 v21, v223, v29
	v_add_f32_e32 v27, 0, v21
	v_cvt_pk_f32_fp8_e32 v[20:21], v155
	v_cvt_pk_f32_fp8_sdwa v[28:29], v155 src0_sel:WORD_1
	v_mul_f32_e32 v21, v222, v21
	v_fmac_f32_e32 v21, v218, v20
	v_fmac_f32_e32 v21, v215, v28
	v_fmac_f32_e32 v21, v217, v29
	v_add_f32_e32 v27, v27, v21
	v_cvt_pk_f32_fp8_e32 v[20:21], v156
	v_cvt_pk_f32_fp8_sdwa v[28:29], v156 src0_sel:WORD_1
	v_mul_f32_e32 v21, v216, v21
	v_fmac_f32_e32 v21, v214, v20
	v_fmac_f32_e32 v21, v211, v28
	v_fmac_f32_e32 v21, v224, v29
	v_add_f32_e32 v27, v27, v21
	v_cvt_pk_f32_fp8_e32 v[20:21], v157
	v_cvt_pk_f32_fp8_sdwa v[28:29], v157 src0_sel:WORD_1
	v_mul_f32_e32 v21, v221, v21
	v_fmac_f32_e32 v21, v219, v20
	v_fmac_f32_e32 v21, v212, v28
	v_fmac_f32_e32 v21, v213, v29
	v_cvt_pk_f32_fp8_e32 v[28:29], v146
	v_add_f32_e32 v20, v27, v21
	v_mul_f32_e32 v21, v226, v29
	v_fmac_f32_e32 v21, v225, v28
	v_cvt_pk_f32_fp8_e32 v[28:29], v147
	v_fmac_f32_e32 v21, v220, v34
	v_fmac_f32_e32 v21, v223, v35
	v_cvt_pk_f32_fp8_sdwa v[34:35], v147 src0_sel:WORD_1
	v_mul_f32_e32 v27, v222, v29
	v_fmac_f32_e32 v27, v218, v28
	v_cvt_pk_f32_fp8_e32 v[28:29], v148
	v_fmac_f32_e32 v27, v215, v34
	v_fmac_f32_e32 v27, v217, v35
	v_cvt_pk_f32_fp8_sdwa v[34:35], v148 src0_sel:WORD_1
	v_add_f32_e32 v21, 0, v21
	v_add_f32_e32 v21, v21, v27
	v_mul_f32_e32 v27, v216, v29
	v_fmac_f32_e32 v27, v214, v28
	v_cvt_pk_f32_fp8_e32 v[28:29], v149
	v_fmac_f32_e32 v27, v211, v34
	v_fmac_f32_e32 v27, v224, v35
	v_cvt_pk_f32_fp8_sdwa v[34:35], v149 src0_sel:WORD_1
	v_add_f32_e32 v21, v21, v27
	v_mul_f32_e32 v27, v221, v29
	v_fmac_f32_e32 v27, v219, v28
	v_cvt_pk_f32_fp8_e32 v[28:29], v138
	v_fmac_f32_e32 v27, v212, v34
	v_fmac_f32_e32 v27, v213, v35
	v_cvt_pk_f32_fp8_sdwa v[34:35], v138 src0_sel:WORD_1
	v_add_f32_e32 v21, v21, v27
	v_mul_f32_e32 v27, v226, v29
	v_fmac_f32_e32 v27, v225, v28
	v_cvt_pk_f32_fp8_e32 v[28:29], v139
	v_fmac_f32_e32 v27, v220, v34
	v_fmac_f32_e32 v27, v223, v35
	v_cvt_pk_f32_fp8_sdwa v[34:35], v139 src0_sel:WORD_1
	v_mul_f32_e32 v29, v222, v29
	v_fmac_f32_e32 v29, v218, v28
	v_add_f32_e32 v27, 0, v27
	v_fmac_f32_e32 v29, v215, v34
	v_fmac_f32_e32 v29, v217, v35
	v_add_f32_e32 v27, v27, v29
	v_cvt_pk_f32_fp8_e32 v[28:29], v140
	v_cvt_pk_f32_fp8_sdwa v[34:35], v140 src0_sel:WORD_1
	v_mul_f32_e32 v29, v216, v29
	v_fmac_f32_e32 v29, v214, v28
	v_fmac_f32_e32 v29, v211, v34
	v_fmac_f32_e32 v29, v224, v35
	v_add_f32_e32 v27, v27, v29
	v_cvt_pk_f32_fp8_e32 v[28:29], v141
	v_cvt_pk_f32_fp8_sdwa v[34:35], v141 src0_sel:WORD_1
	v_mul_f32_e32 v29, v221, v29
	v_fmac_f32_e32 v29, v219, v28
	v_fmac_f32_e32 v29, v212, v34
	v_fmac_f32_e32 v29, v213, v35
	v_add_f32_e32 v27, v27, v29
	v_cvt_pk_f32_fp8_e32 v[28:29], v130
	v_cvt_pk_f32_fp8_sdwa v[34:35], v130 src0_sel:WORD_1
	v_mul_f32_e32 v29, v226, v29
	v_fmac_f32_e32 v29, v225, v28
	v_fmac_f32_e32 v29, v220, v34
	v_fmac_f32_e32 v29, v223, v35
	v_add_f32_e32 v36, 0, v29
	v_cvt_pk_f32_fp8_e32 v[28:29], v131
	v_cvt_pk_f32_fp8_sdwa v[34:35], v131 src0_sel:WORD_1
	v_mul_f32_e32 v29, v222, v29
	v_fmac_f32_e32 v29, v218, v28
	v_fmac_f32_e32 v29, v215, v34
	v_fmac_f32_e32 v29, v217, v35
; __device__ void phase_experts(const Params& p, int l) {
;     ...
;       for (int j = 0; j < 16; ++j) {
;         float acc = 0.f;
; #pragma unroll
;         for (int c = 0; c < 4; ++c) {
;           const f32x2 a = __builtin_amdgcn_cvt_pk_f32_fp8((int)ru[j][c], false), b2 = __builtin_amdgcn_cvt_pk_f32_fp8((int)ru[j][c], true);
;           acc += a.x * hv[c * 4] + a.y * hv[c * 4 + 1] + b2.x * hv[c * 4 + 2] + b2.y * hv[c * 4 + 3];
;         }
;         sj[j] = acc;
	v_add_f32_e32 v36, v36, v29
	v_cvt_pk_f32_fp8_e32 v[28:29], v132
	v_cvt_pk_f32_fp8_sdwa v[34:35], v132 src0_sel:WORD_1
	v_mul_f32_e32 v29, v216, v29
	v_fmac_f32_e32 v29, v214, v28
	v_fmac_f32_e32 v29, v211, v34
	v_fmac_f32_e32 v29, v224, v35
	v_add_f32_e32 v36, v36, v29
	v_cvt_pk_f32_fp8_e32 v[28:29], v133
	v_cvt_pk_f32_fp8_sdwa v[34:35], v133 src0_sel:WORD_1
	v_mul_f32_e32 v29, v221, v29
	v_fmac_f32_e32 v29, v219, v28
	v_fmac_f32_e32 v29, v212, v34
	v_fmac_f32_e32 v29, v213, v35
	v_cvt_pk_f32_fp8_e32 v[34:35], v122
	v_add_f32_e32 v28, v36, v29
	v_cvt_pk_f32_fp8_sdwa v[36:37], v122 src0_sel:WORD_1
	v_mul_f32_e32 v29, v226, v35
	v_fmac_f32_e32 v29, v225, v34
	v_cvt_pk_f32_fp8_e32 v[34:35], v123
	v_fmac_f32_e32 v29, v220, v36
	v_fmac_f32_e32 v29, v223, v37
	v_cvt_pk_f32_fp8_sdwa v[36:37], v123 src0_sel:WORD_1
	v_mul_f32_e32 v35, v222, v35
	v_fmac_f32_e32 v35, v218, v34
	v_add_f32_e32 v29, 0, v29
	v_fmac_f32_e32 v35, v215, v36
	v_fmac_f32_e32 v35, v217, v37
	v_add_f32_e32 v29, v29, v35
	v_cvt_pk_f32_fp8_e32 v[34:35], v124
	v_cvt_pk_f32_fp8_sdwa v[36:37], v124 src0_sel:WORD_1
	v_mul_f32_e32 v35, v216, v35
	v_fmac_f32_e32 v35, v214, v34
	v_fmac_f32_e32 v35, v211, v36
	v_fmac_f32_e32 v35, v224, v37
	v_add_f32_e32 v29, v29, v35
	v_cvt_pk_f32_fp8_e32 v[34:35], v125
	v_cvt_pk_f32_fp8_sdwa v[36:37], v125 src0_sel:WORD_1
	v_mul_f32_e32 v35, v221, v35
	v_fmac_f32_e32 v35, v219, v34
	v_fmac_f32_e32 v35, v212, v36
	v_fmac_f32_e32 v35, v213, v37
	v_add_f32_e32 v29, v29, v35
	v_cvt_pk_f32_fp8_e32 v[34:35], v114
	v_cvt_pk_f32_fp8_sdwa v[36:37], v114 src0_sel:WORD_1
	v_mul_f32_e32 v35, v226, v35
	v_fmac_f32_e32 v35, v225, v34
	v_fmac_f32_e32 v35, v220, v36
	v_fmac_f32_e32 v35, v223, v37
	v_add_f32_e32 v42, 0, v35
	v_cvt_pk_f32_fp8_e32 v[34:35], v115
	v_cvt_pk_f32_fp8_sdwa v[36:37], v115 src0_sel:WORD_1
	v_mul_f32_e32 v35, v222, v35
	v_fmac_f32_e32 v35, v218, v34
	v_fmac_f32_e32 v35, v215, v36
	v_fmac_f32_e32 v35, v217, v37
	v_add_f32_e32 v42, v42, v35
	v_cvt_pk_f32_fp8_e32 v[34:35], v116
	v_cvt_pk_f32_fp8_sdwa v[36:37], v116 src0_sel:WORD_1
	v_mul_f32_e32 v35, v216, v35
	v_fmac_f32_e32 v35, v214, v34
	v_fmac_f32_e32 v35, v211, v36
	v_fmac_f32_e32 v35, v224, v37
	v_add_f32_e32 v42, v42, v35
	v_cvt_pk_f32_fp8_e32 v[34:35], v117
	v_cvt_pk_f32_fp8_sdwa v[36:37], v117 src0_sel:WORD_1
	v_mul_f32_e32 v35, v221, v35
	v_fmac_f32_e32 v35, v219, v34
	v_fmac_f32_e32 v35, v212, v36
	v_fmac_f32_e32 v35, v213, v37
	v_add_f32_e32 v37, v42, v35
	v_cvt_pk_f32_fp8_e32 v[34:35], v110
	v_cvt_pk_f32_fp8_sdwa v[42:43], v110 src0_sel:WORD_1
	v_mul_f32_e32 v35, v226, v35
	v_fmac_f32_e32 v35, v225, v34
	v_fmac_f32_e32 v35, v220, v42
	v_fmac_f32_e32 v35, v223, v43
	v_add_f32_e32 v36, 0, v35
	v_cvt_pk_f32_fp8_e32 v[34:35], v111
	v_cvt_pk_f32_fp8_sdwa v[42:43], v111 src0_sel:WORD_1
	v_mul_f32_e32 v35, v222, v35
	v_fmac_f32_e32 v35, v218, v34
	v_fmac_f32_e32 v35, v215, v42
	v_fmac_f32_e32 v35, v217, v43
	v_add_f32_e32 v36, v36, v35
	v_cvt_pk_f32_fp8_e32 v[34:35], v112
	v_cvt_pk_f32_fp8_sdwa v[42:43], v112 src0_sel:WORD_1
	v_mul_f32_e32 v35, v216, v35
	v_fmac_f32_e32 v35, v214, v34
	v_fmac_f32_e32 v35, v211, v42
	v_fmac_f32_e32 v35, v224, v43
	v_add_f32_e32 v36, v36, v35
	v_cvt_pk_f32_fp8_e32 v[34:35], v113
	v_cvt_pk_f32_fp8_sdwa v[42:43], v113 src0_sel:WORD_1
	v_mul_f32_e32 v35, v221, v35
	v_fmac_f32_e32 v35, v219, v34
	v_fmac_f32_e32 v35, v212, v42
	v_fmac_f32_e32 v35, v213, v43
	v_cvt_pk_f32_fp8_e32 v[42:43], v106
	v_add_f32_e32 v34, v36, v35
	v_mul_f32_e32 v35, v226, v43
	v_fmac_f32_e32 v35, v225, v42
	v_cvt_pk_f32_fp8_e32 v[42:43], v107
	v_fmac_f32_e32 v35, v220, v44
	v_fmac_f32_e32 v35, v223, v45
	v_cvt_pk_f32_fp8_sdwa v[44:45], v107 src0_sel:WORD_1
	v_mul_f32_e32 v36, v222, v43
	v_fmac_f32_e32 v36, v218, v42
	v_cvt_pk_f32_fp8_e32 v[42:43], v108
	v_fmac_f32_e32 v36, v215, v44
	v_fmac_f32_e32 v36, v217, v45
	v_cvt_pk_f32_fp8_sdwa v[44:45], v108 src0_sel:WORD_1
	v_add_f32_e32 v35, 0, v35
	v_add_f32_e32 v35, v35, v36
	v_mul_f32_e32 v36, v216, v43
	v_fmac_f32_e32 v36, v214, v42
	v_cvt_pk_f32_fp8_e32 v[42:43], v109
	v_fmac_f32_e32 v36, v211, v44
	v_fmac_f32_e32 v36, v224, v45
	v_cvt_pk_f32_fp8_sdwa v[44:45], v109 src0_sel:WORD_1
	v_add_f32_e32 v35, v35, v36
	v_mul_f32_e32 v36, v221, v43
	v_fmac_f32_e32 v36, v219, v42
	s_waitcnt vmcnt(21)
	v_cvt_pk_f32_fp8_e32 v[42:43], v102
	v_fmac_f32_e32 v36, v212, v44
	v_fmac_f32_e32 v36, v213, v45
	v_cvt_pk_f32_fp8_sdwa v[44:45], v102 src0_sel:WORD_1
	v_add_f32_e32 v35, v35, v36
	v_mul_f32_e32 v36, v226, v43
	v_fmac_f32_e32 v36, v225, v42
	v_cvt_pk_f32_fp8_e32 v[42:43], v103
	v_fmac_f32_e32 v36, v220, v44
	v_fmac_f32_e32 v36, v223, v45
	v_cvt_pk_f32_fp8_sdwa v[44:45], v103 src0_sel:WORD_1
	v_mul_f32_e32 v43, v222, v43
	v_fmac_f32_e32 v43, v218, v42
	v_add_f32_e32 v36, 0, v36
	v_fmac_f32_e32 v43, v215, v44
	v_fmac_f32_e32 v43, v217, v45
	v_add_f32_e32 v36, v36, v43
	v_cvt_pk_f32_fp8_e32 v[42:43], v104
	v_cvt_pk_f32_fp8_sdwa v[44:45], v104 src0_sel:WORD_1
	s_waitcnt vmcnt(11)
; __device__ void phase_experts(const Params& p, int l) {
;     ...
;       for (int j = 0; j < 16; ++j) {
;         float acc = 0.f;
; #pragma unroll
;         for (int c = 0; c < 4; ++c) {
;           const f32x2 a = __builtin_amdgcn_cvt_pk_f32_fp8((int)ru[j][c], false), b2 = __builtin_amdgcn_cvt_pk_f32_fp8((int)ru[j][c], true);
;           acc += a.x * hv[c * 4] + a.y * hv[c * 4 + 1] + b2.x * hv[c * 4 + 2] + b2.y * hv[c * 4 + 3];
;         }
;         sj[j] = acc;
;       }
; #pragma unroll
;       for (int hw = 8; hw >= 1; hw >>= 1) {
;         const bool up = (lane & hw) != 0;
; #pragma unroll
;         for (int k = 0; k < hw; ++k) {
;           const float send = up ? sj[k] : sj[k + hw], keep = up ? sj[k + hw] : sj[k];
;           sj[k] = keep + __shfl_xor(send, hw);
;         }
;       }
	v_cvt_pk_f32_fp8_sdwa v[102:103], v150 src0_sel:WORD_1
	v_mul_f32_e32 v43, v216, v43
	v_fmac_f32_e32 v43, v214, v42
	v_fmac_f32_e32 v43, v211, v44
	v_fmac_f32_e32 v43, v224, v45
	v_add_f32_e32 v36, v36, v43
	v_cvt_pk_f32_fp8_e32 v[42:43], v105
	v_cvt_pk_f32_fp8_sdwa v[44:45], v105 src0_sel:WORD_1
	v_mul_f32_e32 v43, v221, v43
	v_fmac_f32_e32 v43, v219, v42
	v_fmac_f32_e32 v43, v212, v44
	v_fmac_f32_e32 v43, v213, v45
	v_add_f32_e32 v36, v36, v43
	v_cvt_pk_f32_fp8_e32 v[42:43], v98
	v_cvt_pk_f32_fp8_sdwa v[44:45], v98 src0_sel:WORD_1
	v_mul_f32_e32 v43, v226, v43
	v_fmac_f32_e32 v43, v225, v42
	v_fmac_f32_e32 v43, v220, v44
	v_fmac_f32_e32 v43, v223, v45
	v_add_f32_e32 v50, 0, v43
	v_cvt_pk_f32_fp8_e32 v[42:43], v99
	v_cvt_pk_f32_fp8_sdwa v[44:45], v99 src0_sel:WORD_1
	v_mul_f32_e32 v43, v222, v43
	v_fmac_f32_e32 v43, v218, v42
	v_fmac_f32_e32 v43, v215, v44
	v_fmac_f32_e32 v43, v217, v45
	v_add_f32_e32 v50, v50, v43
	v_cvt_pk_f32_fp8_e32 v[42:43], v100
	v_cvt_pk_f32_fp8_sdwa v[44:45], v100 src0_sel:WORD_1
	v_mul_f32_e32 v43, v216, v43
	v_fmac_f32_e32 v43, v214, v42
	v_fmac_f32_e32 v43, v211, v44
	v_fmac_f32_e32 v43, v224, v45
	v_add_f32_e32 v50, v50, v43
	v_cvt_pk_f32_fp8_e32 v[42:43], v101
	v_cvt_pk_f32_fp8_sdwa v[44:45], v101 src0_sel:WORD_1
	v_mul_f32_e32 v43, v221, v43
	v_fmac_f32_e32 v43, v219, v42
	v_fmac_f32_e32 v43, v212, v44
	v_fmac_f32_e32 v43, v213, v45
	v_cvt_pk_f32_fp8_e32 v[44:45], v94
	v_add_f32_e32 v42, v50, v43
	v_cvt_pk_f32_fp8_sdwa v[50:51], v94 src0_sel:WORD_1
	v_mul_f32_e32 v43, v226, v45
	v_fmac_f32_e32 v43, v225, v44
	v_cvt_pk_f32_fp8_e32 v[44:45], v95
	v_fmac_f32_e32 v43, v220, v50
	v_fmac_f32_e32 v43, v223, v51
	v_cvt_pk_f32_fp8_sdwa v[50:51], v95 src0_sel:WORD_1
	v_mul_f32_e32 v45, v222, v45
	v_fmac_f32_e32 v45, v218, v44
	v_add_f32_e32 v43, 0, v43
	v_fmac_f32_e32 v45, v215, v50
	v_fmac_f32_e32 v45, v217, v51
	v_add_f32_e32 v43, v43, v45
	v_cvt_pk_f32_fp8_e32 v[44:45], v96
	v_cvt_pk_f32_fp8_sdwa v[50:51], v96 src0_sel:WORD_1
	v_cvt_pk_f32_fp8_sdwa v[94:95], v174 src0_sel:WORD_1
	v_mul_f32_e32 v45, v216, v45
	v_fmac_f32_e32 v45, v214, v44
	v_fmac_f32_e32 v45, v211, v50
	v_fmac_f32_e32 v45, v224, v51
	v_add_f32_e32 v43, v43, v45
	v_cvt_pk_f32_fp8_e32 v[44:45], v97
	v_cvt_pk_f32_fp8_sdwa v[50:51], v97 src0_sel:WORD_1
	v_cvt_pk_f32_fp8_sdwa v[96:97], v166 src0_sel:WORD_1
	v_mul_f32_e32 v45, v221, v45
	v_fmac_f32_e32 v45, v219, v44
	v_fmac_f32_e32 v45, v212, v50
	v_fmac_f32_e32 v45, v213, v51
	v_add_f32_e32 v43, v43, v45
	v_cvt_pk_f32_fp8_e32 v[44:45], v90
	v_cvt_pk_f32_fp8_sdwa v[50:51], v90 src0_sel:WORD_1
	v_mul_f32_e32 v45, v226, v45
	v_fmac_f32_e32 v45, v225, v44
	v_fmac_f32_e32 v45, v220, v50
	v_fmac_f32_e32 v45, v223, v51
	v_add_f32_e32 v52, 0, v45
	v_cvt_pk_f32_fp8_e32 v[44:45], v91
	v_cvt_pk_f32_fp8_sdwa v[50:51], v91 src0_sel:WORD_1
	v_mul_f32_e32 v45, v222, v45
	v_fmac_f32_e32 v45, v218, v44
	v_fmac_f32_e32 v45, v215, v50
	v_fmac_f32_e32 v45, v217, v51
	v_add_f32_e32 v52, v52, v45
	v_cvt_pk_f32_fp8_e32 v[44:45], v92
	v_cvt_pk_f32_fp8_sdwa v[50:51], v92 src0_sel:WORD_1
	v_mul_f32_e32 v45, v216, v45
	v_fmac_f32_e32 v45, v214, v44
	v_fmac_f32_e32 v45, v211, v50
	v_fmac_f32_e32 v45, v224, v51
	v_add_f32_e32 v52, v52, v45
	v_cvt_pk_f32_fp8_e32 v[44:45], v93
	v_cvt_pk_f32_fp8_sdwa v[50:51], v93 src0_sel:WORD_1
	v_mul_f32_e32 v45, v221, v45
	v_fmac_f32_e32 v45, v219, v44
	v_fmac_f32_e32 v45, v212, v50
	v_cndmask_b32_e32 v44, v26, v37, vcc
	v_fmac_f32_e32 v45, v213, v51
	v_cndmask_b32_e32 v26, v37, v26, vcc
	ds_bpermute_b32 v37, v205, v44
	v_add_f32_e32 v50, v52, v45
	v_cvt_pk_f32_fp8_e32 v[44:45], v86
	s_waitcnt lgkmcnt(0)
	v_add_f32_e32 v26, v26, v37
	v_mul_f32_e32 v37, v226, v45
	v_fmac_f32_e32 v37, v225, v44
	v_cvt_pk_f32_fp8_sdwa v[44:45], v86 src0_sel:WORD_1
	v_fmac_f32_e32 v37, v220, v44
	v_fmac_f32_e32 v37, v223, v45
	v_cvt_pk_f32_fp8_e32 v[44:45], v87
	v_add_f32_e32 v37, 0, v37
	v_mul_f32_e32 v51, v222, v45
	v_fmac_f32_e32 v51, v218, v44
	v_cvt_pk_f32_fp8_sdwa v[44:45], v87 src0_sel:WORD_1
	v_fmac_f32_e32 v51, v215, v44
	v_fmac_f32_e32 v51, v217, v45
	v_cvt_pk_f32_fp8_e32 v[44:45], v88
	v_add_f32_e32 v37, v37, v51
	v_mul_f32_e32 v51, v216, v45
	v_fmac_f32_e32 v51, v214, v44
	v_cvt_pk_f32_fp8_sdwa v[44:45], v88 src0_sel:WORD_1
	v_fmac_f32_e32 v51, v211, v44
	v_fmac_f32_e32 v51, v224, v45
	v_cvt_pk_f32_fp8_e32 v[44:45], v89
	v_add_f32_e32 v37, v37, v51
	v_mul_f32_e32 v51, v221, v45
	v_fmac_f32_e32 v51, v219, v44
	v_cvt_pk_f32_fp8_sdwa v[44:45], v89 src0_sel:WORD_1
	v_fmac_f32_e32 v51, v212, v44
	v_fmac_f32_e32 v51, v213, v45
	v_cvt_pk_f32_fp8_e32 v[44:45], v78
	v_add_f32_e32 v37, v37, v51
	v_mul_f32_e32 v51, v226, v45
	v_fmac_f32_e32 v51, v225, v44
	v_cvt_pk_f32_fp8_sdwa v[44:45], v78 src0_sel:WORD_1
	v_fmac_f32_e32 v51, v220, v44
	v_fmac_f32_e32 v51, v223, v45
	v_cvt_pk_f32_fp8_e32 v[44:45], v79
	v_add_f32_e32 v51, 0, v51
	v_mul_f32_e32 v52, v222, v45
	v_fmac_f32_e32 v52, v218, v44
	v_cvt_pk_f32_fp8_sdwa v[44:45], v79 src0_sel:WORD_1
	v_fmac_f32_e32 v52, v215, v44
	v_fmac_f32_e32 v52, v217, v45
	v_cvt_pk_f32_fp8_e32 v[44:45], v80
	v_add_f32_e32 v51, v51, v52
	v_mul_f32_e32 v52, v216, v45
	v_fmac_f32_e32 v52, v214, v44
	v_cvt_pk_f32_fp8_sdwa v[44:45], v80 src0_sel:WORD_1
	v_fmac_f32_e32 v52, v211, v44
	v_fmac_f32_e32 v52, v224, v45
	v_cvt_pk_f32_fp8_e32 v[44:45], v81
	v_add_f32_e32 v51, v51, v52
	v_mul_f32_e32 v52, v221, v45
	v_fmac_f32_e32 v52, v219, v44
	v_cvt_pk_f32_fp8_sdwa v[44:45], v81 src0_sel:WORD_1
	v_cvt_pk_f32_fp8_e32 v[80:81], v174
	v_fmac_f32_e32 v52, v212, v44
	v_mul_f32_e32 v79, v226, v81
	v_fmac_f32_e32 v79, v225, v80
	v_cvt_pk_f32_fp8_e32 v[80:81], v175
	v_fmac_f32_e32 v79, v220, v94
; __device__ void phase_experts(const Params& p, int l) {
;     ...
;       for (int j = 0; j < 16; ++j) {
;         float acc = 0.f;
; #pragma unroll
;         for (int c = 0; c < 4; ++c) {
;           const f32x2 a = __builtin_amdgcn_cvt_pk_f32_fp8((int)ru[j][c], false), b2 = __builtin_amdgcn_cvt_pk_f32_fp8((int)ru[j][c], true);
;           acc += a.x * hv[c * 4] + a.y * hv[c * 4 + 1] + b2.x * hv[c * 4 + 2] + b2.y * hv[c * 4 + 3];
;         }
;         sj[j] = acc;
;       }
; #pragma unroll
;       for (int hw = 8; hw >= 1; hw >>= 1) {
;         const bool up = (lane & hw) != 0;
; #pragma unroll
;         for (int k = 0; k < hw; ++k) {
;           const float send = up ? sj[k] : sj[k + hw], keep = up ? sj[k + hw] : sj[k];
;           sj[k] = keep + __shfl_xor(send, hw);
;         }
;       }
	v_fmac_f32_e32 v79, v223, v95
	v_cvt_pk_f32_fp8_sdwa v[94:95], v175 src0_sel:WORD_1
	v_mul_f32_e32 v81, v222, v81
	v_fmac_f32_e32 v81, v218, v80
	v_add_f32_e32 v79, 0, v79
	v_fmac_f32_e32 v81, v215, v94
	v_fmac_f32_e32 v81, v217, v95
	v_add_f32_e32 v79, v79, v81
	v_cvt_pk_f32_fp8_e32 v[80:81], v176
	v_cvt_pk_f32_fp8_sdwa v[94:95], v176 src0_sel:WORD_1
	v_fmac_f32_e32 v52, v213, v45
	v_add_f32_e32 v44, v51, v52
	v_mul_f32_e32 v81, v216, v81
	v_fmac_f32_e32 v81, v214, v80
	v_fmac_f32_e32 v81, v211, v94
	v_fmac_f32_e32 v81, v224, v95
	v_add_f32_e32 v79, v79, v81
	v_cvt_pk_f32_fp8_e32 v[80:81], v177
	v_cvt_pk_f32_fp8_sdwa v[94:95], v177 src0_sel:WORD_1
	v_cndmask_b32_e32 v45, v44, v37, vcc
	v_cndmask_b32_e32 v37, v37, v44, vcc
	v_mul_f32_e32 v81, v221, v81
	v_fmac_f32_e32 v81, v219, v80
	v_fmac_f32_e32 v81, v212, v94
	v_fmac_f32_e32 v81, v213, v95
	v_add_f32_e32 v94, v79, v81
	v_cvt_pk_f32_fp8_e32 v[80:81], v166
	ds_bpermute_b32 v44, v205, v45
	v_mul_f32_e32 v79, v226, v81
	v_fmac_f32_e32 v79, v225, v80
	v_cvt_pk_f32_fp8_e32 v[80:81], v167
	v_fmac_f32_e32 v79, v220, v96
	v_fmac_f32_e32 v79, v223, v97
	v_cvt_pk_f32_fp8_sdwa v[96:97], v167 src0_sel:WORD_1
	v_mul_f32_e32 v81, v222, v81
	v_fmac_f32_e32 v81, v218, v80
	v_add_f32_e32 v79, 0, v79
	v_fmac_f32_e32 v81, v215, v96
	v_fmac_f32_e32 v81, v217, v97
	v_add_f32_e32 v79, v79, v81
	v_cvt_pk_f32_fp8_e32 v[80:81], v168
	v_cvt_pk_f32_fp8_sdwa v[96:97], v168 src0_sel:WORD_1
	s_waitcnt lgkmcnt(0)
	v_add_f32_e32 v37, v37, v44
	v_cndmask_b32_e32 v44, v19, v34, vcc
	v_mul_f32_e32 v81, v216, v81
	v_fmac_f32_e32 v81, v214, v80
	v_fmac_f32_e32 v81, v211, v96
	v_fmac_f32_e32 v81, v224, v97
	v_add_f32_e32 v79, v79, v81
	v_cvt_pk_f32_fp8_e32 v[80:81], v169
	v_cvt_pk_f32_fp8_sdwa v[96:97], v169 src0_sel:WORD_1
	v_cndmask_b32_e32 v19, v34, v19, vcc
	ds_bpermute_b32 v34, v205, v44
	v_mul_f32_e32 v81, v221, v81
	v_fmac_f32_e32 v81, v219, v80
	v_fmac_f32_e32 v81, v212, v96
	v_fmac_f32_e32 v81, v213, v97
	v_add_f32_e32 v79, v79, v81
	v_cvt_pk_f32_fp8_e32 v[80:81], v158
	v_cvt_pk_f32_fp8_sdwa v[96:97], v158 src0_sel:WORD_1
	s_waitcnt lgkmcnt(0)
	v_add_f32_e32 v19, v19, v34
	v_cndmask_b32_e32 v34, v20, v35, vcc
	v_mul_f32_e32 v81, v226, v81
	ds_bpermute_b32 v34, v205, v34
	v_fmac_f32_e32 v81, v225, v80
	v_fmac_f32_e32 v81, v220, v96
	v_fmac_f32_e32 v81, v223, v97
	v_add_f32_e32 v95, 0, v81
	v_cvt_pk_f32_fp8_e32 v[80:81], v159
	v_cndmask_b32_e32 v20, v35, v20, vcc
	s_waitcnt lgkmcnt(0)
	v_add_f32_e32 v20, v20, v34
	v_cndmask_b32_e32 v34, v21, v36, vcc
	v_cvt_pk_f32_fp8_sdwa v[96:97], v159 src0_sel:WORD_1
	ds_bpermute_b32 v34, v205, v34
	v_mul_f32_e32 v81, v222, v81
	v_fmac_f32_e32 v81, v218, v80
	v_fmac_f32_e32 v81, v215, v96
	v_cndmask_b32_e32 v21, v36, v21, vcc
	v_fmac_f32_e32 v81, v217, v97
	s_waitcnt lgkmcnt(0)
	v_add_f32_e32 v21, v21, v34
	v_cndmask_b32_e32 v34, v27, v42, vcc
	v_add_f32_e32 v95, v95, v81
	v_cvt_pk_f32_fp8_e32 v[80:81], v160
	ds_bpermute_b32 v34, v205, v34
	v_cvt_pk_f32_fp8_sdwa v[96:97], v160 src0_sel:WORD_1
	v_cndmask_b32_e32 v27, v42, v27, vcc
	v_mul_f32_e32 v81, v216, v81
	v_fmac_f32_e32 v81, v214, v80
	s_waitcnt lgkmcnt(0)
	v_add_f32_e32 v27, v27, v34
	v_cndmask_b32_e32 v34, v28, v43, vcc
	v_fmac_f32_e32 v81, v211, v96
	ds_bpermute_b32 v34, v205, v34
	v_fmac_f32_e32 v81, v224, v97
	v_add_f32_e32 v95, v95, v81
	v_cvt_pk_f32_fp8_e32 v[80:81], v161
	v_cvt_pk_f32_fp8_sdwa v[96:97], v161 src0_sel:WORD_1
	v_cndmask_b32_e32 v28, v43, v28, vcc
	s_waitcnt lgkmcnt(0)
	v_add_f32_e32 v28, v28, v34
	v_cndmask_b32_e32 v34, v29, v50, vcc
	v_mul_f32_e32 v81, v221, v81
	ds_bpermute_b32 v34, v205, v34
	v_fmac_f32_e32 v81, v219, v80
	v_fmac_f32_e32 v81, v212, v96
	v_fmac_f32_e32 v81, v213, v97
	v_cvt_pk_f32_fp8_e32 v[96:97], v150
	v_cndmask_b32_e32 v29, v50, v29, vcc
	s_waitcnt lgkmcnt(0)
	v_add_f32_e32 v29, v29, v34
	v_cndmask_b32_e64 v34, v26, v21, s[4:5]
	v_cndmask_b32_e64 v21, v21, v26, s[4:5]
	ds_bpermute_b32 v26, v206, v34
	v_add_f32_e32 v80, v95, v81
	v_mul_f32_e32 v81, v226, v97
	v_fmac_f32_e32 v81, v225, v96
	v_cvt_pk_f32_fp8_e32 v[96:97], v151
	v_fmac_f32_e32 v81, v220, v102
	v_fmac_f32_e32 v81, v223, v103
	v_cvt_pk_f32_fp8_sdwa v[102:103], v151 src0_sel:WORD_1
	s_waitcnt lgkmcnt(0)
	v_add_f32_e32 v21, v21, v26
	v_cndmask_b32_e64 v26, v37, v27, s[4:5]
	v_mul_f32_e32 v95, v222, v97
	ds_bpermute_b32 v26, v206, v26
	v_fmac_f32_e32 v95, v218, v96
	v_cvt_pk_f32_fp8_e32 v[96:97], v152
	v_fmac_f32_e32 v95, v215, v102
	v_fmac_f32_e32 v95, v217, v103
	v_cvt_pk_f32_fp8_sdwa v[102:103], v152 src0_sel:WORD_1
	v_add_f32_e32 v81, 0, v81
	v_cndmask_b32_e64 v27, v27, v37, s[4:5]
	v_add_f32_e32 v81, v81, v95
	v_mul_f32_e32 v95, v216, v97
	s_waitcnt lgkmcnt(0)
	v_add_f32_e32 v26, v27, v26
	v_cndmask_b32_e64 v27, v19, v28, s[4:5]
	v_fmac_f32_e32 v95, v214, v96
	v_cvt_pk_f32_fp8_e32 v[96:97], v153
	ds_bpermute_b32 v27, v206, v27
	v_fmac_f32_e32 v95, v211, v102
	v_fmac_f32_e32 v95, v224, v103
	v_cvt_pk_f32_fp8_sdwa v[102:103], v153 src0_sel:WORD_1
	v_add_f32_e32 v81, v81, v95
	v_mul_f32_e32 v95, v221, v97
	v_cndmask_b32_e64 v19, v28, v19, s[4:5]
	v_fmac_f32_e32 v95, v219, v96
	s_waitcnt vmcnt(10)
	v_cvt_pk_f32_fp8_e32 v[96:97], v142
	s_waitcnt lgkmcnt(0)
	v_add_f32_e32 v19, v19, v27
	v_cndmask_b32_e64 v27, v20, v29, s[4:5]
	v_fmac_f32_e32 v95, v212, v102
	ds_bpermute_b32 v27, v206, v27
	v_fmac_f32_e32 v95, v213, v103
	v_cvt_pk_f32_fp8_sdwa v[102:103], v142 src0_sel:WORD_1
	v_add_f32_e32 v81, v81, v95
	v_mul_f32_e32 v95, v226, v97
	v_fmac_f32_e32 v95, v225, v96
	v_cvt_pk_f32_fp8_e32 v[96:97], v143
	v_cndmask_b32_e64 v20, v29, v20, s[4:5]
	v_fmac_f32_e32 v95, v220, v102
	s_waitcnt lgkmcnt(0)
; __device__ void phase_experts(const Params& p, int l) {
;     ...
;       {
;         const int nb = (bi + 1) & 7;
;         const int idv = bi == 7 ? idn0 : (nb < 4 ? id0 : id1);
; #pragma unroll
;         for (int j = 0; j < 16; ++j) {
;           const int row = __builtin_amdgcn_readlane(idv, (nb & 3) * 16 + j);
;           rbuf[(bi + 1) & 1][j] = *(const u32x4*)(U + (size_t)row * 1024 + lane * 16);
;         }
;     ...
;       for (int hw = 8; hw >= 1; hw >>= 1) {
;         const bool up = (lane & hw) != 0;
; #pragma unroll
;         for (int k = 0; k < hw; ++k) {
;           const float send = up ? sj[k] : sj[k + hw], keep = up ? sj[k + hw] : sj[k];
;           sj[k] = keep + __shfl_xor(send, hw);
;         }
;       }
;       float tot = sj[0];
;       tot = xsum_rows(tot);
;       if ((lane >> 4) == (bi & 3)) { if (bi < 4) d0 = tot; else d1 = tot; }
	v_add_f32_e32 v20, v20, v27
	v_cndmask_b32_e64 v27, v21, v19, s[6:7]
	v_fmac_f32_e32 v95, v223, v103
	v_cvt_pk_f32_fp8_sdwa v[102:103], v143 src0_sel:WORD_1
	v_cndmask_b32_e64 v19, v19, v21, s[6:7]
	ds_bpermute_b32 v21, v207, v27
	v_mul_f32_e32 v97, v222, v97
	v_fmac_f32_e32 v97, v218, v96
	v_fmac_f32_e32 v97, v215, v102
	v_add_f32_e32 v95, 0, v95
	v_fmac_f32_e32 v97, v217, v103
	s_waitcnt lgkmcnt(0)
	v_add_f32_e32 v19, v19, v21
	v_cndmask_b32_e64 v21, v26, v20, s[6:7]
	v_add_f32_e32 v95, v95, v97
	v_cvt_pk_f32_fp8_e32 v[96:97], v144
	ds_bpermute_b32 v21, v207, v21
	v_cvt_pk_f32_fp8_sdwa v[102:103], v144 src0_sel:WORD_1
	v_cndmask_b32_e64 v20, v20, v26, s[6:7]
	v_mul_f32_e32 v97, v216, v97
	v_fmac_f32_e32 v97, v214, v96
	s_waitcnt lgkmcnt(0)
	v_add_f32_e32 v20, v20, v21
	v_fmac_f32_e32 v97, v211, v102
	v_cndmask_b32_e64 v21, v19, v20, s[8:9]
	v_fmac_f32_e32 v97, v224, v103
	v_cndmask_b32_e64 v19, v20, v19, s[8:9]
	ds_bpermute_b32 v20, v208, v21
	v_add_f32_e32 v95, v95, v97
	v_cvt_pk_f32_fp8_e32 v[96:97], v145
	v_cvt_pk_f32_fp8_sdwa v[102:103], v145 src0_sel:WORD_1
	s_waitcnt lgkmcnt(0)
	v_add_f32_e32 v19, v19, v20
	v_mul_f32_e32 v97, v221, v97
	v_fmac_f32_e32 v97, v219, v96
	v_mov_b32_e32 v20, v19
	v_fmac_f32_e32 v97, v212, v102
	s_nop 0
	v_permlane16_swap_b32_e32 v19, v20
	v_fmac_f32_e32 v97, v213, v103
	v_add_f32_e32 v19, v19, v20
	v_add_f32_e32 v95, v95, v97
	s_waitcnt vmcnt(9)
	v_cvt_pk_f32_fp8_e32 v[96:97], v134
	v_mov_b32_e32 v20, v19
	s_nop 1
	v_permlane32_swap_b32_e32 v19, v20
	v_cvt_pk_f32_fp8_sdwa v[102:103], v134 src0_sel:WORD_1
	v_add_f32_e32 v19, v19, v20
	v_cndmask_b32_e64 v78, v18, v19, s[12:13]
	v_lshl_add_u64 v[18:19], v[182:183], 0, s[0:1]
	v_mul_f32_e32 v97, v226, v97
	global_load_dwordx4 v[146:149], v[18:19], off
	v_fmac_f32_e32 v97, v225, v96
	v_fmac_f32_e32 v97, v220, v102
	v_fmac_f32_e32 v97, v223, v103
	v_add_f32_e32 v104, 0, v97
	v_cvt_pk_f32_fp8_e32 v[96:97], v135
	v_cvt_pk_f32_fp8_sdwa v[102:103], v135 src0_sel:WORD_1
	v_readlane_b32 s0, v228, 49
	s_ashr_i32 s1, s0, 31
	v_mul_f32_e32 v97, v222, v97
	v_fmac_f32_e32 v97, v218, v96
	v_fmac_f32_e32 v97, v215, v102
	v_fmac_f32_e32 v97, v217, v103
	v_add_f32_e32 v104, v104, v97
	v_cvt_pk_f32_fp8_e32 v[96:97], v136
	v_cvt_pk_f32_fp8_sdwa v[102:103], v136 src0_sel:WORD_1
	s_lshl_b64 s[0:1], s[0:1], 10
	v_lshl_add_u64 v[18:19], v[182:183], 0, s[0:1]
	v_mul_f32_e32 v97, v216, v97
	v_fmac_f32_e32 v97, v214, v96
	v_fmac_f32_e32 v97, v211, v102
	v_fmac_f32_e32 v97, v224, v103
	v_add_f32_e32 v104, v104, v97
	v_cvt_pk_f32_fp8_e32 v[96:97], v137
	v_cvt_pk_f32_fp8_sdwa v[102:103], v137 src0_sel:WORD_1
	v_readlane_b32 s0, v228, 50
	s_ashr_i32 s1, s0, 31
	v_mul_f32_e32 v97, v221, v97
	v_fmac_f32_e32 v97, v219, v96
	v_fmac_f32_e32 v97, v212, v102
	s_lshl_b64 s[0:1], s[0:1], 10
	v_fmac_f32_e32 v97, v213, v103
	s_waitcnt vmcnt(9)
	v_cvt_pk_f32_fp8_e32 v[102:103], v126
	v_lshl_add_u64 v[26:27], v[182:183], 0, s[0:1]
	global_load_dwordx4 v[138:141], v[26:27], off
	v_add_f32_e32 v96, v104, v97
	v_cvt_pk_f32_fp8_sdwa v[104:105], v126 src0_sel:WORD_1
	v_mul_f32_e32 v97, v226, v103
	v_fmac_f32_e32 v97, v225, v102
	v_cvt_pk_f32_fp8_e32 v[102:103], v127
	v_fmac_f32_e32 v97, v220, v104
	v_fmac_f32_e32 v97, v223, v105
	v_cvt_pk_f32_fp8_sdwa v[104:105], v127 src0_sel:WORD_1
	v_mul_f32_e32 v103, v222, v103
	v_fmac_f32_e32 v103, v218, v102
	v_add_f32_e32 v97, 0, v97
	v_fmac_f32_e32 v103, v215, v104
	v_fmac_f32_e32 v103, v217, v105
	v_add_f32_e32 v97, v97, v103
	v_cvt_pk_f32_fp8_e32 v[102:103], v128
	v_cvt_pk_f32_fp8_sdwa v[104:105], v128 src0_sel:WORD_1
	v_readlane_b32 s0, v228, 51
	s_ashr_i32 s1, s0, 31
	v_mul_f32_e32 v103, v216, v103
	v_fmac_f32_e32 v103, v214, v102
	v_fmac_f32_e32 v103, v211, v104
	s_lshl_b64 s[0:1], s[0:1], 10
	v_fmac_f32_e32 v103, v224, v105
	v_lshl_add_u64 v[26:27], v[182:183], 0, s[0:1]
	v_add_f32_e32 v97, v97, v103
	v_cvt_pk_f32_fp8_e32 v[102:103], v129
	global_load_dwordx4 v[122:125], v[26:27], off
	v_cvt_pk_f32_fp8_sdwa v[104:105], v129 src0_sel:WORD_1
	v_readlane_b32 s0, v228, 52
	v_mul_f32_e32 v103, v221, v103
	v_fmac_f32_e32 v103, v219, v102
	v_fmac_f32_e32 v103, v212, v104
	v_fmac_f32_e32 v103, v213, v105
	v_add_f32_e32 v97, v97, v103
	s_waitcnt vmcnt(10)
	v_cvt_pk_f32_fp8_e32 v[102:103], v118
	v_cvt_pk_f32_fp8_sdwa v[104:105], v118 src0_sel:WORD_1
	s_ashr_i32 s1, s0, 31
	s_lshl_b64 s[0:1], s[0:1], 10
	v_mul_f32_e32 v103, v226, v103
	v_fmac_f32_e32 v103, v225, v102
	v_fmac_f32_e32 v103, v220, v104
	v_fmac_f32_e32 v103, v223, v105
	v_add_f32_e32 v110, 0, v103
	v_cvt_pk_f32_fp8_e32 v[102:103], v119
	v_cvt_pk_f32_fp8_sdwa v[104:105], v119 src0_sel:WORD_1
	v_lshl_add_u64 v[26:27], v[182:183], 0, s[0:1]
	global_load_dwordx4 v[114:117], v[26:27], off
	v_mul_f32_e32 v103, v222, v103
	v_fmac_f32_e32 v103, v218, v102
	v_fmac_f32_e32 v103, v215, v104
	v_fmac_f32_e32 v103, v217, v105
	v_add_f32_e32 v110, v110, v103
	v_cvt_pk_f32_fp8_e32 v[102:103], v120
	v_cvt_pk_f32_fp8_sdwa v[104:105], v120 src0_sel:WORD_1
	s_waitcnt vmcnt(3)
; __device__ void phase_experts(const Params& p, int l) {
;     ...
;       {
;         const int nb = (bi + 1) & 7;
;         const int idv = bi == 7 ? idn0 : (nb < 4 ? id0 : id1);
; #pragma unroll
;         for (int j = 0; j < 16; ++j) {
;           const int row = __builtin_amdgcn_readlane(idv, (nb & 3) * 16 + j);
;           rbuf[(bi + 1) & 1][j] = *(const u32x4*)(U + (size_t)row * 1024 + lane * 16);
;         }
;     ...
;       for (int j = 0; j < 16; ++j) {
;         float acc = 0.f;
; #pragma unroll
;         for (int c = 0; c < 4; ++c) {
;           const f32x2 a = __builtin_amdgcn_cvt_pk_f32_fp8((int)ru[j][c], false), b2 = __builtin_amdgcn_cvt_pk_f32_fp8((int)ru[j][c], true);
;           acc += a.x * hv[c * 4] + a.y * hv[c * 4 + 1] + b2.x * hv[c * 4 + 2] + b2.y * hv[c * 4 + 3];
;         }
;         sj[j] = acc;
	v_cvt_pk_f32_fp8_e32 v[128:129], v146
	v_cvt_pk_f32_fp8_sdwa v[134:135], v146 src0_sel:WORD_1
	v_mul_f32_e32 v103, v216, v103
	v_fmac_f32_e32 v103, v214, v102
	v_fmac_f32_e32 v103, v211, v104
	v_fmac_f32_e32 v103, v224, v105
	v_add_f32_e32 v110, v110, v103
	v_cvt_pk_f32_fp8_e32 v[102:103], v121
	v_cvt_pk_f32_fp8_sdwa v[104:105], v121 src0_sel:WORD_1
	v_mul_f32_e32 v127, v226, v129
	v_fmac_f32_e32 v127, v225, v128
	v_mul_f32_e32 v103, v221, v103
	v_fmac_f32_e32 v103, v219, v102
	v_fmac_f32_e32 v103, v212, v104
	v_cvt_pk_f32_fp8_e32 v[128:129], v147
	v_fmac_f32_e32 v103, v213, v105
	v_cvt_pk_f32_fp8_e32 v[104:105], v82
	v_fmac_f32_e32 v127, v220, v134
	v_fmac_f32_e32 v127, v223, v135
	v_cvt_pk_f32_fp8_sdwa v[134:135], v147 src0_sel:WORD_1
	v_add_f32_e32 v102, v110, v103
	v_cvt_pk_f32_fp8_sdwa v[110:111], v82 src0_sel:WORD_1
	v_mul_f32_e32 v129, v222, v129
	v_mul_f32_e32 v82, v226, v105
	v_fmac_f32_e32 v129, v218, v128
	v_fmac_f32_e32 v82, v225, v104
	v_fmac_f32_e32 v129, v215, v134
	v_fmac_f32_e32 v82, v220, v110
	v_cvt_pk_f32_fp8_e32 v[104:105], v83
	v_add_f32_e32 v127, 0, v127
	v_fmac_f32_e32 v129, v217, v135
	v_fmac_f32_e32 v82, v223, v111
	v_add_f32_e32 v127, v127, v129
	v_cvt_pk_f32_fp8_e32 v[128:129], v148
	v_add_f32_e32 v103, 0, v82
	v_cvt_pk_f32_fp8_sdwa v[82:83], v83 src0_sel:WORD_1
	v_cvt_pk_f32_fp8_sdwa v[134:135], v148 src0_sel:WORD_1
	v_mul_f32_e32 v105, v222, v105
	v_fmac_f32_e32 v105, v218, v104
	v_mul_f32_e32 v129, v216, v129
	v_fmac_f32_e32 v105, v215, v82
	v_fmac_f32_e32 v129, v214, v128
	v_fmac_f32_e32 v105, v217, v83
	v_cvt_pk_f32_fp8_e32 v[82:83], v84
	v_fmac_f32_e32 v129, v211, v134
	v_readlane_b32 s0, v228, 53
	v_fmac_f32_e32 v129, v224, v135
	s_ashr_i32 s1, s0, 31
	v_add_f32_e32 v103, v103, v105
	v_cvt_pk_f32_fp8_sdwa v[104:105], v84 src0_sel:WORD_1
	v_add_f32_e32 v127, v127, v129
	v_cvt_pk_f32_fp8_e32 v[128:129], v149
	s_lshl_b64 s[0:1], s[0:1], 10
	v_lshl_add_u64 v[26:27], v[182:183], 0, s[0:1]
	v_mul_f32_e32 v83, v216, v83
	v_cvt_pk_f32_fp8_sdwa v[134:135], v149 src0_sel:WORD_1
	global_load_dwordx4 v[106:109], v[26:27], off
	v_fmac_f32_e32 v83, v214, v82
	v_fmac_f32_e32 v83, v211, v104
	v_mul_f32_e32 v129, v221, v129
	v_fmac_f32_e32 v83, v224, v105
	v_fmac_f32_e32 v129, v219, v128
	v_add_f32_e32 v103, v103, v83
	v_cvt_pk_f32_fp8_e32 v[82:83], v85
	v_fmac_f32_e32 v129, v212, v134
	v_fmac_f32_e32 v129, v213, v135
	s_waitcnt vmcnt(3)
	v_cvt_pk_f32_fp8_e32 v[134:135], v138
	v_cvt_pk_f32_fp8_sdwa v[84:85], v85 src0_sel:WORD_1
	v_cvt_pk_f32_fp8_sdwa v[136:137], v138 src0_sel:WORD_1
	v_mul_f32_e32 v83, v221, v83
	v_fmac_f32_e32 v83, v219, v82
	v_add_f32_e32 v128, v127, v129
	v_mul_f32_e32 v127, v226, v135
	v_fmac_f32_e32 v83, v212, v84
	v_fmac_f32_e32 v127, v225, v134
	v_cvt_pk_f32_fp8_e32 v[134:135], v139
	v_fmac_f32_e32 v83, v213, v85
	v_cvt_pk_f32_fp8_e32 v[84:85], v70
	v_fmac_f32_e32 v127, v220, v136
	v_fmac_f32_e32 v127, v223, v137
	v_cvt_pk_f32_fp8_sdwa v[136:137], v139 src0_sel:WORD_1
	v_cvt_pk_f32_fp8_sdwa v[104:105], v70 src0_sel:WORD_1
	v_mul_f32_e32 v129, v222, v135
	v_mul_f32_e32 v70, v226, v85
	v_fmac_f32_e32 v129, v218, v134
	v_cvt_pk_f32_fp8_e32 v[134:135], v140
	v_fmac_f32_e32 v70, v225, v84
	v_fmac_f32_e32 v129, v215, v136
	v_fmac_f32_e32 v70, v220, v104
	v_cvt_pk_f32_fp8_e32 v[84:85], v71
	v_fmac_f32_e32 v129, v217, v137
	v_cvt_pk_f32_fp8_sdwa v[136:137], v140 src0_sel:WORD_1
	v_fmac_f32_e32 v70, v223, v105
	v_add_f32_e32 v127, 0, v127
	v_add_f32_e32 v82, v103, v83
	v_add_f32_e32 v83, 0, v70
	v_cvt_pk_f32_fp8_sdwa v[70:71], v71 src0_sel:WORD_1
	v_add_f32_e32 v127, v127, v129
	v_mul_f32_e32 v129, v216, v135
	v_fmac_f32_e32 v129, v214, v134
	v_cvt_pk_f32_fp8_e32 v[134:135], v141
	v_mul_f32_e32 v85, v222, v85
	v_fmac_f32_e32 v129, v211, v136
	v_fmac_f32_e32 v85, v218, v84
	v_fmac_f32_e32 v129, v224, v137
	v_cvt_pk_f32_fp8_sdwa v[136:137], v141 src0_sel:WORD_1
	v_fmac_f32_e32 v85, v215, v70
	v_fmac_f32_e32 v85, v217, v71
	v_cvt_pk_f32_fp8_e32 v[70:71], v72
	v_add_f32_e32 v127, v127, v129
	v_mul_f32_e32 v129, v221, v135
	v_readlane_b32 s0, v228, 54
	v_fmac_f32_e32 v129, v219, v134
	s_waitcnt vmcnt(2)
	v_cvt_pk_f32_fp8_e32 v[134:135], v122
	s_ashr_i32 s1, s0, 31
	v_add_f32_e32 v83, v83, v85
	v_cvt_pk_f32_fp8_sdwa v[84:85], v72 src0_sel:WORD_1
	v_fmac_f32_e32 v129, v212, v136
	s_lshl_b64 s[0:1], s[0:1], 10
	v_fmac_f32_e32 v129, v213, v137
	v_cvt_pk_f32_fp8_sdwa v[136:137], v122 src0_sel:WORD_1
	v_lshl_add_u64 v[26:27], v[182:183], 0, s[0:1]
	v_mul_f32_e32 v71, v216, v71
	global_load_dwordx4 v[98:101], v[26:27], off
	v_fmac_f32_e32 v71, v214, v70
	v_mul_f32_e32 v122, v226, v135
	v_fmac_f32_e32 v71, v211, v84
	v_fmac_f32_e32 v122, v225, v134
	v_fmac_f32_e32 v71, v224, v85
	v_fmac_f32_e32 v122, v220, v136
	v_cvt_pk_f32_fp8_e32 v[134:135], v123
	v_add_f32_e32 v83, v83, v71
	v_cvt_pk_f32_fp8_e32 v[70:71], v73
	v_fmac_f32_e32 v122, v223, v137
	v_add_f32_e32 v127, v127, v129
	v_add_f32_e32 v129, 0, v122
	v_cvt_pk_f32_fp8_sdwa v[122:123], v123 src0_sel:WORD_1
	v_cvt_pk_f32_fp8_sdwa v[72:73], v73 src0_sel:WORD_1
	v_mul_f32_e32 v135, v222, v135
	v_mul_f32_e32 v71, v221, v71
	v_fmac_f32_e32 v135, v218, v134
	v_fmac_f32_e32 v71, v219, v70
	v_fmac_f32_e32 v135, v215, v122
	v_fmac_f32_e32 v71, v212, v72
	v_fmac_f32_e32 v135, v217, v123
	v_cvt_pk_f32_fp8_e32 v[122:123], v124
	v_fmac_f32_e32 v71, v213, v73
	v_cvt_pk_f32_fp8_e32 v[72:73], v62
	v_add_f32_e32 v129, v129, v135
	v_cvt_pk_f32_fp8_sdwa v[134:135], v124 src0_sel:WORD_1
	v_cvt_pk_f32_fp8_sdwa v[84:85], v62 src0_sel:WORD_1
	v_mul_f32_e32 v123, v216, v123
	v_mul_f32_e32 v62, v226, v73
	v_fmac_f32_e32 v123, v214, v122
	v_fmac_f32_e32 v62, v225, v72
	v_fmac_f32_e32 v123, v211, v134
	v_fmac_f32_e32 v62, v220, v84
	v_cvt_pk_f32_fp8_e32 v[72:73], v63
	v_fmac_f32_e32 v123, v224, v135
	v_fmac_f32_e32 v62, v223, v85
	v_add_f32_e32 v129, v129, v123
	v_cvt_pk_f32_fp8_e32 v[122:123], v125
	v_add_f32_e32 v70, v83, v71
	v_add_f32_e32 v71, 0, v62
	v_cvt_pk_f32_fp8_sdwa v[62:63], v63 src0_sel:WORD_1
	v_cvt_pk_f32_fp8_sdwa v[124:125], v125 src0_sel:WORD_1
	v_mul_f32_e32 v73, v222, v73
	v_fmac_f32_e32 v73, v218, v72
	v_mul_f32_e32 v123, v221, v123
	v_fmac_f32_e32 v73, v215, v62
	v_fmac_f32_e32 v123, v219, v122
	v_fmac_f32_e32 v73, v217, v63
	v_cvt_pk_f32_fp8_e32 v[62:63], v64
	v_fmac_f32_e32 v123, v212, v124
	v_readlane_b32 s0, v228, 55
	v_fmac_f32_e32 v123, v213, v125
	s_waitcnt vmcnt(2)
; __device__ void phase_experts(const Params& p, int l) {
;     ...
;       {
;         const int nb = (bi + 1) & 7;
;         const int idv = bi == 7 ? idn0 : (nb < 4 ? id0 : id1);
; #pragma unroll
;         for (int j = 0; j < 16; ++j) {
;           const int row = __builtin_amdgcn_readlane(idv, (nb & 3) * 16 + j);
;           rbuf[(bi + 1) & 1][j] = *(const u32x4*)(U + (size_t)row * 1024 + lane * 16);
;         }
;     ...
;       for (int j = 0; j < 16; ++j) {
;         float acc = 0.f;
; #pragma unroll
;         for (int c = 0; c < 4; ++c) {
;           const f32x2 a = __builtin_amdgcn_cvt_pk_f32_fp8((int)ru[j][c], false), b2 = __builtin_amdgcn_cvt_pk_f32_fp8((int)ru[j][c], true);
;           acc += a.x * hv[c * 4] + a.y * hv[c * 4 + 1] + b2.x * hv[c * 4 + 2] + b2.y * hv[c * 4 + 3];
;         }
;         sj[j] = acc;
	v_cvt_pk_f32_fp8_e32 v[124:125], v114
	s_ashr_i32 s1, s0, 31
	v_add_f32_e32 v71, v71, v73
	v_cvt_pk_f32_fp8_sdwa v[72:73], v64 src0_sel:WORD_1
	s_lshl_b64 s[0:1], s[0:1], 10
	v_cvt_pk_f32_fp8_sdwa v[134:135], v114 src0_sel:WORD_1
	v_lshl_add_u64 v[26:27], v[182:183], 0, s[0:1]
	v_mul_f32_e32 v63, v216, v63
	global_load_dwordx4 v[90:93], v[26:27], off
	v_fmac_f32_e32 v63, v214, v62
	v_mul_f32_e32 v114, v226, v125
	v_fmac_f32_e32 v63, v211, v72
	v_fmac_f32_e32 v114, v225, v124
	v_fmac_f32_e32 v63, v224, v73
	v_fmac_f32_e32 v114, v220, v134
	v_cvt_pk_f32_fp8_e32 v[124:125], v115
	v_add_f32_e32 v71, v71, v63
	v_cvt_pk_f32_fp8_e32 v[62:63], v65
	v_fmac_f32_e32 v114, v223, v135
	v_add_f32_e32 v122, v129, v123
	v_add_f32_e32 v123, 0, v114
	v_cvt_pk_f32_fp8_sdwa v[114:115], v115 src0_sel:WORD_1
	v_cvt_pk_f32_fp8_sdwa v[64:65], v65 src0_sel:WORD_1
	v_mul_f32_e32 v125, v222, v125
	v_mul_f32_e32 v63, v221, v63
	v_fmac_f32_e32 v125, v218, v124
	v_fmac_f32_e32 v63, v219, v62
	v_fmac_f32_e32 v125, v215, v114
	v_fmac_f32_e32 v63, v212, v64
	v_fmac_f32_e32 v125, v217, v115
	v_cvt_pk_f32_fp8_e32 v[114:115], v116
	v_fmac_f32_e32 v63, v213, v65
	v_cvt_pk_f32_fp8_e32 v[64:65], v54
	v_add_f32_e32 v123, v123, v125
	v_cvt_pk_f32_fp8_sdwa v[124:125], v116 src0_sel:WORD_1
	v_cvt_pk_f32_fp8_sdwa v[72:73], v54 src0_sel:WORD_1
	v_mul_f32_e32 v115, v216, v115
	v_mul_f32_e32 v54, v226, v65
	v_fmac_f32_e32 v115, v214, v114
	v_fmac_f32_e32 v54, v225, v64
	v_fmac_f32_e32 v115, v211, v124
	v_fmac_f32_e32 v54, v220, v72
	v_cvt_pk_f32_fp8_e32 v[64:65], v55
	v_fmac_f32_e32 v115, v224, v125
	v_fmac_f32_e32 v54, v223, v73
	v_add_f32_e32 v123, v123, v115
	v_cvt_pk_f32_fp8_e32 v[114:115], v117
	v_add_f32_e32 v62, v71, v63
	v_add_f32_e32 v63, 0, v54
	v_cvt_pk_f32_fp8_sdwa v[54:55], v55 src0_sel:WORD_1
	v_cvt_pk_f32_fp8_sdwa v[116:117], v117 src0_sel:WORD_1
	v_mul_f32_e32 v65, v222, v65
	v_fmac_f32_e32 v65, v218, v64
	v_mul_f32_e32 v115, v221, v115
	v_fmac_f32_e32 v65, v215, v54
	v_fmac_f32_e32 v115, v219, v114
	v_fmac_f32_e32 v65, v217, v55
	v_cvt_pk_f32_fp8_e32 v[54:55], v56
	v_fmac_f32_e32 v115, v212, v116
	v_readlane_b32 s0, v228, 56
	v_fmac_f32_e32 v115, v213, v117
	s_waitcnt vmcnt(2)
	v_cvt_pk_f32_fp8_e32 v[116:117], v106
	s_ashr_i32 s1, s0, 31
	v_add_f32_e32 v63, v63, v65
	v_cvt_pk_f32_fp8_sdwa v[64:65], v56 src0_sel:WORD_1
	s_lshl_b64 s[0:1], s[0:1], 10
	v_cvt_pk_f32_fp8_sdwa v[124:125], v106 src0_sel:WORD_1
	v_lshl_add_u64 v[26:27], v[182:183], 0, s[0:1]
	v_mul_f32_e32 v55, v216, v55
	global_load_dwordx4 v[86:89], v[26:27], off
	v_fmac_f32_e32 v55, v214, v54
	v_mul_f32_e32 v106, v226, v117
	v_fmac_f32_e32 v55, v211, v64
	v_fmac_f32_e32 v106, v225, v116
	v_fmac_f32_e32 v55, v224, v65
	v_fmac_f32_e32 v106, v220, v124
	v_cvt_pk_f32_fp8_e32 v[116:117], v107
	v_add_f32_e32 v63, v63, v55
	v_cvt_pk_f32_fp8_e32 v[54:55], v57
	v_fmac_f32_e32 v106, v223, v125
	v_add_f32_e32 v114, v123, v115
	v_add_f32_e32 v115, 0, v106
	v_cvt_pk_f32_fp8_sdwa v[106:107], v107 src0_sel:WORD_1
	v_cvt_pk_f32_fp8_sdwa v[56:57], v57 src0_sel:WORD_1
	v_mul_f32_e32 v117, v222, v117
	v_mul_f32_e32 v55, v221, v55
	v_fmac_f32_e32 v117, v218, v116
	v_fmac_f32_e32 v55, v219, v54
	v_fmac_f32_e32 v117, v215, v106
	v_fmac_f32_e32 v55, v212, v56
	v_fmac_f32_e32 v117, v217, v107
	v_cvt_pk_f32_fp8_e32 v[106:107], v108
	v_fmac_f32_e32 v55, v213, v57
	v_cvt_pk_f32_fp8_e32 v[56:57], v46
	v_add_f32_e32 v115, v115, v117
	v_cvt_pk_f32_fp8_sdwa v[116:117], v108 src0_sel:WORD_1
	v_cvt_pk_f32_fp8_sdwa v[64:65], v46 src0_sel:WORD_1
	v_mul_f32_e32 v107, v216, v107
	v_mul_f32_e32 v46, v226, v57
	v_fmac_f32_e32 v107, v214, v106
	v_fmac_f32_e32 v46, v225, v56
	v_fmac_f32_e32 v107, v211, v116
	v_fmac_f32_e32 v46, v220, v64
	v_cvt_pk_f32_fp8_e32 v[56:57], v47
	v_fmac_f32_e32 v107, v224, v117
	v_fmac_f32_e32 v46, v223, v65
	v_add_f32_e32 v115, v115, v107
	v_cvt_pk_f32_fp8_e32 v[106:107], v109
	v_add_f32_e32 v54, v63, v55
	v_add_f32_e32 v55, 0, v46
	v_cvt_pk_f32_fp8_sdwa v[46:47], v47 src0_sel:WORD_1
	v_cvt_pk_f32_fp8_sdwa v[108:109], v109 src0_sel:WORD_1
	v_mul_f32_e32 v57, v222, v57
	v_readlane_b32 s0, v228, 57
	v_fmac_f32_e32 v57, v218, v56
	v_mul_f32_e32 v107, v221, v107
	s_ashr_i32 s1, s0, 31
	v_fmac_f32_e32 v57, v215, v46
	v_fmac_f32_e32 v107, v219, v106
	s_lshl_b64 s[0:1], s[0:1], 10
	v_fmac_f32_e32 v57, v217, v47
	v_cvt_pk_f32_fp8_e32 v[46:47], v48
	v_fmac_f32_e32 v107, v212, v108
	v_lshl_add_u64 v[26:27], v[182:183], 0, s[0:1]
	v_readlane_b32 s0, v228, 58
	v_fmac_f32_e32 v107, v213, v109
	s_waitcnt vmcnt(2)
	v_cvt_pk_f32_fp8_e32 v[108:109], v98
	s_ashr_i32 s1, s0, 31
	v_add_f32_e32 v55, v55, v57
	v_cvt_pk_f32_fp8_sdwa v[56:57], v48 src0_sel:WORD_1
	s_lshl_b64 s[0:1], s[0:1], 10
	v_cvt_pk_f32_fp8_sdwa v[116:117], v98 src0_sel:WORD_1
	v_lshl_add_u64 v[34:35], v[182:183], 0, s[0:1]
	v_mul_f32_e32 v47, v216, v47
	global_load_dwordx4 v[74:77], v[34:35], off
	v_fmac_f32_e32 v47, v214, v46
	v_mul_f32_e32 v98, v226, v109
	v_fmac_f32_e32 v47, v211, v56
	v_fmac_f32_e32 v98, v225, v108
	v_fmac_f32_e32 v47, v224, v57
	v_fmac_f32_e32 v98, v220, v116
	v_cvt_pk_f32_fp8_e32 v[108:109], v99
	v_add_f32_e32 v55, v55, v47
	v_cvt_pk_f32_fp8_e32 v[46:47], v49
	v_fmac_f32_e32 v98, v223, v117
	v_add_f32_e32 v106, v115, v107
	v_add_f32_e32 v107, 0, v98
	v_cvt_pk_f32_fp8_sdwa v[98:99], v99 src0_sel:WORD_1
	v_cvt_pk_f32_fp8_sdwa v[48:49], v49 src0_sel:WORD_1
	v_mul_f32_e32 v109, v222, v109
	v_mul_f32_e32 v47, v221, v47
	v_fmac_f32_e32 v109, v218, v108
	v_fmac_f32_e32 v47, v219, v46
	v_fmac_f32_e32 v109, v215, v98
	v_fmac_f32_e32 v47, v212, v48
	v_fmac_f32_e32 v109, v217, v99
	v_cvt_pk_f32_fp8_e32 v[98:99], v100
	v_fmac_f32_e32 v47, v213, v49
	v_cvt_pk_f32_fp8_e32 v[48:49], v38
	v_add_f32_e32 v107, v107, v109
	v_cvt_pk_f32_fp8_sdwa v[108:109], v100 src0_sel:WORD_1
	v_cvt_pk_f32_fp8_sdwa v[56:57], v38 src0_sel:WORD_1
	v_mul_f32_e32 v99, v216, v99
	v_mul_f32_e32 v38, v226, v49
	v_fmac_f32_e32 v99, v214, v98
	v_fmac_f32_e32 v38, v225, v48
	v_fmac_f32_e32 v99, v211, v108
	v_fmac_f32_e32 v38, v220, v56
	v_cvt_pk_f32_fp8_e32 v[48:49], v39
	v_fmac_f32_e32 v99, v224, v109
	v_fmac_f32_e32 v38, v223, v57
	v_add_f32_e32 v107, v107, v99
	v_cvt_pk_f32_fp8_e32 v[98:99], v101
	v_add_f32_e32 v46, v55, v47
	v_add_f32_e32 v47, 0, v38
	v_cvt_pk_f32_fp8_sdwa v[38:39], v39 src0_sel:WORD_1
	v_cvt_pk_f32_fp8_sdwa v[100:101], v101 src0_sel:WORD_1
	v_mul_f32_e32 v49, v222, v49
	v_fmac_f32_e32 v49, v218, v48
	v_mul_f32_e32 v99, v221, v99
	v_fmac_f32_e32 v49, v215, v38
	v_fmac_f32_e32 v99, v219, v98
	v_fmac_f32_e32 v49, v217, v39
	v_cvt_pk_f32_fp8_e32 v[38:39], v40
	v_fmac_f32_e32 v99, v212, v100
	v_readlane_b32 s0, v228, 59
	v_fmac_f32_e32 v99, v213, v101
	s_waitcnt vmcnt(2)
; __device__ void phase_experts(const Params& p, int l) {
;     ...
;       {
;         const int nb = (bi + 1) & 7;
;         const int idv = bi == 7 ? idn0 : (nb < 4 ? id0 : id1);
; #pragma unroll
;         for (int j = 0; j < 16; ++j) {
;           const int row = __builtin_amdgcn_readlane(idv, (nb & 3) * 16 + j);
;           rbuf[(bi + 1) & 1][j] = *(const u32x4*)(U + (size_t)row * 1024 + lane * 16);
;         }
;     ...
;       for (int j = 0; j < 16; ++j) {
;         float acc = 0.f;
; #pragma unroll
;         for (int c = 0; c < 4; ++c) {
;           const f32x2 a = __builtin_amdgcn_cvt_pk_f32_fp8((int)ru[j][c], false), b2 = __builtin_amdgcn_cvt_pk_f32_fp8((int)ru[j][c], true);
;           acc += a.x * hv[c * 4] + a.y * hv[c * 4 + 1] + b2.x * hv[c * 4 + 2] + b2.y * hv[c * 4 + 3];
;         }
;         sj[j] = acc;
;       }
; #pragma unroll
;       for (int hw = 8; hw >= 1; hw >>= 1) {
;         const bool up = (lane & hw) != 0;
; #pragma unroll
;         for (int k = 0; k < hw; ++k) {
;           const float send = up ? sj[k] : sj[k + hw], keep = up ? sj[k + hw] : sj[k];
;           sj[k] = keep + __shfl_xor(send, hw);
;         }
;       }
	v_cvt_pk_f32_fp8_e32 v[100:101], v90
	s_ashr_i32 s1, s0, 31
	v_add_f32_e32 v47, v47, v49
	v_cvt_pk_f32_fp8_sdwa v[48:49], v40 src0_sel:WORD_1
	s_lshl_b64 s[0:1], s[0:1], 10
	v_cvt_pk_f32_fp8_sdwa v[108:109], v90 src0_sel:WORD_1
	v_lshl_add_u64 v[34:35], v[182:183], 0, s[0:1]
	v_mul_f32_e32 v39, v216, v39
	global_load_dwordx4 v[66:69], v[34:35], off
	v_fmac_f32_e32 v39, v214, v38
	v_mul_f32_e32 v90, v226, v101
	v_fmac_f32_e32 v39, v211, v48
	v_fmac_f32_e32 v90, v225, v100
	v_fmac_f32_e32 v39, v224, v49
	v_fmac_f32_e32 v90, v220, v108
	v_cvt_pk_f32_fp8_e32 v[100:101], v91
	v_add_f32_e32 v47, v47, v39
	v_cvt_pk_f32_fp8_e32 v[38:39], v41
	v_fmac_f32_e32 v90, v223, v109
	v_add_f32_e32 v98, v107, v99
	v_add_f32_e32 v99, 0, v90
	v_cvt_pk_f32_fp8_sdwa v[90:91], v91 src0_sel:WORD_1
	v_mul_f32_e32 v101, v222, v101
	v_cvt_pk_f32_fp8_sdwa v[40:41], v41 src0_sel:WORD_1
	v_mul_f32_e32 v39, v221, v39
	v_fmac_f32_e32 v101, v218, v100
	v_fmac_f32_e32 v39, v219, v38
	v_cndmask_b32_e32 v38, v94, v102, vcc
	v_fmac_f32_e32 v101, v215, v90
	ds_bpermute_b32 v38, v205, v38
	v_fmac_f32_e32 v101, v217, v91
	v_cvt_pk_f32_fp8_e32 v[90:91], v92
	v_fmac_f32_e32 v39, v212, v40
	v_add_f32_e32 v99, v99, v101
	v_cvt_pk_f32_fp8_sdwa v[100:101], v92 src0_sel:WORD_1
	v_fmac_f32_e32 v39, v213, v41
	v_add_f32_e32 v40, v47, v39
	v_cndmask_b32_e32 v39, v102, v94, vcc
	v_mul_f32_e32 v91, v216, v91
	s_waitcnt lgkmcnt(0)
	v_add_f32_e32 v41, v39, v38
	v_cvt_pk_f32_fp8_e32 v[38:39], v30
	v_fmac_f32_e32 v91, v214, v90
	v_fmac_f32_e32 v91, v211, v100
	v_fmac_f32_e32 v91, v224, v101
	v_add_f32_e32 v99, v99, v91
	v_cvt_pk_f32_fp8_e32 v[90:91], v93
	v_mul_f32_e32 v47, v226, v39
	v_fmac_f32_e32 v47, v225, v38
	v_cvt_pk_f32_fp8_sdwa v[38:39], v30 src0_sel:WORD_1
	v_cvt_pk_f32_fp8_sdwa v[92:93], v93 src0_sel:WORD_1
	v_mul_f32_e32 v91, v221, v91
	v_fmac_f32_e32 v91, v219, v90
	v_fmac_f32_e32 v47, v220, v38
	v_fmac_f32_e32 v91, v212, v92
	v_readlane_b32 s0, v228, 60
	v_fmac_f32_e32 v47, v223, v39
	v_cvt_pk_f32_fp8_e32 v[38:39], v31
	v_fmac_f32_e32 v91, v213, v93
	s_waitcnt vmcnt(2)
	v_cvt_pk_f32_fp8_e32 v[92:93], v86
	s_ashr_i32 s1, s0, 31
	s_lshl_b64 s[0:1], s[0:1], 10
	v_cvt_pk_f32_fp8_sdwa v[30:31], v31 src0_sel:WORD_1
	v_cvt_pk_f32_fp8_sdwa v[100:101], v86 src0_sel:WORD_1
	v_lshl_add_u64 v[34:35], v[182:183], 0, s[0:1]
	global_load_dwordx4 v[58:61], v[34:35], off
	v_mul_f32_e32 v39, v222, v39
	v_mul_f32_e32 v86, v226, v93
	v_fmac_f32_e32 v39, v218, v38
	v_fmac_f32_e32 v86, v225, v92
	v_fmac_f32_e32 v39, v215, v30
	v_fmac_f32_e32 v86, v220, v100
	v_cvt_pk_f32_fp8_e32 v[92:93], v87
	v_fmac_f32_e32 v39, v217, v31
	v_cvt_pk_f32_fp8_e32 v[30:31], v32
	v_fmac_f32_e32 v86, v223, v101
	v_add_f32_e32 v90, v99, v91
	v_add_f32_e32 v91, 0, v86
	v_cvt_pk_f32_fp8_sdwa v[86:87], v87 src0_sel:WORD_1
	v_add_f32_e32 v47, 0, v47
	v_mul_f32_e32 v93, v222, v93
	v_add_f32_e32 v38, v47, v39
	v_mul_f32_e32 v39, v216, v31
	v_fmac_f32_e32 v93, v218, v92
	v_fmac_f32_e32 v39, v214, v30
	v_cvt_pk_f32_fp8_sdwa v[30:31], v32 src0_sel:WORD_1
	v_fmac_f32_e32 v93, v215, v86
	v_fmac_f32_e32 v93, v217, v87
	v_cvt_pk_f32_fp8_e32 v[86:87], v88
	v_add_f32_e32 v91, v91, v93
	v_cvt_pk_f32_fp8_sdwa v[92:93], v88 src0_sel:WORD_1
	v_fmac_f32_e32 v39, v211, v30
	v_fmac_f32_e32 v39, v224, v31
	v_cvt_pk_f32_fp8_e32 v[30:31], v33
	v_mul_f32_e32 v87, v216, v87
	v_fmac_f32_e32 v87, v214, v86
	v_fmac_f32_e32 v87, v211, v92
	v_fmac_f32_e32 v87, v224, v93
	v_add_f32_e32 v32, v38, v39
	v_mul_f32_e32 v38, v221, v31
	v_add_f32_e32 v91, v91, v87
	v_cvt_pk_f32_fp8_e32 v[86:87], v89
	v_fmac_f32_e32 v38, v219, v30
	v_cvt_pk_f32_fp8_sdwa v[30:31], v33 src0_sel:WORD_1
	v_cvt_pk_f32_fp8_sdwa v[88:89], v89 src0_sel:WORD_1
	v_mul_f32_e32 v87, v221, v87
	v_fmac_f32_e32 v87, v219, v86
	v_fmac_f32_e32 v38, v212, v30
	v_fmac_f32_e32 v38, v213, v31
	v_cvt_pk_f32_fp8_e32 v[30:31], v22
	v_fmac_f32_e32 v87, v212, v88
	v_readlane_b32 s0, v228, 61
	v_fmac_f32_e32 v87, v213, v89
	s_waitcnt vmcnt(2)
	v_cvt_pk_f32_fp8_e32 v[88:89], v74
	s_ashr_i32 s1, s0, 31
	s_lshl_b64 s[0:1], s[0:1], 10
	v_cvt_pk_f32_fp8_sdwa v[92:93], v74 src0_sel:WORD_1
	v_lshl_add_u64 v[34:35], v[182:183], 0, s[0:1]
	v_mul_f32_e32 v33, v226, v31
	global_load_dwordx4 v[50:53], v[34:35], off
	v_fmac_f32_e32 v33, v225, v30
	v_cvt_pk_f32_fp8_sdwa v[30:31], v22 src0_sel:WORD_1
	v_mul_f32_e32 v74, v226, v89
	v_fmac_f32_e32 v74, v225, v88
	v_fmac_f32_e32 v74, v220, v92
	v_cvt_pk_f32_fp8_e32 v[88:89], v75
	v_fmac_f32_e32 v74, v223, v93
	v_fmac_f32_e32 v33, v220, v30
	v_add_f32_e32 v86, v91, v87
	v_add_f32_e32 v87, 0, v74
	v_cvt_pk_f32_fp8_sdwa v[74:75], v75 src0_sel:WORD_1
	v_fmac_f32_e32 v33, v223, v31
	v_cvt_pk_f32_fp8_e32 v[30:31], v23
	v_mul_f32_e32 v89, v222, v89
	v_cvt_pk_f32_fp8_sdwa v[22:23], v23 src0_sel:WORD_1
	v_fmac_f32_e32 v89, v218, v88
	v_fmac_f32_e32 v89, v215, v74
	v_mul_f32_e32 v31, v222, v31
	v_fmac_f32_e32 v89, v217, v75
	v_cvt_pk_f32_fp8_e32 v[74:75], v76
	v_fmac_f32_e32 v31, v218, v30
	v_fmac_f32_e32 v31, v215, v22
	v_add_f32_e32 v87, v87, v89
	v_cvt_pk_f32_fp8_sdwa v[88:89], v76 src0_sel:WORD_1
	v_fmac_f32_e32 v31, v217, v23
	v_cvt_pk_f32_fp8_e32 v[22:23], v24
	v_mul_f32_e32 v75, v216, v75
	v_fmac_f32_e32 v75, v214, v74
	v_add_f32_e32 v33, 0, v33
	v_fmac_f32_e32 v75, v211, v88
	v_add_f32_e32 v30, v33, v31
	v_mul_f32_e32 v31, v216, v23
	v_fmac_f32_e32 v75, v224, v89
	v_fmac_f32_e32 v31, v214, v22
	v_cvt_pk_f32_fp8_sdwa v[22:23], v24 src0_sel:WORD_1
	v_add_f32_e32 v87, v87, v75
	v_cvt_pk_f32_fp8_e32 v[74:75], v77
	v_cvt_pk_f32_fp8_sdwa v[76:77], v77 src0_sel:WORD_1
	v_fmac_f32_e32 v31, v211, v22
	v_fmac_f32_e32 v31, v224, v23
	v_mul_f32_e32 v75, v221, v75
	v_cvt_pk_f32_fp8_e32 v[22:23], v25
	v_fmac_f32_e32 v75, v219, v74
	v_fmac_f32_e32 v75, v212, v76
	v_readlane_b32 s0, v228, 62
	v_fmac_f32_e32 v75, v213, v77
	s_waitcnt vmcnt(2)
; __device__ void phase_experts(const Params& p, int l) {
;     ...
;       for (int j = 0; j < 16; ++j) {
;         float acc = 0.f;
; #pragma unroll
;         for (int c = 0; c < 4; ++c) {
;           const f32x2 a = __builtin_amdgcn_cvt_pk_f32_fp8((int)ru[j][c], false), b2 = __builtin_amdgcn_cvt_pk_f32_fp8((int)ru[j][c], true);
;           acc += a.x * hv[c * 4] + a.y * hv[c * 4 + 1] + b2.x * hv[c * 4 + 2] + b2.y * hv[c * 4 + 3];
;         }
;         sj[j] = acc;
;       }
; #pragma unroll
;       for (int hw = 8; hw >= 1; hw >>= 1) {
;         const bool up = (lane & hw) != 0;
; #pragma unroll
;         for (int k = 0; k < hw; ++k) {
;           const float send = up ? sj[k] : sj[k + hw], keep = up ? sj[k + hw] : sj[k];
;           sj[k] = keep + __shfl_xor(send, hw);
;         }
;       }
	v_cvt_pk_f32_fp8_e32 v[76:77], v66
	s_ashr_i32 s1, s0, 31
	s_lshl_b64 s[0:1], s[0:1], 10
	v_add_f32_e32 v24, v30, v31
	v_mul_f32_e32 v30, v221, v23
	v_cvt_pk_f32_fp8_sdwa v[88:89], v66 src0_sel:WORD_1
	v_lshl_add_u64 v[34:35], v[182:183], 0, s[0:1]
	v_fmac_f32_e32 v30, v219, v22
	v_cvt_pk_f32_fp8_sdwa v[22:23], v25 src0_sel:WORD_1
	global_load_dwordx4 v[42:45], v[34:35], off
	v_mul_f32_e32 v66, v226, v77
	v_fmac_f32_e32 v66, v225, v76
	v_fmac_f32_e32 v66, v220, v88
	v_cvt_pk_f32_fp8_e32 v[76:77], v67
	v_fmac_f32_e32 v30, v212, v22
	v_fmac_f32_e32 v66, v223, v89
	v_fmac_f32_e32 v30, v213, v23
	v_add_f32_e32 v74, v87, v75
	v_add_f32_e32 v75, 0, v66
	v_cvt_pk_f32_fp8_sdwa v[66:67], v67 src0_sel:WORD_1
	v_add_f32_e32 v32, v32, v38
	v_add_f32_e32 v22, v24, v30
	v_cndmask_b32_e32 v23, v22, v32, vcc
	v_mul_f32_e32 v77, v222, v77
	ds_bpermute_b32 v23, v205, v23
	v_fmac_f32_e32 v77, v218, v76
	v_fmac_f32_e32 v77, v215, v66
	v_fmac_f32_e32 v77, v217, v67
	v_cvt_pk_f32_fp8_e32 v[66:67], v68
	v_cndmask_b32_e32 v22, v32, v22, vcc
	v_add_f32_e32 v75, v75, v77
	v_cvt_pk_f32_fp8_sdwa v[76:77], v68 src0_sel:WORD_1
	s_waitcnt lgkmcnt(0)
	v_add_f32_e32 v22, v22, v23
	v_cndmask_b32_e32 v23, v79, v82, vcc
	ds_bpermute_b32 v23, v205, v23
	v_mul_f32_e32 v67, v216, v67
	v_fmac_f32_e32 v67, v214, v66
	v_fmac_f32_e32 v67, v211, v76
	v_fmac_f32_e32 v67, v224, v77
	v_cndmask_b32_e32 v24, v82, v79, vcc
	v_add_f32_e32 v75, v75, v67
	v_cvt_pk_f32_fp8_e32 v[66:67], v69
	s_waitcnt lgkmcnt(0)
	v_add_f32_e32 v23, v24, v23
	v_cndmask_b32_e32 v24, v80, v70, vcc
	ds_bpermute_b32 v24, v205, v24
	v_cvt_pk_f32_fp8_sdwa v[68:69], v69 src0_sel:WORD_1
	v_mul_f32_e32 v67, v221, v67
	v_fmac_f32_e32 v67, v219, v66
	v_cndmask_b32_e32 v25, v70, v80, vcc
	v_fmac_f32_e32 v67, v212, v68
	v_readlane_b32 s0, v228, 63
	s_waitcnt lgkmcnt(0)
	v_add_f32_e32 v24, v25, v24
	v_cndmask_b32_e32 v25, v81, v62, vcc
	v_fmac_f32_e32 v67, v213, v69
	s_waitcnt vmcnt(2)
	v_cvt_pk_f32_fp8_e32 v[68:69], v58
	s_ashr_i32 s1, s0, 31
	ds_bpermute_b32 v25, v205, v25
	s_lshl_b64 s[0:1], s[0:1], 10
	v_cvt_pk_f32_fp8_sdwa v[76:77], v58 src0_sel:WORD_1
	v_lshl_add_u64 v[34:35], v[182:183], 0, s[0:1]
	global_load_dwordx4 v[34:37], v[34:35], off
	v_mul_f32_e32 v58, v226, v69
	v_cndmask_b32_e32 v30, v62, v81, vcc
	v_fmac_f32_e32 v58, v225, v68
	s_waitcnt lgkmcnt(0)
	v_add_f32_e32 v25, v30, v25
	v_cndmask_b32_e32 v30, v95, v54, vcc
	v_fmac_f32_e32 v58, v220, v76
	v_cvt_pk_f32_fp8_e32 v[68:69], v59
	ds_bpermute_b32 v30, v205, v30
	v_fmac_f32_e32 v58, v223, v77
	v_add_f32_e32 v66, v75, v67
	v_add_f32_e32 v67, 0, v58
	v_cvt_pk_f32_fp8_sdwa v[58:59], v59 src0_sel:WORD_1
	v_mul_f32_e32 v69, v222, v69
	v_cndmask_b32_e32 v31, v54, v95, vcc
	v_fmac_f32_e32 v69, v218, v68
	s_waitcnt lgkmcnt(0)
	v_add_f32_e32 v30, v31, v30
	v_cndmask_b32_e32 v31, v96, v46, vcc
	v_fmac_f32_e32 v69, v215, v58
	ds_bpermute_b32 v31, v205, v31
	v_fmac_f32_e32 v69, v217, v59
	v_cvt_pk_f32_fp8_e32 v[58:59], v60
	v_add_f32_e32 v67, v67, v69
	v_cvt_pk_f32_fp8_sdwa v[68:69], v60 src0_sel:WORD_1
	v_cndmask_b32_e32 v32, v46, v96, vcc
	v_mul_f32_e32 v59, v216, v59
	s_waitcnt lgkmcnt(0)
	v_add_f32_e32 v31, v32, v31
	v_cndmask_b32_e32 v32, v97, v40, vcc
	v_fmac_f32_e32 v59, v214, v58
	ds_bpermute_b32 v32, v205, v32
	v_fmac_f32_e32 v59, v211, v68
	v_fmac_f32_e32 v59, v224, v69
	v_add_f32_e32 v67, v67, v59
	v_cvt_pk_f32_fp8_e32 v[58:59], v61
	v_cndmask_b32_e32 v33, v40, v97, vcc
	v_cvt_pk_f32_fp8_sdwa v[60:61], v61 src0_sel:WORD_1
	s_waitcnt lgkmcnt(0)
	v_add_f32_e32 v32, v33, v32
	v_cndmask_b32_e64 v33, v41, v25, s[4:5]
	ds_bpermute_b32 v33, v206, v33
	v_mul_f32_e32 v59, v221, v59
	v_fmac_f32_e32 v59, v219, v58
	v_fmac_f32_e32 v59, v212, v60
	v_fmac_f32_e32 v59, v213, v61
	s_waitcnt vmcnt(2)
	v_cvt_pk_f32_fp8_e32 v[60:61], v50
	v_cndmask_b32_e64 v25, v25, v41, s[4:5]
	s_waitcnt lgkmcnt(0)
	v_add_f32_e32 v25, v25, v33
	v_cndmask_b32_e64 v33, v22, v30, s[4:5]
	v_cvt_pk_f32_fp8_sdwa v[68:69], v50 src0_sel:WORD_1
	v_cndmask_b32_e64 v22, v30, v22, s[4:5]
	ds_bpermute_b32 v30, v206, v33
	v_mul_f32_e32 v50, v226, v61
	v_fmac_f32_e32 v50, v225, v60
	v_fmac_f32_e32 v50, v220, v68
	v_cvt_pk_f32_fp8_e32 v[60:61], v51
	v_fmac_f32_e32 v50, v223, v69
	global_load_dwordx4 v[26:29], v[26:27], off
	s_waitcnt lgkmcnt(0)
	v_add_f32_e32 v22, v22, v30
	v_cndmask_b32_e64 v30, v23, v31, s[4:5]
	v_add_f32_e32 v58, v67, v59
	v_add_f32_e32 v59, 0, v50
	v_cvt_pk_f32_fp8_sdwa v[50:51], v51 src0_sel:WORD_1
	ds_bpermute_b32 v30, v206, v30
	v_mul_f32_e32 v61, v222, v61
	v_fmac_f32_e32 v61, v218, v60
	v_fmac_f32_e32 v61, v215, v50
	v_cndmask_b32_e64 v23, v31, v23, s[4:5]
	v_fmac_f32_e32 v61, v217, v51
	v_cvt_pk_f32_fp8_e32 v[50:51], v52
	s_waitcnt lgkmcnt(0)
	v_add_f32_e32 v23, v23, v30
	v_cndmask_b32_e64 v30, v24, v32, s[4:5]
	ds_bpermute_b32 v30, v206, v30
	v_add_f32_e32 v59, v59, v61
	v_cvt_pk_f32_fp8_sdwa v[60:61], v52 src0_sel:WORD_1
	v_mul_f32_e32 v51, v216, v51
	v_fmac_f32_e32 v51, v214, v50
	v_cndmask_b32_e64 v24, v32, v24, s[4:5]
	v_fmac_f32_e32 v51, v211, v60
	s_waitcnt lgkmcnt(0)
	v_add_f32_e32 v24, v24, v30
	v_cndmask_b32_e64 v30, v25, v23, s[6:7]
	v_fmac_f32_e32 v51, v224, v61
	v_cndmask_b32_e64 v23, v23, v25, s[6:7]
	ds_bpermute_b32 v25, v207, v30
	v_add_f32_e32 v59, v59, v51
	v_cvt_pk_f32_fp8_e32 v[50:51], v53
	v_cvt_pk_f32_fp8_sdwa v[52:53], v53 src0_sel:WORD_1
	s_waitcnt vmcnt(2)
	v_cvt_pk_f32_fp8_sdwa v[60:61], v42 src0_sel:WORD_1
	s_waitcnt lgkmcnt(0)
	v_add_f32_e32 v23, v23, v25
	v_mul_f32_e32 v51, v221, v51
	v_cndmask_b32_e64 v25, v22, v24, s[6:7]
	v_fmac_f32_e32 v51, v219, v50
	ds_bpermute_b32 v25, v207, v25
	v_fmac_f32_e32 v51, v212, v52
	v_fmac_f32_e32 v51, v213, v53
	v_cvt_pk_f32_fp8_e32 v[52:53], v42
	v_cndmask_b32_e64 v22, v24, v22, s[6:7]
	s_waitcnt lgkmcnt(0)
; __device__ void phase_experts(const Params& p, int l) {
;     ...
;       {
;         const int nb = (bi + 1) & 7;
;         const int idv = bi == 7 ? idn0 : (nb < 4 ? id0 : id1);
; #pragma unroll
;         for (int j = 0; j < 16; ++j) {
;           const int row = __builtin_amdgcn_readlane(idv, (nb & 3) * 16 + j);
;           rbuf[(bi + 1) & 1][j] = *(const u32x4*)(U + (size_t)row * 1024 + lane * 16);
;         }
;     ...
;       for (int hw = 8; hw >= 1; hw >>= 1) {
;         const bool up = (lane & hw) != 0;
; #pragma unroll
;         for (int k = 0; k < hw; ++k) {
;           const float send = up ? sj[k] : sj[k + hw], keep = up ? sj[k + hw] : sj[k];
;           sj[k] = keep + __shfl_xor(send, hw);
;         }
;       }
;       float tot = sj[0];
;       tot = xsum_rows(tot);
;       if ((lane >> 4) == (bi & 3)) { if (bi < 4) d0 = tot; else d1 = tot; }
	v_add_f32_e32 v22, v22, v25
	v_cndmask_b32_e64 v24, v23, v22, s[8:9]
	v_mul_f32_e32 v42, v226, v53
	v_fmac_f32_e32 v42, v225, v52
	v_cndmask_b32_e64 v22, v22, v23, s[8:9]
	ds_bpermute_b32 v23, v208, v24
	v_fmac_f32_e32 v42, v220, v60
	v_cvt_pk_f32_fp8_e32 v[52:53], v43
	v_fmac_f32_e32 v42, v223, v61
	v_add_f32_e32 v50, v59, v51
	v_add_f32_e32 v51, 0, v42
	v_cvt_pk_f32_fp8_sdwa v[42:43], v43 src0_sel:WORD_1
	v_mul_f32_e32 v53, v222, v53
	s_waitcnt lgkmcnt(0)
	v_add_f32_e32 v22, v22, v23
	v_fmac_f32_e32 v53, v218, v52
	v_mov_b32_e32 v23, v22
	v_fmac_f32_e32 v53, v215, v42
	s_nop 0
	v_permlane16_swap_b32_e32 v22, v23
	v_fmac_f32_e32 v53, v217, v43
	v_cvt_pk_f32_fp8_e32 v[42:43], v44
	v_add_f32_e32 v22, v22, v23
	v_mov_b32_e32 v23, v22
	v_readlane_b32 s0, v227, 0
	v_add_f32_e32 v51, v51, v53
	v_cvt_pk_f32_fp8_sdwa v[52:53], v44 src0_sel:WORD_1
	v_permlane32_swap_b32_e32 v22, v23
	s_ashr_i32 s1, s0, 31
	global_load_dwordx4 v[18:21], v[18:19], off
	v_add_f32_e32 v22, v22, v23
	s_lshl_b64 s[0:1], s[0:1], 10
	v_mul_f32_e32 v43, v216, v43
	v_cndmask_b32_e64 v126, v78, v22, s[14:15]
	v_lshl_add_u64 v[22:23], v[182:183], 0, s[0:1]
	v_readlane_b32 s0, v227, 1
	v_fmac_f32_e32 v43, v214, v42
	s_ashr_i32 s1, s0, 31
	v_fmac_f32_e32 v43, v211, v52
	s_lshl_b64 s[0:1], s[0:1], 10
	v_fmac_f32_e32 v43, v224, v53
	global_load_dwordx4 v[154:157], v[22:23], off
	v_lshl_add_u64 v[22:23], v[182:183], 0, s[0:1]
	v_readlane_b32 s0, v227, 2
	v_add_f32_e32 v51, v51, v43
	v_cvt_pk_f32_fp8_e32 v[42:43], v45
	s_ashr_i32 s1, s0, 31
	s_lshl_b64 s[0:1], s[0:1], 10
	v_cvt_pk_f32_fp8_sdwa v[44:45], v45 src0_sel:WORD_1
	v_lshl_add_u64 v[30:31], v[182:183], 0, s[0:1]
	v_readlane_b32 s0, v227, 3
	s_ashr_i32 s1, s0, 31
	v_mul_f32_e32 v43, v221, v43
	s_lshl_b64 s[0:1], s[0:1], 10
	v_fmac_f32_e32 v43, v219, v42
	global_load_dwordx4 v[142:145], v[30:31], off
	v_lshl_add_u64 v[30:31], v[182:183], 0, s[0:1]
	v_fmac_f32_e32 v43, v212, v44
	global_load_dwordx4 v[130:133], v[30:31], off
	v_fmac_f32_e32 v43, v213, v45
	s_waitcnt vmcnt(5)
	v_cvt_pk_f32_fp8_e32 v[44:45], v34
	v_cvt_pk_f32_fp8_sdwa v[52:53], v34 src0_sel:WORD_1
	v_add_f32_e32 v42, v51, v43
	v_readlane_b32 s0, v227, 4
	v_mul_f32_e32 v34, v226, v45
	v_fmac_f32_e32 v34, v225, v44
	v_fmac_f32_e32 v34, v220, v52
	v_cvt_pk_f32_fp8_e32 v[44:45], v35
	v_fmac_f32_e32 v34, v223, v53
	v_add_f32_e32 v43, 0, v34
	v_cvt_pk_f32_fp8_sdwa v[34:35], v35 src0_sel:WORD_1
	v_mul_f32_e32 v45, v222, v45
	v_fmac_f32_e32 v45, v218, v44
	s_ashr_i32 s1, s0, 31
	v_fmac_f32_e32 v45, v215, v34
	v_fmac_f32_e32 v45, v217, v35
	v_cvt_pk_f32_fp8_e32 v[34:35], v36
	v_add_f32_e32 v43, v43, v45
	v_cvt_pk_f32_fp8_sdwa v[44:45], v36 src0_sel:WORD_1
	s_lshl_b64 s[0:1], s[0:1], 10
	v_mul_f32_e32 v35, v216, v35
	v_fmac_f32_e32 v35, v214, v34
	v_fmac_f32_e32 v35, v211, v44
	v_fmac_f32_e32 v35, v224, v45
	v_add_f32_e32 v43, v43, v35
	v_cvt_pk_f32_fp8_e32 v[34:35], v37
	v_cvt_pk_f32_fp8_sdwa v[36:37], v37 src0_sel:WORD_1
	v_lshl_add_u64 v[30:31], v[182:183], 0, s[0:1]
	global_load_dwordx4 v[118:121], v[30:31], off
	v_mul_f32_e32 v35, v221, v35
	v_fmac_f32_e32 v35, v219, v34
	v_cndmask_b32_e32 v34, v128, v86, vcc
	ds_bpermute_b32 v34, v205, v34
	v_fmac_f32_e32 v35, v212, v36
	v_fmac_f32_e32 v35, v213, v37
	v_add_f32_e32 v36, v43, v35
	v_cndmask_b32_e32 v35, v86, v128, vcc
	s_waitcnt lgkmcnt(0)
	v_add_f32_e32 v37, v35, v34
	s_waitcnt vmcnt(5)
	v_cvt_pk_f32_fp8_e32 v[34:35], v26
	v_readlane_b32 s0, v227, 5
	s_ashr_i32 s1, s0, 31
	s_lshl_b64 s[0:1], s[0:1], 10
	v_mul_f32_e32 v43, v226, v35
	v_fmac_f32_e32 v43, v225, v34
	v_cvt_pk_f32_fp8_sdwa v[34:35], v26 src0_sel:WORD_1
	v_lshl_add_u64 v[30:31], v[182:183], 0, s[0:1]
	global_load_dwordx4 v[110:113], v[30:31], off
	v_readlane_b32 s0, v227, 6
	v_fmac_f32_e32 v43, v220, v34
	v_fmac_f32_e32 v43, v223, v35
	v_cvt_pk_f32_fp8_e32 v[34:35], v27
	v_cvt_pk_f32_fp8_sdwa v[26:27], v27 src0_sel:WORD_1
	v_add_f32_e32 v43, 0, v43
	s_ashr_i32 s1, s0, 31
	v_mul_f32_e32 v35, v222, v35
	v_fmac_f32_e32 v35, v218, v34
	v_fmac_f32_e32 v35, v215, v26
	v_fmac_f32_e32 v35, v217, v27
	v_cvt_pk_f32_fp8_e32 v[26:27], v28
	v_add_f32_e32 v34, v43, v35
	s_lshl_b64 s[0:1], s[0:1], 10
	s_waitcnt vmcnt(4)
	v_cvt_pk_f32_fp8_sdwa v[116:117], v154 src0_sel:WORD_1
	v_mul_f32_e32 v35, v216, v27
	v_fmac_f32_e32 v35, v214, v26
	v_cvt_pk_f32_fp8_sdwa v[26:27], v28 src0_sel:WORD_1
	v_lshl_add_u64 v[30:31], v[182:183], 0, s[0:1]
	global_load_dwordx4 v[102:105], v[30:31], off
	v_readlane_b32 s0, v227, 7
	v_fmac_f32_e32 v35, v211, v26
	v_fmac_f32_e32 v35, v224, v27
	v_cvt_pk_f32_fp8_e32 v[26:27], v29
	v_add_f32_e32 v28, v34, v35
	s_ashr_i32 s1, s0, 31
	s_lshl_b64 s[0:1], s[0:1], 10
	v_mul_f32_e32 v34, v221, v27
	v_fmac_f32_e32 v34, v219, v26
	v_cvt_pk_f32_fp8_sdwa v[26:27], v29 src0_sel:WORD_1
	v_lshl_add_u64 v[30:31], v[182:183], 0, s[0:1]
	s_waitcnt vmcnt(3)
; __device__ void phase_experts(const Params& p, int l) {
;     ...
;       {
;         const int nb = (bi + 1) & 7;
;         const int idv = bi == 7 ? idn0 : (nb < 4 ? id0 : id1);
; #pragma unroll
;         for (int j = 0; j < 16; ++j) {
;           const int row = __builtin_amdgcn_readlane(idv, (nb & 3) * 16 + j);
;           rbuf[(bi + 1) & 1][j] = *(const u32x4*)(U + (size_t)row * 1024 + lane * 16);
;         }
;     ...
;       for (int j = 0; j < 16; ++j) {
;         float acc = 0.f;
; #pragma unroll
;         for (int c = 0; c < 4; ++c) {
;           const f32x2 a = __builtin_amdgcn_cvt_pk_f32_fp8((int)ru[j][c], false), b2 = __builtin_amdgcn_cvt_pk_f32_fp8((int)ru[j][c], true);
;           acc += a.x * hv[c * 4] + a.y * hv[c * 4 + 1] + b2.x * hv[c * 4 + 2] + b2.y * hv[c * 4 + 3];
;         }
;         sj[j] = acc;
;       }
; #pragma unroll
;       for (int hw = 8; hw >= 1; hw >>= 1) {
;         const bool up = (lane & hw) != 0;
; #pragma unroll
;         for (int k = 0; k < hw; ++k) {
;           const float send = up ? sj[k] : sj[k + hw], keep = up ? sj[k + hw] : sj[k];
;           sj[k] = keep + __shfl_xor(send, hw);
;         }
;       }
	v_cvt_pk_f32_fp8_sdwa v[124:125], v130 src0_sel:WORD_1
	global_load_dwordx4 v[94:97], v[30:31], off
	v_fmac_f32_e32 v34, v212, v26
	v_fmac_f32_e32 v34, v213, v27
	v_cvt_pk_f32_fp8_e32 v[26:27], v18
	v_add_f32_e32 v28, v28, v34
	v_readlane_b32 s0, v227, 8
	s_ashr_i32 s1, s0, 31
	v_mul_f32_e32 v29, v226, v27
	v_fmac_f32_e32 v29, v225, v26
	v_cvt_pk_f32_fp8_sdwa v[26:27], v18 src0_sel:WORD_1
	s_lshl_b64 s[0:1], s[0:1], 10
	v_lshl_add_u64 v[30:31], v[182:183], 0, s[0:1]
	global_load_dwordx4 v[82:85], v[30:31], off
	v_fmac_f32_e32 v29, v220, v26
	v_fmac_f32_e32 v29, v223, v27
	v_cvt_pk_f32_fp8_e32 v[26:27], v19
	v_cvt_pk_f32_fp8_sdwa v[18:19], v19 src0_sel:WORD_1
	v_add_f32_e32 v29, 0, v29
	v_readlane_b32 s0, v227, 9
	v_mul_f32_e32 v27, v222, v27
	v_fmac_f32_e32 v27, v218, v26
	v_fmac_f32_e32 v27, v215, v18
	v_fmac_f32_e32 v27, v217, v19
	v_cvt_pk_f32_fp8_e32 v[18:19], v20
	v_add_f32_e32 v26, v29, v27
	s_ashr_i32 s1, s0, 31
	s_lshl_b64 s[0:1], s[0:1], 10
	v_mul_f32_e32 v27, v216, v19
	v_fmac_f32_e32 v27, v214, v18
	v_cvt_pk_f32_fp8_sdwa v[18:19], v20 src0_sel:WORD_1
	v_lshl_add_u64 v[30:31], v[182:183], 0, s[0:1]
	v_readlane_b32 s0, v227, 10
	s_ashr_i32 s1, s0, 31
	v_fmac_f32_e32 v27, v211, v18
	v_fmac_f32_e32 v27, v224, v19
	v_cvt_pk_f32_fp8_e32 v[18:19], v21
	v_add_f32_e32 v20, v26, v27
	s_lshl_b64 s[0:1], s[0:1], 10
	v_lshl_add_u64 v[38:39], v[182:183], 0, s[0:1]
	v_mul_f32_e32 v26, v221, v19
	v_fmac_f32_e32 v26, v219, v18
	v_cvt_pk_f32_fp8_sdwa v[18:19], v21 src0_sel:WORD_1
	v_cndmask_b32_e32 v21, v66, v122, vcc
	global_load_dwordx4 v[78:81], v[38:39], off
	v_readlane_b32 s0, v227, 11
	v_fmac_f32_e32 v26, v212, v18
	v_fmac_f32_e32 v26, v213, v19
	v_add_f32_e32 v18, v20, v26
	v_cndmask_b32_e32 v19, v18, v28, vcc
	ds_bpermute_b32 v19, v205, v19
	v_cndmask_b32_e32 v18, v28, v18, vcc
	v_cndmask_b32_e32 v20, v74, v127, vcc
	v_cndmask_b32_e32 v26, v58, v114, vcc
	s_ashr_i32 s1, s0, 31
	s_waitcnt lgkmcnt(0)
	v_add_f32_e32 v18, v18, v19
	v_cndmask_b32_e32 v19, v127, v74, vcc
	ds_bpermute_b32 v19, v205, v19
	s_lshl_b64 s[0:1], s[0:1], 10
	v_lshl_add_u64 v[38:39], v[182:183], 0, s[0:1]
	global_load_dwordx4 v[70:73], v[38:39], off
	v_readlane_b32 s0, v227, 12
	s_waitcnt lgkmcnt(0)
	v_add_f32_e32 v19, v20, v19
	v_cndmask_b32_e32 v20, v122, v66, vcc
	ds_bpermute_b32 v20, v205, v20
	s_ashr_i32 s1, s0, 31
	s_lshl_b64 s[0:1], s[0:1], 10
	v_lshl_add_u64 v[38:39], v[182:183], 0, s[0:1]
	global_load_dwordx4 v[62:65], v[38:39], off
	s_waitcnt lgkmcnt(0)
	v_add_f32_e32 v20, v21, v20
	v_cndmask_b32_e32 v21, v114, v58, vcc
	v_cvt_pk_f32_fp8_e32 v[114:115], v154
	v_readlane_b32 s0, v227, 13
	s_ashr_i32 s1, s0, 31
	s_lshl_b64 s[0:1], s[0:1], 10
	v_mul_f32_e32 v115, v226, v115
	v_fmac_f32_e32 v115, v225, v114
	v_fmac_f32_e32 v115, v220, v116
	v_fmac_f32_e32 v115, v223, v117
	v_add_f32_e32 v122, 0, v115
	v_cvt_pk_f32_fp8_e32 v[114:115], v155
	v_cvt_pk_f32_fp8_sdwa v[116:117], v155 src0_sel:WORD_1
	v_lshl_add_u64 v[38:39], v[182:183], 0, s[0:1]
	global_load_dwordx4 v[54:57], v[38:39], off
	v_mul_f32_e32 v115, v222, v115
	v_fmac_f32_e32 v115, v218, v114
	v_fmac_f32_e32 v115, v215, v116
	v_fmac_f32_e32 v115, v217, v117
	v_add_f32_e32 v122, v122, v115
	v_cvt_pk_f32_fp8_e32 v[114:115], v156
	v_cvt_pk_f32_fp8_sdwa v[116:117], v156 src0_sel:WORD_1
	v_readlane_b32 s0, v227, 14
	s_ashr_i32 s1, s0, 31
	v_mul_f32_e32 v115, v216, v115
	v_fmac_f32_e32 v115, v214, v114
	v_fmac_f32_e32 v115, v211, v116
	v_fmac_f32_e32 v115, v224, v117
	v_add_f32_e32 v122, v122, v115
	v_cvt_pk_f32_fp8_e32 v[114:115], v157
	v_cvt_pk_f32_fp8_sdwa v[116:117], v157 src0_sel:WORD_1
	s_lshl_b64 s[0:1], s[0:1], 10
	v_lshl_add_u64 v[38:39], v[182:183], 0, s[0:1]
	v_mul_f32_e32 v115, v221, v115
	v_fmac_f32_e32 v115, v219, v114
	v_fmac_f32_e32 v115, v212, v116
	v_fmac_f32_e32 v115, v213, v117
	v_add_f32_e32 v117, v122, v115
	v_cvt_pk_f32_fp8_e32 v[114:115], v142
	v_cvt_pk_f32_fp8_sdwa v[122:123], v142 src0_sel:WORD_1
	global_load_dwordx4 v[46:49], v[38:39], off
	v_readlane_b32 s0, v227, 15
	v_mul_f32_e32 v115, v226, v115
	v_fmac_f32_e32 v115, v225, v114
	v_fmac_f32_e32 v115, v220, v122
	v_fmac_f32_e32 v115, v223, v123
	v_add_f32_e32 v116, 0, v115
	v_cvt_pk_f32_fp8_e32 v[114:115], v143
	v_cvt_pk_f32_fp8_sdwa v[122:123], v143 src0_sel:WORD_1
	s_ashr_i32 s1, s0, 31
	ds_bpermute_b32 v21, v205, v21
	v_mul_f32_e32 v115, v222, v115
	v_fmac_f32_e32 v115, v218, v114
	v_fmac_f32_e32 v115, v215, v122
	v_fmac_f32_e32 v115, v217, v123
	v_add_f32_e32 v116, v116, v115
	v_cvt_pk_f32_fp8_e32 v[114:115], v144
	v_cvt_pk_f32_fp8_sdwa v[122:123], v144 src0_sel:WORD_1
	s_lshl_b64 s[0:1], s[0:1], 10
	v_lshl_add_u64 v[38:39], v[182:183], 0, s[0:1]
	v_mul_f32_e32 v115, v216, v115
	v_fmac_f32_e32 v115, v214, v114
	v_fmac_f32_e32 v115, v211, v122
	v_fmac_f32_e32 v115, v224, v123
	v_add_f32_e32 v116, v116, v115
	v_cvt_pk_f32_fp8_e32 v[114:115], v145
	v_cvt_pk_f32_fp8_sdwa v[122:123], v145 src0_sel:WORD_1
	global_load_dwordx4 v[38:41], v[38:39], off
	s_waitcnt lgkmcnt(0)
	v_add_f32_e32 v21, v26, v21
	v_mul_f32_e32 v115, v221, v115
	v_fmac_f32_e32 v115, v219, v114
	v_fmac_f32_e32 v115, v212, v122
	v_fmac_f32_e32 v115, v213, v123
	v_cvt_pk_f32_fp8_e32 v[122:123], v130
	v_add_f32_e32 v114, v116, v115
	v_cndmask_b32_e32 v26, v106, v50, vcc
	ds_bpermute_b32 v26, v205, v26
	v_mul_f32_e32 v115, v226, v123
	v_fmac_f32_e32 v115, v225, v122
	v_cvt_pk_f32_fp8_e32 v[122:123], v131
	v_fmac_f32_e32 v115, v220, v124
	v_fmac_f32_e32 v115, v223, v125
	v_cvt_pk_f32_fp8_sdwa v[124:125], v131 src0_sel:WORD_1
	v_mul_f32_e32 v116, v222, v123
	v_fmac_f32_e32 v116, v218, v122
	v_cvt_pk_f32_fp8_e32 v[122:123], v132
	v_fmac_f32_e32 v116, v215, v124
	v_add_f32_e32 v115, 0, v115
	v_fmac_f32_e32 v116, v217, v125
	v_cvt_pk_f32_fp8_sdwa v[124:125], v132 src0_sel:WORD_1
	v_add_f32_e32 v115, v115, v116
	v_mul_f32_e32 v116, v216, v123
	v_fmac_f32_e32 v116, v214, v122
	v_cvt_pk_f32_fp8_e32 v[122:123], v133
	v_fmac_f32_e32 v116, v211, v124
	v_fmac_f32_e32 v116, v224, v125
	v_cvt_pk_f32_fp8_sdwa v[124:125], v133 src0_sel:WORD_1
	v_add_f32_e32 v115, v115, v116
	v_mul_f32_e32 v116, v221, v123
	v_fmac_f32_e32 v116, v219, v122
	s_waitcnt vmcnt(10)
; __device__ void phase_experts(const Params& p, int l) {
;     ...
;       for (int j = 0; j < 16; ++j) {
;         float acc = 0.f;
; #pragma unroll
;         for (int c = 0; c < 4; ++c) {
;           const f32x2 a = __builtin_amdgcn_cvt_pk_f32_fp8((int)ru[j][c], false), b2 = __builtin_amdgcn_cvt_pk_f32_fp8((int)ru[j][c], true);
;           acc += a.x * hv[c * 4] + a.y * hv[c * 4 + 1] + b2.x * hv[c * 4 + 2] + b2.y * hv[c * 4 + 3];
;         }
;         sj[j] = acc;
;       }
; #pragma unroll
;       for (int hw = 8; hw >= 1; hw >>= 1) {
;         const bool up = (lane & hw) != 0;
; #pragma unroll
;         for (int k = 0; k < hw; ++k) {
;           const float send = up ? sj[k] : sj[k + hw], keep = up ? sj[k + hw] : sj[k];
;           sj[k] = keep + __shfl_xor(send, hw);
;         }
;       }
	v_cvt_pk_f32_fp8_e32 v[122:123], v118
	v_fmac_f32_e32 v116, v212, v124
	v_fmac_f32_e32 v116, v213, v125
	v_add_f32_e32 v115, v115, v116
	v_mul_f32_e32 v116, v226, v123
	v_fmac_f32_e32 v116, v225, v122
	v_cvt_pk_f32_fp8_e32 v[122:123], v119
	v_cvt_pk_f32_fp8_sdwa v[124:125], v118 src0_sel:WORD_1
	v_cvt_pk_f32_fp8_sdwa v[118:119], v119 src0_sel:WORD_1
	v_cndmask_b32_e32 v27, v50, v106, vcc
	v_mul_f32_e32 v123, v222, v123
	v_fmac_f32_e32 v123, v218, v122
	v_fmac_f32_e32 v116, v220, v124
	v_fmac_f32_e32 v123, v215, v118
	v_fmac_f32_e32 v116, v223, v125
	v_fmac_f32_e32 v123, v217, v119
	v_cvt_pk_f32_fp8_e32 v[118:119], v120
	v_add_f32_e32 v116, 0, v116
	v_add_f32_e32 v116, v116, v123
	v_cvt_pk_f32_fp8_sdwa v[122:123], v120 src0_sel:WORD_1
	v_mul_f32_e32 v119, v216, v119
	v_fmac_f32_e32 v119, v214, v118
	s_waitcnt lgkmcnt(0)
	v_add_f32_e32 v26, v27, v26
	v_fmac_f32_e32 v119, v211, v122
	v_fmac_f32_e32 v119, v224, v123
	v_add_f32_e32 v116, v116, v119
	v_cvt_pk_f32_fp8_e32 v[118:119], v121
	v_cvt_pk_f32_fp8_sdwa v[120:121], v121 src0_sel:WORD_1
	v_cndmask_b32_e32 v27, v98, v42, vcc
	ds_bpermute_b32 v27, v205, v27
	v_mul_f32_e32 v119, v221, v119
	v_fmac_f32_e32 v119, v219, v118
	v_fmac_f32_e32 v119, v212, v120
	v_fmac_f32_e32 v119, v213, v121
	v_add_f32_e32 v116, v116, v119
	s_waitcnt vmcnt(9)
	v_cvt_pk_f32_fp8_e32 v[118:119], v110
	v_cvt_pk_f32_fp8_sdwa v[120:121], v110 src0_sel:WORD_1
	v_cndmask_b32_e32 v28, v42, v98, vcc
	s_waitcnt lgkmcnt(0)
	v_add_f32_e32 v27, v28, v27
	v_mul_f32_e32 v110, v226, v119
	v_fmac_f32_e32 v110, v225, v118
	v_fmac_f32_e32 v110, v220, v120
	v_cvt_pk_f32_fp8_e32 v[118:119], v111
	v_fmac_f32_e32 v110, v223, v121
	v_add_f32_e32 v120, 0, v110
	v_cvt_pk_f32_fp8_sdwa v[110:111], v111 src0_sel:WORD_1
	v_mul_f32_e32 v119, v222, v119
	v_fmac_f32_e32 v119, v218, v118
	v_cndmask_b32_e32 v28, v90, v36, vcc
	v_fmac_f32_e32 v119, v215, v110
	v_fmac_f32_e32 v119, v217, v111
	v_cvt_pk_f32_fp8_e32 v[110:111], v112
	v_add_f32_e32 v120, v120, v119
	v_cvt_pk_f32_fp8_sdwa v[118:119], v112 src0_sel:WORD_1
	ds_bpermute_b32 v28, v205, v28
	v_mul_f32_e32 v111, v216, v111
	v_fmac_f32_e32 v111, v214, v110
	v_fmac_f32_e32 v111, v211, v118
	v_fmac_f32_e32 v111, v224, v119
	v_add_f32_e32 v118, v120, v111
	v_cvt_pk_f32_fp8_e32 v[110:111], v113
	v_cvt_pk_f32_fp8_sdwa v[112:113], v113 src0_sel:WORD_1
	v_cndmask_b32_e32 v29, v36, v90, vcc
	s_waitcnt lgkmcnt(0)
	v_add_f32_e32 v28, v29, v28
	v_mul_f32_e32 v111, v221, v111
	v_fmac_f32_e32 v111, v219, v110
	v_fmac_f32_e32 v111, v212, v112
	v_fmac_f32_e32 v111, v213, v113
	s_waitcnt vmcnt(8)
	v_cvt_pk_f32_fp8_e32 v[112:113], v102
	v_add_f32_e32 v110, v118, v111
	v_cvt_pk_f32_fp8_sdwa v[118:119], v102 src0_sel:WORD_1
	v_cndmask_b32_e64 v29, v37, v21, s[4:5]
	v_mul_f32_e32 v102, v226, v113
	v_fmac_f32_e32 v102, v225, v112
	v_fmac_f32_e32 v102, v220, v118
	v_cvt_pk_f32_fp8_e32 v[112:113], v103
	v_fmac_f32_e32 v102, v223, v119
	v_add_f32_e32 v111, 0, v102
	v_cvt_pk_f32_fp8_sdwa v[102:103], v103 src0_sel:WORD_1
	v_mul_f32_e32 v113, v222, v113
	v_fmac_f32_e32 v113, v218, v112
	ds_bpermute_b32 v29, v206, v29
	v_fmac_f32_e32 v113, v215, v102
	v_fmac_f32_e32 v113, v217, v103
	v_cvt_pk_f32_fp8_e32 v[102:103], v104
	v_add_f32_e32 v111, v111, v113
	v_cvt_pk_f32_fp8_sdwa v[112:113], v104 src0_sel:WORD_1
	v_cndmask_b32_e64 v21, v21, v37, s[4:5]
	v_mul_f32_e32 v103, v216, v103
	v_fmac_f32_e32 v103, v214, v102
	v_fmac_f32_e32 v103, v211, v112
	v_fmac_f32_e32 v103, v224, v113
	v_add_f32_e32 v111, v111, v103
	v_cvt_pk_f32_fp8_e32 v[102:103], v105
	v_cvt_pk_f32_fp8_sdwa v[104:105], v105 src0_sel:WORD_1
	s_waitcnt vmcnt(7)
	v_cvt_pk_f32_fp8_sdwa v[112:113], v94 src0_sel:WORD_1
	s_waitcnt lgkmcnt(0)
	v_add_f32_e32 v21, v21, v29
	v_mul_f32_e32 v103, v221, v103
	v_fmac_f32_e32 v103, v219, v102
	v_fmac_f32_e32 v103, v212, v104
	v_fmac_f32_e32 v103, v213, v105
	v_cvt_pk_f32_fp8_e32 v[104:105], v94
	v_add_f32_e32 v102, v111, v103
	v_cndmask_b32_e64 v29, v18, v26, s[4:5]
	v_cndmask_b32_e64 v18, v26, v18, s[4:5]
	v_mul_f32_e32 v94, v226, v105
	v_fmac_f32_e32 v94, v225, v104
	v_fmac_f32_e32 v94, v220, v112
	v_cvt_pk_f32_fp8_e32 v[104:105], v95
	v_fmac_f32_e32 v94, v223, v113
	v_add_f32_e32 v103, 0, v94
	v_cvt_pk_f32_fp8_sdwa v[94:95], v95 src0_sel:WORD_1
	v_mul_f32_e32 v105, v222, v105
	v_fmac_f32_e32 v105, v218, v104
	ds_bpermute_b32 v26, v206, v29
	v_fmac_f32_e32 v105, v215, v94
	v_fmac_f32_e32 v105, v217, v95
	v_cvt_pk_f32_fp8_e32 v[94:95], v96
	v_add_f32_e32 v103, v103, v105
	v_cvt_pk_f32_fp8_sdwa v[104:105], v96 src0_sel:WORD_1
	global_load_dwordx4 v[30:33], v[30:31], off
	v_mul_f32_e32 v95, v216, v95
	v_fmac_f32_e32 v95, v214, v94
	v_fmac_f32_e32 v95, v211, v104
	v_fmac_f32_e32 v95, v224, v105
	v_add_f32_e32 v103, v103, v95
	v_cvt_pk_f32_fp8_e32 v[94:95], v97
	v_cvt_pk_f32_fp8_sdwa v[96:97], v97 src0_sel:WORD_1
	s_waitcnt vmcnt(7)
	v_cvt_pk_f32_fp8_sdwa v[104:105], v82 src0_sel:WORD_1
	s_waitcnt lgkmcnt(0)
	v_add_f32_e32 v18, v18, v26
	v_mul_f32_e32 v95, v221, v95
	v_fmac_f32_e32 v95, v219, v94
	v_fmac_f32_e32 v95, v212, v96
	v_fmac_f32_e32 v95, v213, v97
	v_cvt_pk_f32_fp8_e32 v[96:97], v82
	v_add_f32_e32 v94, v103, v95
	v_cndmask_b32_e64 v26, v19, v27, s[4:5]
	ds_bpermute_b32 v26, v206, v26
	v_mul_f32_e32 v82, v226, v97
	v_fmac_f32_e32 v82, v225, v96
	v_fmac_f32_e32 v82, v220, v104
	v_cvt_pk_f32_fp8_e32 v[96:97], v83
	v_fmac_f32_e32 v82, v223, v105
	v_add_f32_e32 v95, 0, v82
	v_cvt_pk_f32_fp8_sdwa v[82:83], v83 src0_sel:WORD_1
	v_mul_f32_e32 v97, v222, v97
	v_fmac_f32_e32 v97, v218, v96
	v_cndmask_b32_e64 v19, v27, v19, s[4:5]
	v_fmac_f32_e32 v97, v215, v82
	v_fmac_f32_e32 v97, v217, v83
	v_cvt_pk_f32_fp8_e32 v[82:83], v84
	v_add_f32_e32 v95, v95, v97
	v_cvt_pk_f32_fp8_sdwa v[96:97], v84 src0_sel:WORD_1
	s_waitcnt lgkmcnt(0)
; __device__ void phase_experts(const Params& p, int l) {
;     ...
;       for (int j = 0; j < 16; ++j) {
;         float acc = 0.f;
; #pragma unroll
;         for (int c = 0; c < 4; ++c) {
;           const f32x2 a = __builtin_amdgcn_cvt_pk_f32_fp8((int)ru[j][c], false), b2 = __builtin_amdgcn_cvt_pk_f32_fp8((int)ru[j][c], true);
;           acc += a.x * hv[c * 4] + a.y * hv[c * 4 + 1] + b2.x * hv[c * 4 + 2] + b2.y * hv[c * 4 + 3];
;         }
;         sj[j] = acc;
;       }
; #pragma unroll
;       for (int hw = 8; hw >= 1; hw >>= 1) {
;         const bool up = (lane & hw) != 0;
; #pragma unroll
;         for (int k = 0; k < hw; ++k) {
;           const float send = up ? sj[k] : sj[k + hw], keep = up ? sj[k + hw] : sj[k];
;           sj[k] = keep + __shfl_xor(send, hw);
;         }
;       }
;       float tot = sj[0];
;       tot = xsum_rows(tot);
;       if ((lane >> 4) == (bi & 3)) { if (bi < 4) d0 = tot; else d1 = tot; }
	v_add_f32_e32 v19, v19, v26
	v_mul_f32_e32 v83, v216, v83
	v_fmac_f32_e32 v83, v214, v82
	v_fmac_f32_e32 v83, v211, v96
	v_fmac_f32_e32 v83, v224, v97
	v_add_f32_e32 v95, v95, v83
	v_cvt_pk_f32_fp8_e32 v[82:83], v85
	v_cvt_pk_f32_fp8_sdwa v[84:85], v85 src0_sel:WORD_1
	s_waitcnt vmcnt(6)
	v_cvt_pk_f32_fp8_sdwa v[96:97], v78 src0_sel:WORD_1
	v_cndmask_b32_e64 v26, v20, v28, s[4:5]
	v_mul_f32_e32 v83, v221, v83
	v_fmac_f32_e32 v83, v219, v82
	v_fmac_f32_e32 v83, v212, v84
	v_fmac_f32_e32 v83, v213, v85
	v_cvt_pk_f32_fp8_e32 v[84:85], v78
	v_add_f32_e32 v82, v95, v83
	ds_bpermute_b32 v26, v206, v26
	v_cndmask_b32_e64 v20, v28, v20, s[4:5]
	v_mul_f32_e32 v78, v226, v85
	v_fmac_f32_e32 v78, v225, v84
	v_fmac_f32_e32 v78, v220, v96
	v_cvt_pk_f32_fp8_e32 v[84:85], v79
	v_fmac_f32_e32 v78, v223, v97
	v_add_f32_e32 v83, 0, v78
	v_cvt_pk_f32_fp8_sdwa v[78:79], v79 src0_sel:WORD_1
	v_mul_f32_e32 v85, v222, v85
	v_fmac_f32_e32 v85, v218, v84
	s_waitcnt lgkmcnt(0)
	v_add_f32_e32 v20, v20, v26
	v_fmac_f32_e32 v85, v215, v78
	v_fmac_f32_e32 v85, v217, v79
	v_cvt_pk_f32_fp8_e32 v[78:79], v80
	v_add_f32_e32 v83, v83, v85
	v_cvt_pk_f32_fp8_sdwa v[84:85], v80 src0_sel:WORD_1
	v_cndmask_b32_e64 v26, v21, v19, s[6:7]
	v_mul_f32_e32 v79, v216, v79
	v_fmac_f32_e32 v79, v214, v78
	v_fmac_f32_e32 v79, v211, v84
	v_fmac_f32_e32 v79, v224, v85
	v_add_f32_e32 v83, v83, v79
	v_cvt_pk_f32_fp8_e32 v[78:79], v81
	v_cvt_pk_f32_fp8_sdwa v[80:81], v81 src0_sel:WORD_1
	s_waitcnt vmcnt(5)
	v_cvt_pk_f32_fp8_sdwa v[84:85], v70 src0_sel:WORD_1
	v_cndmask_b32_e64 v19, v19, v21, s[6:7]
	v_mul_f32_e32 v79, v221, v79
	v_fmac_f32_e32 v79, v219, v78
	v_fmac_f32_e32 v79, v212, v80
	v_fmac_f32_e32 v79, v213, v81
	v_cvt_pk_f32_fp8_e32 v[80:81], v70
	v_add_f32_e32 v78, v83, v79
	ds_bpermute_b32 v21, v207, v26
	v_readlane_b32 s0, v227, 16
	v_mul_f32_e32 v70, v226, v81
	v_fmac_f32_e32 v70, v225, v80
	v_fmac_f32_e32 v70, v220, v84
	v_cvt_pk_f32_fp8_e32 v[80:81], v71
	v_fmac_f32_e32 v70, v223, v85
	v_add_f32_e32 v79, 0, v70
	v_cvt_pk_f32_fp8_sdwa v[70:71], v71 src0_sel:WORD_1
	v_mul_f32_e32 v81, v222, v81
	v_fmac_f32_e32 v81, v218, v80
	s_waitcnt lgkmcnt(0)
	v_add_f32_e32 v19, v19, v21
	v_fmac_f32_e32 v81, v215, v70
	v_fmac_f32_e32 v81, v217, v71
	v_cvt_pk_f32_fp8_e32 v[70:71], v72
	v_add_f32_e32 v79, v79, v81
	v_cvt_pk_f32_fp8_sdwa v[80:81], v72 src0_sel:WORD_1
	v_cndmask_b32_e64 v21, v18, v20, s[6:7]
	v_mul_f32_e32 v71, v216, v71
	v_fmac_f32_e32 v71, v214, v70
	v_fmac_f32_e32 v71, v211, v80
	v_fmac_f32_e32 v71, v224, v81
	v_add_f32_e32 v79, v79, v71
	v_cvt_pk_f32_fp8_e32 v[70:71], v73
	v_cvt_pk_f32_fp8_sdwa v[72:73], v73 src0_sel:WORD_1
	s_waitcnt vmcnt(4)
	v_cvt_pk_f32_fp8_sdwa v[80:81], v62 src0_sel:WORD_1
	ds_bpermute_b32 v21, v207, v21
	v_mul_f32_e32 v71, v221, v71
	v_fmac_f32_e32 v71, v219, v70
	v_fmac_f32_e32 v71, v212, v72
	v_fmac_f32_e32 v71, v213, v73
	v_cvt_pk_f32_fp8_e32 v[72:73], v62
	v_add_f32_e32 v70, v79, v71
	v_cndmask_b32_e64 v18, v20, v18, s[6:7]
	s_waitcnt lgkmcnt(0)
	v_add_f32_e32 v18, v18, v21
	v_mul_f32_e32 v62, v226, v73
	v_fmac_f32_e32 v62, v225, v72
	v_fmac_f32_e32 v62, v220, v80
	v_cvt_pk_f32_fp8_e32 v[72:73], v63
	v_fmac_f32_e32 v62, v223, v81
	v_add_f32_e32 v71, 0, v62
	v_cvt_pk_f32_fp8_sdwa v[62:63], v63 src0_sel:WORD_1
	v_mul_f32_e32 v73, v222, v73
	v_fmac_f32_e32 v73, v218, v72
	v_cndmask_b32_e64 v20, v19, v18, s[8:9]
	v_fmac_f32_e32 v73, v215, v62
	v_fmac_f32_e32 v73, v217, v63
	v_cvt_pk_f32_fp8_e32 v[62:63], v64
	v_add_f32_e32 v71, v71, v73
	v_cvt_pk_f32_fp8_sdwa v[72:73], v64 src0_sel:WORD_1
	v_cndmask_b32_e64 v18, v18, v19, s[8:9]
	v_mul_f32_e32 v63, v216, v63
	v_fmac_f32_e32 v63, v214, v62
	v_fmac_f32_e32 v63, v211, v72
	v_fmac_f32_e32 v63, v224, v73
	v_add_f32_e32 v71, v71, v63
	v_cvt_pk_f32_fp8_e32 v[62:63], v65
	v_cvt_pk_f32_fp8_sdwa v[64:65], v65 src0_sel:WORD_1
	s_waitcnt vmcnt(3)
	v_cvt_pk_f32_fp8_sdwa v[72:73], v54 src0_sel:WORD_1
	ds_bpermute_b32 v19, v208, v20
	v_mul_f32_e32 v63, v221, v63
	v_fmac_f32_e32 v63, v219, v62
	v_fmac_f32_e32 v63, v212, v64
	v_fmac_f32_e32 v63, v213, v65
	v_cvt_pk_f32_fp8_e32 v[64:65], v54
	v_add_f32_e32 v62, v71, v63
	s_waitcnt lgkmcnt(0)
	v_add_f32_e32 v18, v18, v19
	v_mov_b32_e32 v19, v18
	v_mul_f32_e32 v54, v226, v65
	v_fmac_f32_e32 v54, v225, v64
	v_fmac_f32_e32 v54, v220, v72
	v_cvt_pk_f32_fp8_e32 v[64:65], v55
	v_fmac_f32_e32 v54, v223, v73
	v_add_f32_e32 v63, 0, v54
	v_cvt_pk_f32_fp8_sdwa v[54:55], v55 src0_sel:WORD_1
	v_mul_f32_e32 v65, v222, v65
	v_fmac_f32_e32 v65, v218, v64
	v_permlane16_swap_b32_e32 v18, v19
	v_fmac_f32_e32 v65, v215, v54
	v_fmac_f32_e32 v65, v217, v55
	v_cvt_pk_f32_fp8_e32 v[54:55], v56
	v_add_f32_e32 v63, v63, v65
	v_cvt_pk_f32_fp8_sdwa v[64:65], v56 src0_sel:WORD_1
	v_add_f32_e32 v18, v18, v19
	v_mul_f32_e32 v55, v216, v55
	v_fmac_f32_e32 v55, v214, v54
	v_fmac_f32_e32 v55, v211, v64
	v_fmac_f32_e32 v55, v224, v65
	v_add_f32_e32 v63, v63, v55
	v_cvt_pk_f32_fp8_e32 v[54:55], v57
	v_cvt_pk_f32_fp8_sdwa v[56:57], v57 src0_sel:WORD_1
	s_waitcnt vmcnt(2)
; __device__ void phase_experts(const Params& p, int l) {
;     ...
;       {
;         const int nb = (bi + 1) & 7;
;         const int idv = bi == 7 ? idn0 : (nb < 4 ? id0 : id1);
; #pragma unroll
;         for (int j = 0; j < 16; ++j) {
;           const int row = __builtin_amdgcn_readlane(idv, (nb & 3) * 16 + j);
;           rbuf[(bi + 1) & 1][j] = *(const u32x4*)(U + (size_t)row * 1024 + lane * 16);
;         }
;     ...
;       float tot = sj[0];
;       tot = xsum_rows(tot);
;       if ((lane >> 4) == (bi & 3)) { if (bi < 4) d0 = tot; else d1 = tot; }
	v_cvt_pk_f32_fp8_sdwa v[64:65], v46 src0_sel:WORD_1
	v_mov_b32_e32 v19, v18
	v_mul_f32_e32 v55, v221, v55
	v_fmac_f32_e32 v55, v219, v54
	v_fmac_f32_e32 v55, v212, v56
	v_fmac_f32_e32 v55, v213, v57
	v_cvt_pk_f32_fp8_e32 v[56:57], v46
	v_add_f32_e32 v54, v63, v55
	v_permlane32_swap_b32_e32 v18, v19
	v_mul_f32_e32 v46, v226, v57
	v_fmac_f32_e32 v46, v225, v56
	v_fmac_f32_e32 v46, v220, v64
	v_cvt_pk_f32_fp8_e32 v[56:57], v47
	v_fmac_f32_e32 v46, v223, v65
	v_add_f32_e32 v55, 0, v46
	v_cvt_pk_f32_fp8_sdwa v[46:47], v47 src0_sel:WORD_1
	v_mul_f32_e32 v57, v222, v57
	v_fmac_f32_e32 v57, v218, v56
	s_ashr_i32 s1, s0, 31
	v_fmac_f32_e32 v57, v215, v46
	v_fmac_f32_e32 v57, v217, v47
	v_cvt_pk_f32_fp8_e32 v[46:47], v48
	v_add_f32_e32 v55, v55, v57
	v_cvt_pk_f32_fp8_sdwa v[56:57], v48 src0_sel:WORD_1
	global_load_dwordx4 v[22:25], v[22:23], off
	v_add_f32_e32 v18, v18, v19
	s_lshl_b64 s[0:1], s[0:1], 10
	v_mul_f32_e32 v47, v216, v47
	v_cndmask_b32_e64 v228, v126, v18, s[16:17]
	v_lshl_add_u64 v[18:19], v[182:183], 0, s[0:1]
	v_readlane_b32 s0, v227, 17
	v_fmac_f32_e32 v47, v214, v46
	s_ashr_i32 s1, s0, 31
	v_fmac_f32_e32 v47, v211, v56
	s_lshl_b64 s[0:1], s[0:1], 10
	v_fmac_f32_e32 v47, v224, v57
	global_load_dwordx4 v[158:161], v[18:19], off
	v_lshl_add_u64 v[18:19], v[182:183], 0, s[0:1]
	v_readlane_b32 s0, v227, 18
	v_add_f32_e32 v55, v55, v47
	v_cvt_pk_f32_fp8_e32 v[46:47], v49
	s_ashr_i32 s1, s0, 31
	s_lshl_b64 s[0:1], s[0:1], 10
	v_cvt_pk_f32_fp8_sdwa v[48:49], v49 src0_sel:WORD_1
	v_lshl_add_u64 v[26:27], v[182:183], 0, s[0:1]
	v_readlane_b32 s0, v227, 19
	s_ashr_i32 s1, s0, 31
	v_mul_f32_e32 v47, v221, v47
	s_lshl_b64 s[0:1], s[0:1], 10
	v_fmac_f32_e32 v47, v219, v46
	global_load_dwordx4 v[150:153], v[26:27], off
	v_lshl_add_u64 v[26:27], v[182:183], 0, s[0:1]
	v_fmac_f32_e32 v47, v212, v48
	global_load_dwordx4 v[134:137], v[26:27], off
	v_fmac_f32_e32 v47, v213, v49
	s_waitcnt vmcnt(5)
	v_cvt_pk_f32_fp8_e32 v[48:49], v38
	v_cvt_pk_f32_fp8_sdwa v[56:57], v38 src0_sel:WORD_1
	v_add_f32_e32 v46, v55, v47
	v_readlane_b32 s0, v227, 20
	v_mul_f32_e32 v38, v226, v49
	v_fmac_f32_e32 v38, v225, v48
	v_fmac_f32_e32 v38, v220, v56
	v_cvt_pk_f32_fp8_e32 v[48:49], v39
	v_fmac_f32_e32 v38, v223, v57
	v_add_f32_e32 v47, 0, v38
	v_cvt_pk_f32_fp8_sdwa v[38:39], v39 src0_sel:WORD_1
	v_mul_f32_e32 v49, v222, v49
	v_fmac_f32_e32 v49, v218, v48
	s_ashr_i32 s1, s0, 31
	v_fmac_f32_e32 v49, v215, v38
	v_fmac_f32_e32 v49, v217, v39
	v_cvt_pk_f32_fp8_e32 v[38:39], v40
	v_add_f32_e32 v47, v47, v49
	v_cvt_pk_f32_fp8_sdwa v[48:49], v40 src0_sel:WORD_1
	s_lshl_b64 s[0:1], s[0:1], 10
	v_mul_f32_e32 v39, v216, v39
	v_fmac_f32_e32 v39, v214, v38
	v_fmac_f32_e32 v39, v211, v48
	v_fmac_f32_e32 v39, v224, v49
	v_add_f32_e32 v47, v47, v39
	v_cvt_pk_f32_fp8_e32 v[38:39], v41
	v_cvt_pk_f32_fp8_sdwa v[40:41], v41 src0_sel:WORD_1
	v_lshl_add_u64 v[26:27], v[182:183], 0, s[0:1]
	global_load_dwordx4 v[126:129], v[26:27], off
	v_mul_f32_e32 v39, v221, v39
	v_fmac_f32_e32 v39, v219, v38
	v_cndmask_b32_e32 v38, v117, v82, vcc
	ds_bpermute_b32 v38, v205, v38
	v_fmac_f32_e32 v39, v212, v40
	v_fmac_f32_e32 v39, v213, v41
	v_add_f32_e32 v40, v47, v39
	v_cndmask_b32_e32 v39, v82, v117, vcc
	s_waitcnt lgkmcnt(0)
	v_add_f32_e32 v41, v39, v38
	s_waitcnt vmcnt(5)
	v_cvt_pk_f32_fp8_e32 v[38:39], v30
	v_readlane_b32 s0, v227, 21
	s_ashr_i32 s1, s0, 31
	s_lshl_b64 s[0:1], s[0:1], 10
	v_mul_f32_e32 v47, v226, v39
	v_fmac_f32_e32 v47, v225, v38
	v_cvt_pk_f32_fp8_sdwa v[38:39], v30 src0_sel:WORD_1
	v_lshl_add_u64 v[26:27], v[182:183], 0, s[0:1]
	global_load_dwordx4 v[106:109], v[26:27], off
	v_readlane_b32 s0, v227, 22
	v_fmac_f32_e32 v47, v220, v38
	v_fmac_f32_e32 v47, v223, v39
	v_cvt_pk_f32_fp8_e32 v[38:39], v31
	v_cvt_pk_f32_fp8_sdwa v[30:31], v31 src0_sel:WORD_1
	v_add_f32_e32 v47, 0, v47
	s_ashr_i32 s1, s0, 31
	v_mul_f32_e32 v39, v222, v39
	v_fmac_f32_e32 v39, v218, v38
	v_fmac_f32_e32 v39, v215, v30
	v_fmac_f32_e32 v39, v217, v31
	v_cvt_pk_f32_fp8_e32 v[30:31], v32
	v_add_f32_e32 v38, v47, v39
	s_lshl_b64 s[0:1], s[0:1], 10
	s_waitcnt vmcnt(4)
	v_cvt_pk_f32_fp8_sdwa v[80:81], v158 src0_sel:WORD_1
	v_mul_f32_e32 v39, v216, v31
	v_fmac_f32_e32 v39, v214, v30
	v_cvt_pk_f32_fp8_sdwa v[30:31], v32 src0_sel:WORD_1
	v_lshl_add_u64 v[26:27], v[182:183], 0, s[0:1]
	global_load_dwordx4 v[98:101], v[26:27], off
	v_readlane_b32 s0, v227, 23
	v_fmac_f32_e32 v39, v211, v30
	v_fmac_f32_e32 v39, v224, v31
	v_cvt_pk_f32_fp8_e32 v[30:31], v33
	v_add_f32_e32 v32, v38, v39
	s_ashr_i32 s1, s0, 31
	s_lshl_b64 s[0:1], s[0:1], 10
	v_mul_f32_e32 v38, v221, v31
	v_fmac_f32_e32 v38, v219, v30
	v_cvt_pk_f32_fp8_sdwa v[30:31], v33 src0_sel:WORD_1
	v_lshl_add_u64 v[26:27], v[182:183], 0, s[0:1]
	s_waitcnt vmcnt(3)
; __device__ void phase_experts(const Params& p, int l) {
;     ...
;       {
;         const int nb = (bi + 1) & 7;
;         const int idv = bi == 7 ? idn0 : (nb < 4 ? id0 : id1);
; #pragma unroll
;         for (int j = 0; j < 16; ++j) {
;           const int row = __builtin_amdgcn_readlane(idv, (nb & 3) * 16 + j);
;           rbuf[(bi + 1) & 1][j] = *(const u32x4*)(U + (size_t)row * 1024 + lane * 16);
;         }
;     ...
;       for (int j = 0; j < 16; ++j) {
;         float acc = 0.f;
; #pragma unroll
;         for (int c = 0; c < 4; ++c) {
;           const f32x2 a = __builtin_amdgcn_cvt_pk_f32_fp8((int)ru[j][c], false), b2 = __builtin_amdgcn_cvt_pk_f32_fp8((int)ru[j][c], true);
;           acc += a.x * hv[c * 4] + a.y * hv[c * 4 + 1] + b2.x * hv[c * 4 + 2] + b2.y * hv[c * 4 + 3];
;         }
;         sj[j] = acc;
;       }
; #pragma unroll
;       for (int hw = 8; hw >= 1; hw >>= 1) {
;         const bool up = (lane & hw) != 0;
; #pragma unroll
;         for (int k = 0; k < hw; ++k) {
;           const float send = up ? sj[k] : sj[k + hw], keep = up ? sj[k + hw] : sj[k];
;           sj[k] = keep + __shfl_xor(send, hw);
;         }
;       }
	v_cvt_pk_f32_fp8_sdwa v[96:97], v134 src0_sel:WORD_1
	global_load_dwordx4 v[90:93], v[26:27], off
	v_fmac_f32_e32 v38, v212, v30
	v_fmac_f32_e32 v38, v213, v31
	v_cvt_pk_f32_fp8_e32 v[30:31], v22
	v_add_f32_e32 v32, v32, v38
	v_readlane_b32 s0, v227, 24
	s_ashr_i32 s1, s0, 31
	v_mul_f32_e32 v33, v226, v31
	v_fmac_f32_e32 v33, v225, v30
	v_cvt_pk_f32_fp8_sdwa v[30:31], v22 src0_sel:WORD_1
	s_lshl_b64 s[0:1], s[0:1], 10
	v_lshl_add_u64 v[26:27], v[182:183], 0, s[0:1]
	global_load_dwordx4 v[86:89], v[26:27], off
	v_fmac_f32_e32 v33, v220, v30
	v_fmac_f32_e32 v33, v223, v31
	v_cvt_pk_f32_fp8_e32 v[30:31], v23
	v_cvt_pk_f32_fp8_sdwa v[22:23], v23 src0_sel:WORD_1
	v_add_f32_e32 v33, 0, v33
	v_readlane_b32 s0, v227, 25
	v_mul_f32_e32 v31, v222, v31
	v_fmac_f32_e32 v31, v218, v30
	v_fmac_f32_e32 v31, v215, v22
	v_fmac_f32_e32 v31, v217, v23
	v_cvt_pk_f32_fp8_e32 v[22:23], v24
	v_add_f32_e32 v30, v33, v31
	v_cndmask_b32_e32 v33, v40, v94, vcc
	s_ashr_i32 s1, s0, 31
	v_mul_f32_e32 v31, v216, v23
	v_fmac_f32_e32 v31, v214, v22
	v_cvt_pk_f32_fp8_sdwa v[22:23], v24 src0_sel:WORD_1
	s_lshl_b64 s[0:1], s[0:1], 10
	v_lshl_add_u64 v[26:27], v[182:183], 0, s[0:1]
	v_readlane_b32 s0, v227, 26
	v_fmac_f32_e32 v31, v211, v22
	v_fmac_f32_e32 v31, v224, v23
	v_cvt_pk_f32_fp8_e32 v[22:23], v25
	v_add_f32_e32 v24, v30, v31
	v_cndmask_b32_e32 v31, v54, v110, vcc
	s_ashr_i32 s1, s0, 31
	v_mul_f32_e32 v30, v221, v23
	v_fmac_f32_e32 v30, v219, v22
	v_cvt_pk_f32_fp8_sdwa v[22:23], v25 src0_sel:WORD_1
	v_cndmask_b32_e32 v25, v70, v115, vcc
	s_lshl_b64 s[0:1], s[0:1], 10
	v_lshl_add_u64 v[34:35], v[182:183], 0, s[0:1]
	v_fmac_f32_e32 v30, v212, v22
	v_fmac_f32_e32 v30, v213, v23
	v_add_f32_e32 v22, v24, v30
	v_cndmask_b32_e32 v23, v22, v32, vcc
	ds_bpermute_b32 v23, v205, v23
	v_cndmask_b32_e32 v22, v32, v22, vcc
	v_cndmask_b32_e32 v24, v78, v114, vcc
	v_cndmask_b32_e32 v30, v62, v116, vcc
	v_cndmask_b32_e32 v32, v46, v102, vcc
	s_waitcnt lgkmcnt(0)
	v_add_f32_e32 v22, v22, v23
	v_cndmask_b32_e32 v23, v114, v78, vcc
	ds_bpermute_b32 v23, v205, v23
	v_cvt_pk_f32_fp8_e32 v[78:79], v158
	global_load_dwordx4 v[74:77], v[34:35], off
	v_readlane_b32 s0, v227, 27
	s_ashr_i32 s1, s0, 31
	s_waitcnt lgkmcnt(0)
	v_add_f32_e32 v23, v24, v23
	v_cndmask_b32_e32 v24, v115, v70, vcc
	ds_bpermute_b32 v24, v205, v24
	v_mul_f32_e32 v79, v226, v79
	v_fmac_f32_e32 v79, v225, v78
	v_fmac_f32_e32 v79, v220, v80
	v_fmac_f32_e32 v79, v223, v81
	s_waitcnt lgkmcnt(0)
	v_add_f32_e32 v24, v25, v24
	v_cndmask_b32_e32 v25, v116, v62, vcc
	ds_bpermute_b32 v25, v205, v25
	v_cvt_pk_f32_fp8_sdwa v[80:81], v159 src0_sel:WORD_1
	s_lshl_b64 s[0:1], s[0:1], 10
	v_lshl_add_u64 v[34:35], v[182:183], 0, s[0:1]
	global_load_dwordx4 v[66:69], v[34:35], off
	s_waitcnt lgkmcnt(0)
	v_add_f32_e32 v25, v30, v25
	v_cndmask_b32_e32 v30, v110, v54, vcc
	ds_bpermute_b32 v30, v205, v30
	v_readlane_b32 s0, v227, 28
	s_ashr_i32 s1, s0, 31
	s_lshl_b64 s[0:1], s[0:1], 10
	v_lshl_add_u64 v[34:35], v[182:183], 0, s[0:1]
	s_waitcnt lgkmcnt(0)
	v_add_f32_e32 v30, v31, v30
	v_cndmask_b32_e32 v31, v102, v46, vcc
	ds_bpermute_b32 v31, v205, v31
	global_load_dwordx4 v[58:61], v[34:35], off
	v_readlane_b32 s0, v227, 29
	s_ashr_i32 s1, s0, 31
	s_lshl_b64 s[0:1], s[0:1], 10
	s_waitcnt lgkmcnt(0)
	v_add_f32_e32 v31, v32, v31
	v_cndmask_b32_e32 v32, v94, v40, vcc
	v_add_f32_e32 v94, 0, v79
	v_cvt_pk_f32_fp8_e32 v[78:79], v159
	v_lshl_add_u64 v[34:35], v[182:183], 0, s[0:1]
	global_load_dwordx4 v[50:53], v[34:35], off
	v_readlane_b32 s0, v227, 30
	v_mul_f32_e32 v79, v222, v79
	v_fmac_f32_e32 v79, v218, v78
	v_fmac_f32_e32 v79, v215, v80
	v_fmac_f32_e32 v79, v217, v81
	v_add_f32_e32 v94, v94, v79
	v_cvt_pk_f32_fp8_e32 v[78:79], v160
	v_cvt_pk_f32_fp8_sdwa v[80:81], v160 src0_sel:WORD_1
	s_ashr_i32 s1, s0, 31
	s_lshl_b64 s[0:1], s[0:1], 10
	v_mul_f32_e32 v79, v216, v79
	v_fmac_f32_e32 v79, v214, v78
	v_fmac_f32_e32 v79, v211, v80
	v_fmac_f32_e32 v79, v224, v81
	v_add_f32_e32 v94, v94, v79
	v_cvt_pk_f32_fp8_e32 v[78:79], v161
	v_cvt_pk_f32_fp8_sdwa v[80:81], v161 src0_sel:WORD_1
	v_lshl_add_u64 v[34:35], v[182:183], 0, s[0:1]
	global_load_dwordx4 v[42:45], v[34:35], off
	v_mul_f32_e32 v79, v221, v79
	v_fmac_f32_e32 v79, v219, v78
	v_fmac_f32_e32 v79, v212, v80
	v_fmac_f32_e32 v79, v213, v81
	v_add_f32_e32 v81, v94, v79
	v_cvt_pk_f32_fp8_e32 v[78:79], v150
	v_cvt_pk_f32_fp8_sdwa v[94:95], v150 src0_sel:WORD_1
	v_readlane_b32 s0, v227, 31
	s_ashr_i32 s1, s0, 31
	v_mul_f32_e32 v79, v226, v79
	v_fmac_f32_e32 v79, v225, v78
	v_fmac_f32_e32 v79, v220, v94
	v_fmac_f32_e32 v79, v223, v95
	v_add_f32_e32 v80, 0, v79
	v_cvt_pk_f32_fp8_e32 v[78:79], v151
	v_cvt_pk_f32_fp8_sdwa v[94:95], v151 src0_sel:WORD_1
	s_lshl_b64 s[0:1], s[0:1], 10
	v_lshl_add_u64 v[34:35], v[182:183], 0, s[0:1]
	v_mul_f32_e32 v79, v222, v79
	v_fmac_f32_e32 v79, v218, v78
	v_fmac_f32_e32 v79, v215, v94
	v_fmac_f32_e32 v79, v217, v95
	v_add_f32_e32 v80, v80, v79
	v_cvt_pk_f32_fp8_e32 v[78:79], v152
	v_cvt_pk_f32_fp8_sdwa v[94:95], v152 src0_sel:WORD_1
	global_load_dwordx4 v[34:37], v[34:35], off
	ds_bpermute_b32 v32, v205, v32
	v_mul_f32_e32 v79, v216, v79
	v_fmac_f32_e32 v79, v214, v78
	v_fmac_f32_e32 v79, v211, v94
	v_fmac_f32_e32 v79, v224, v95
	v_add_f32_e32 v80, v80, v79
	v_cvt_pk_f32_fp8_e32 v[78:79], v153
	v_cvt_pk_f32_fp8_sdwa v[94:95], v153 src0_sel:WORD_1
	s_waitcnt lgkmcnt(0)
; __device__ void phase_experts(const Params& p, int l) {
;     ...
; #pragma unroll
;       for (int j = 0; j < 16; ++j) {
;         float acc = 0.f;
; #pragma unroll
;         for (int c = 0; c < 4; ++c) {
;           const f32x2 a = __builtin_amdgcn_cvt_pk_f32_fp8((int)ru[j][c], false), b2 = __builtin_amdgcn_cvt_pk_f32_fp8((int)ru[j][c], true);
;           acc += a.x * hv[c * 4] + a.y * hv[c * 4 + 1] + b2.x * hv[c * 4 + 2] + b2.y * hv[c * 4 + 3];
;         }
;         sj[j] = acc;
;       }
; #pragma unroll
;       for (int hw = 8; hw >= 1; hw >>= 1) {
;         const bool up = (lane & hw) != 0;
; #pragma unroll
;         for (int k = 0; k < hw; ++k) {
;           const float send = up ? sj[k] : sj[k + hw], keep = up ? sj[k + hw] : sj[k];
;           sj[k] = keep + __shfl_xor(send, hw);
;         }
;       }
	v_add_f32_e32 v32, v33, v32
	v_cndmask_b32_e64 v33, v41, v25, s[4:5]
	v_mul_f32_e32 v79, v221, v79
	v_fmac_f32_e32 v79, v219, v78
	v_fmac_f32_e32 v79, v212, v94
	v_fmac_f32_e32 v79, v213, v95
	v_cvt_pk_f32_fp8_e32 v[94:95], v134
	v_add_f32_e32 v78, v80, v79
	ds_bpermute_b32 v33, v206, v33
	v_cndmask_b32_e64 v25, v25, v41, s[4:5]
	v_mul_f32_e32 v79, v226, v95
	v_fmac_f32_e32 v79, v225, v94
	v_cvt_pk_f32_fp8_e32 v[94:95], v135
	v_fmac_f32_e32 v79, v220, v96
	v_fmac_f32_e32 v79, v223, v97
	v_cvt_pk_f32_fp8_sdwa v[96:97], v135 src0_sel:WORD_1
	v_mul_f32_e32 v80, v222, v95
	v_fmac_f32_e32 v80, v218, v94
	v_cvt_pk_f32_fp8_e32 v[94:95], v136
	v_fmac_f32_e32 v80, v215, v96
	v_fmac_f32_e32 v80, v217, v97
	v_cvt_pk_f32_fp8_sdwa v[96:97], v136 src0_sel:WORD_1
	v_add_f32_e32 v79, 0, v79
	v_add_f32_e32 v79, v79, v80
	v_mul_f32_e32 v80, v216, v95
	v_fmac_f32_e32 v80, v214, v94
	v_cvt_pk_f32_fp8_e32 v[94:95], v137
	v_fmac_f32_e32 v80, v211, v96
	v_fmac_f32_e32 v80, v224, v97
	v_cvt_pk_f32_fp8_sdwa v[96:97], v137 src0_sel:WORD_1
	v_add_f32_e32 v79, v79, v80
	v_mul_f32_e32 v80, v221, v95
	v_fmac_f32_e32 v80, v219, v94
	s_waitcnt vmcnt(10)
	v_cvt_pk_f32_fp8_e32 v[94:95], v126
	v_fmac_f32_e32 v80, v212, v96
	v_fmac_f32_e32 v80, v213, v97
	v_cvt_pk_f32_fp8_sdwa v[96:97], v126 src0_sel:WORD_1
	v_add_f32_e32 v79, v79, v80
	v_mul_f32_e32 v80, v226, v95
	v_fmac_f32_e32 v80, v225, v94
	v_cvt_pk_f32_fp8_e32 v[94:95], v127
	v_fmac_f32_e32 v80, v220, v96
	v_fmac_f32_e32 v80, v223, v97
	v_cvt_pk_f32_fp8_sdwa v[96:97], v127 src0_sel:WORD_1
	v_mul_f32_e32 v95, v222, v95
	v_fmac_f32_e32 v95, v218, v94
	v_add_f32_e32 v80, 0, v80
	v_fmac_f32_e32 v95, v215, v96
	v_fmac_f32_e32 v95, v217, v97
	v_add_f32_e32 v80, v80, v95
	v_cvt_pk_f32_fp8_e32 v[94:95], v128
	v_cvt_pk_f32_fp8_sdwa v[96:97], v128 src0_sel:WORD_1
	s_waitcnt lgkmcnt(0)
	v_add_f32_e32 v25, v25, v33
	v_cndmask_b32_e64 v33, v22, v30, s[4:5]
	v_mul_f32_e32 v95, v216, v95
	v_fmac_f32_e32 v95, v214, v94
	v_fmac_f32_e32 v95, v211, v96
	v_fmac_f32_e32 v95, v224, v97
	v_add_f32_e32 v80, v80, v95
	v_cvt_pk_f32_fp8_e32 v[94:95], v129
	v_cvt_pk_f32_fp8_sdwa v[96:97], v129 src0_sel:WORD_1
	v_cndmask_b32_e64 v22, v30, v22, s[4:5]
	ds_bpermute_b32 v30, v206, v33
	v_mul_f32_e32 v95, v221, v95
	v_fmac_f32_e32 v95, v219, v94
	v_fmac_f32_e32 v95, v212, v96
	v_fmac_f32_e32 v95, v213, v97
	v_add_f32_e32 v80, v80, v95
	s_waitcnt vmcnt(9)
	v_cvt_pk_f32_fp8_e32 v[94:95], v106
	v_cvt_pk_f32_fp8_sdwa v[96:97], v106 src0_sel:WORD_1
	global_load_dwordx4 v[26:29], v[26:27], off
	s_waitcnt lgkmcnt(0)
	v_add_f32_e32 v22, v22, v30
	v_mul_f32_e32 v95, v226, v95
	v_fmac_f32_e32 v95, v225, v94
	v_fmac_f32_e32 v95, v220, v96
	v_fmac_f32_e32 v95, v223, v97
	v_add_f32_e32 v102, 0, v95
	v_cvt_pk_f32_fp8_e32 v[94:95], v107
	v_cvt_pk_f32_fp8_sdwa v[96:97], v107 src0_sel:WORD_1
	v_cndmask_b32_e64 v30, v23, v31, s[4:5]
	ds_bpermute_b32 v30, v206, v30
	v_mul_f32_e32 v95, v222, v95
	v_fmac_f32_e32 v95, v218, v94
	v_fmac_f32_e32 v95, v215, v96
	v_fmac_f32_e32 v95, v217, v97
	v_add_f32_e32 v102, v102, v95
	v_cvt_pk_f32_fp8_e32 v[94:95], v108
	v_cvt_pk_f32_fp8_sdwa v[96:97], v108 src0_sel:WORD_1
	v_cndmask_b32_e64 v23, v31, v23, s[4:5]
	s_waitcnt lgkmcnt(0)
	v_add_f32_e32 v23, v23, v30
	v_mul_f32_e32 v95, v216, v95
	v_fmac_f32_e32 v95, v214, v94
	v_fmac_f32_e32 v95, v211, v96
	v_fmac_f32_e32 v95, v224, v97
	v_add_f32_e32 v102, v102, v95
	v_cvt_pk_f32_fp8_e32 v[94:95], v109
	v_cvt_pk_f32_fp8_sdwa v[96:97], v109 src0_sel:WORD_1
	v_cndmask_b32_e64 v30, v24, v32, s[4:5]
	ds_bpermute_b32 v30, v206, v30
	v_mul_f32_e32 v95, v221, v95
	v_fmac_f32_e32 v95, v219, v94
	v_fmac_f32_e32 v95, v212, v96
	v_fmac_f32_e32 v95, v213, v97
	s_waitcnt vmcnt(9)
	v_cvt_pk_f32_fp8_e32 v[96:97], v98
	v_add_f32_e32 v94, v102, v95
	v_cvt_pk_f32_fp8_sdwa v[102:103], v98 src0_sel:WORD_1
	v_cndmask_b32_e64 v24, v32, v24, s[4:5]
	v_mul_f32_e32 v95, v226, v97
	v_fmac_f32_e32 v95, v225, v96
	v_cvt_pk_f32_fp8_e32 v[96:97], v99
	v_cvt_pk_f32_fp8_sdwa v[98:99], v99 src0_sel:WORD_1
	v_fmac_f32_e32 v95, v220, v102
	v_fmac_f32_e32 v95, v223, v103
	v_mul_f32_e32 v97, v222, v97
	v_fmac_f32_e32 v97, v218, v96
	v_fmac_f32_e32 v97, v215, v98
	v_add_f32_e32 v95, 0, v95
	v_fmac_f32_e32 v97, v217, v99
	v_add_f32_e32 v95, v95, v97
	v_cvt_pk_f32_fp8_e32 v[96:97], v100
	v_cvt_pk_f32_fp8_sdwa v[98:99], v100 src0_sel:WORD_1
	s_waitcnt lgkmcnt(0)
	v_add_f32_e32 v24, v24, v30
	v_cndmask_b32_e64 v30, v25, v23, s[6:7]
	v_mul_f32_e32 v97, v216, v97
	v_fmac_f32_e32 v97, v214, v96
	v_fmac_f32_e32 v97, v211, v98
	v_fmac_f32_e32 v97, v224, v99
	v_add_f32_e32 v95, v95, v97
	v_cvt_pk_f32_fp8_e32 v[96:97], v101
	v_cvt_pk_f32_fp8_sdwa v[98:99], v101 src0_sel:WORD_1
	v_cndmask_b32_e64 v23, v23, v25, s[6:7]
	ds_bpermute_b32 v25, v207, v30
	v_mul_f32_e32 v97, v221, v97
	v_fmac_f32_e32 v97, v219, v96
	v_fmac_f32_e32 v97, v212, v98
	v_fmac_f32_e32 v97, v213, v99
	v_add_f32_e32 v95, v95, v97
	s_waitcnt vmcnt(8)
	v_cvt_pk_f32_fp8_e32 v[96:97], v90
	v_cvt_pk_f32_fp8_sdwa v[98:99], v90 src0_sel:WORD_1
	s_waitcnt lgkmcnt(0)
	v_add_f32_e32 v23, v23, v25
	v_cndmask_b32_e64 v25, v22, v24, s[6:7]
	v_mul_f32_e32 v90, v226, v97
	v_fmac_f32_e32 v90, v225, v96
	v_fmac_f32_e32 v90, v220, v98
	v_cvt_pk_f32_fp8_e32 v[96:97], v91
	v_fmac_f32_e32 v90, v223, v99
	v_add_f32_e32 v98, 0, v90
	v_cvt_pk_f32_fp8_sdwa v[90:91], v91 src0_sel:WORD_1
	v_mul_f32_e32 v97, v222, v97
	v_fmac_f32_e32 v97, v218, v96
	ds_bpermute_b32 v25, v207, v25
	v_fmac_f32_e32 v97, v215, v90
	v_fmac_f32_e32 v97, v217, v91
	v_cvt_pk_f32_fp8_e32 v[90:91], v92
	v_add_f32_e32 v98, v98, v97
	v_cvt_pk_f32_fp8_sdwa v[96:97], v92 src0_sel:WORD_1
	v_cndmask_b32_e64 v22, v24, v22, s[6:7]
	v_mul_f32_e32 v91, v216, v91
	v_fmac_f32_e32 v91, v214, v90
	v_fmac_f32_e32 v91, v211, v96
	v_fmac_f32_e32 v91, v224, v97
	v_add_f32_e32 v96, v98, v91
	v_cvt_pk_f32_fp8_e32 v[90:91], v93
	v_cvt_pk_f32_fp8_sdwa v[92:93], v93 src0_sel:WORD_1
	s_waitcnt lgkmcnt(0)
; __device__ void phase_experts(const Params& p, int l) {
;     ...
;         const int nb = (bi + 1) & 7;
;         const int idv = bi == 7 ? idn0 : (nb < 4 ? id0 : id1);
; #pragma unroll
;         for (int j = 0; j < 16; ++j) {
;           const int row = __builtin_amdgcn_readlane(idv, (nb & 3) * 16 + j);
;           rbuf[(bi + 1) & 1][j] = *(const u32x4*)(U + (size_t)row * 1024 + lane * 16);
;         }
;       }
;       u32x4 (&ru)[16] = rbuf[bi & 1];
;       float sj[16];
; #pragma unroll
;       for (int j = 0; j < 16; ++j) {
;         float acc = 0.f;
; #pragma unroll
;         for (int c = 0; c < 4; ++c) {
;           const f32x2 a = __builtin_amdgcn_cvt_pk_f32_fp8((int)ru[j][c], false), b2 = __builtin_amdgcn_cvt_pk_f32_fp8((int)ru[j][c], true);
;           acc += a.x * hv[c * 4] + a.y * hv[c * 4 + 1] + b2.x * hv[c * 4 + 2] + b2.y * hv[c * 4 + 3];
;         }
;         sj[j] = acc;
;       }
; #pragma unroll
;       for (int hw = 8; hw >= 1; hw >>= 1) {
;         const bool up = (lane & hw) != 0;
; #pragma unroll
;         for (int k = 0; k < hw; ++k) {
;           const float send = up ? sj[k] : sj[k + hw], keep = up ? sj[k + hw] : sj[k];
;           sj[k] = keep + __shfl_xor(send, hw);
;         }
;       }
;       float tot = sj[0];
;       tot = xsum_rows(tot);
	v_add_f32_e32 v22, v22, v25
	v_cndmask_b32_e64 v24, v23, v22, s[8:9]
	v_mul_f32_e32 v91, v221, v91
	v_fmac_f32_e32 v91, v219, v90
	v_fmac_f32_e32 v91, v212, v92
	v_fmac_f32_e32 v91, v213, v93
	s_waitcnt vmcnt(7)
	v_cvt_pk_f32_fp8_e32 v[92:93], v86
	v_add_f32_e32 v90, v96, v91
	v_cvt_pk_f32_fp8_sdwa v[96:97], v86 src0_sel:WORD_1
	v_cndmask_b32_e64 v22, v22, v23, s[8:9]
	v_mul_f32_e32 v86, v226, v93
	v_fmac_f32_e32 v86, v225, v92
	v_fmac_f32_e32 v86, v220, v96
	v_cvt_pk_f32_fp8_e32 v[92:93], v87
	v_fmac_f32_e32 v86, v223, v97
	v_add_f32_e32 v91, 0, v86
	v_cvt_pk_f32_fp8_sdwa v[86:87], v87 src0_sel:WORD_1
	v_mul_f32_e32 v93, v222, v93
	v_fmac_f32_e32 v93, v218, v92
	ds_bpermute_b32 v23, v208, v24
	v_fmac_f32_e32 v93, v215, v86
	v_fmac_f32_e32 v93, v217, v87
	v_cvt_pk_f32_fp8_e32 v[86:87], v88
	v_add_f32_e32 v91, v91, v93
	v_cvt_pk_f32_fp8_sdwa v[92:93], v88 src0_sel:WORD_1
	s_waitcnt lgkmcnt(0)
	v_add_f32_e32 v22, v22, v23
	v_mul_f32_e32 v87, v216, v87
	v_fmac_f32_e32 v87, v214, v86
	v_fmac_f32_e32 v87, v211, v92
	v_fmac_f32_e32 v87, v224, v93
	v_add_f32_e32 v91, v91, v87
	v_cvt_pk_f32_fp8_e32 v[86:87], v89
	v_cvt_pk_f32_fp8_sdwa v[88:89], v89 src0_sel:WORD_1
	s_waitcnt vmcnt(6)
	v_cvt_pk_f32_fp8_sdwa v[92:93], v74 src0_sel:WORD_1
	v_readlane_b32 s0, v227, 32
	v_mul_f32_e32 v87, v221, v87
	v_fmac_f32_e32 v87, v219, v86
	v_fmac_f32_e32 v87, v212, v88
	v_fmac_f32_e32 v87, v213, v89
	v_cvt_pk_f32_fp8_e32 v[88:89], v74
	v_add_f32_e32 v86, v91, v87
	v_mov_b32_e32 v23, v22
	s_ashr_i32 s1, s0, 31
	v_mul_f32_e32 v74, v226, v89
	v_fmac_f32_e32 v74, v225, v88
	v_fmac_f32_e32 v74, v220, v92
	v_cvt_pk_f32_fp8_e32 v[88:89], v75
	v_fmac_f32_e32 v74, v223, v93
	v_add_f32_e32 v87, 0, v74
	v_cvt_pk_f32_fp8_sdwa v[74:75], v75 src0_sel:WORD_1
	v_mul_f32_e32 v89, v222, v89
	v_fmac_f32_e32 v89, v218, v88
	global_load_dwordx4 v[18:21], v[18:19], off
	v_fmac_f32_e32 v89, v215, v74
	v_fmac_f32_e32 v89, v217, v75
	v_cvt_pk_f32_fp8_e32 v[74:75], v76
	v_add_f32_e32 v87, v87, v89
	v_cvt_pk_f32_fp8_sdwa v[88:89], v76 src0_sel:WORD_1
	v_permlane16_swap_b32_e32 v22, v23
	v_mul_f32_e32 v75, v216, v75
	v_fmac_f32_e32 v75, v214, v74
	v_fmac_f32_e32 v75, v211, v88
	v_fmac_f32_e32 v75, v224, v89
	v_add_f32_e32 v87, v87, v75
	v_cvt_pk_f32_fp8_e32 v[74:75], v77
	v_cvt_pk_f32_fp8_sdwa v[76:77], v77 src0_sel:WORD_1
	s_waitcnt vmcnt(6)
	v_cvt_pk_f32_fp8_sdwa v[88:89], v66 src0_sel:WORD_1
	s_lshl_b64 s[0:1], s[0:1], 10
	v_mul_f32_e32 v75, v221, v75
	v_fmac_f32_e32 v75, v219, v74
	v_fmac_f32_e32 v75, v212, v76
	v_fmac_f32_e32 v75, v213, v77
	v_cvt_pk_f32_fp8_e32 v[76:77], v66
	v_add_f32_e32 v74, v87, v75
	v_add_f32_e32 v229, v22, v23
	v_lshl_add_u64 v[22:23], v[182:183], 0, s[0:1]
	v_mul_f32_e32 v66, v226, v77
	v_fmac_f32_e32 v66, v225, v76
	v_fmac_f32_e32 v66, v220, v88
	v_cvt_pk_f32_fp8_e32 v[76:77], v67
	v_fmac_f32_e32 v66, v223, v89
	v_add_f32_e32 v75, 0, v66
	v_cvt_pk_f32_fp8_sdwa v[66:67], v67 src0_sel:WORD_1
	v_mul_f32_e32 v77, v222, v77
	v_fmac_f32_e32 v77, v218, v76
	v_readlane_b32 s0, v227, 33
	v_fmac_f32_e32 v77, v215, v66
	v_fmac_f32_e32 v77, v217, v67
	v_cvt_pk_f32_fp8_e32 v[66:67], v68
	v_add_f32_e32 v75, v75, v77
	v_cvt_pk_f32_fp8_sdwa v[76:77], v68 src0_sel:WORD_1
	s_ashr_i32 s1, s0, 31
	v_mul_f32_e32 v67, v216, v67
	v_fmac_f32_e32 v67, v214, v66
	v_fmac_f32_e32 v67, v211, v76
	v_fmac_f32_e32 v67, v224, v77
	v_add_f32_e32 v75, v75, v67
	v_cvt_pk_f32_fp8_e32 v[66:67], v69
	v_cvt_pk_f32_fp8_sdwa v[68:69], v69 src0_sel:WORD_1
	s_waitcnt vmcnt(5)
	v_cvt_pk_f32_fp8_sdwa v[76:77], v58 src0_sel:WORD_1
	s_lshl_b64 s[0:1], s[0:1], 10
	v_mul_f32_e32 v67, v221, v67
	v_fmac_f32_e32 v67, v219, v66
	v_fmac_f32_e32 v67, v212, v68
	v_fmac_f32_e32 v67, v213, v69
	v_cvt_pk_f32_fp8_e32 v[68:69], v58
	v_add_f32_e32 v66, v75, v67
	global_load_dwordx4 v[170:173], v[22:23], off
	v_lshl_add_u64 v[22:23], v[182:183], 0, s[0:1]
	v_mul_f32_e32 v58, v226, v69
	v_fmac_f32_e32 v58, v225, v68
	v_fmac_f32_e32 v58, v220, v76
	v_cvt_pk_f32_fp8_e32 v[68:69], v59
	v_fmac_f32_e32 v58, v223, v77
	v_add_f32_e32 v67, 0, v58
	v_cvt_pk_f32_fp8_sdwa v[58:59], v59 src0_sel:WORD_1
	v_mul_f32_e32 v69, v222, v69
	v_fmac_f32_e32 v69, v218, v68
	v_readlane_b32 s0, v227, 34
	v_fmac_f32_e32 v69, v215, v58
	v_fmac_f32_e32 v69, v217, v59
	v_cvt_pk_f32_fp8_e32 v[58:59], v60
	v_add_f32_e32 v67, v67, v69
	v_cvt_pk_f32_fp8_sdwa v[68:69], v60 src0_sel:WORD_1
	s_ashr_i32 s1, s0, 31
	v_mul_f32_e32 v59, v216, v59
	v_fmac_f32_e32 v59, v214, v58
	v_fmac_f32_e32 v59, v211, v68
	v_fmac_f32_e32 v59, v224, v69
	v_add_f32_e32 v67, v67, v59
	v_cvt_pk_f32_fp8_e32 v[58:59], v61
	v_cvt_pk_f32_fp8_sdwa v[60:61], v61 src0_sel:WORD_1
	s_waitcnt vmcnt(5)
	v_cvt_pk_f32_fp8_sdwa v[68:69], v50 src0_sel:WORD_1
	s_lshl_b64 s[0:1], s[0:1], 10
	v_mul_f32_e32 v59, v221, v59
	v_fmac_f32_e32 v59, v219, v58
	v_fmac_f32_e32 v59, v212, v60
	v_fmac_f32_e32 v59, v213, v61
	v_cvt_pk_f32_fp8_e32 v[60:61], v50
	v_add_f32_e32 v58, v67, v59
	v_lshl_add_u64 v[30:31], v[182:183], 0, s[0:1]
	v_readlane_b32 s0, v227, 35
	v_mul_f32_e32 v50, v226, v61
	v_fmac_f32_e32 v50, v225, v60
	v_fmac_f32_e32 v50, v220, v68
	v_cvt_pk_f32_fp8_e32 v[60:61], v51
	v_fmac_f32_e32 v50, v223, v69
	v_add_f32_e32 v59, 0, v50
	v_cvt_pk_f32_fp8_sdwa v[50:51], v51 src0_sel:WORD_1
	v_mul_f32_e32 v61, v222, v61
	v_fmac_f32_e32 v61, v218, v60
	s_ashr_i32 s1, s0, 31
	v_fmac_f32_e32 v61, v215, v50
	v_fmac_f32_e32 v61, v217, v51
	v_cvt_pk_f32_fp8_e32 v[50:51], v52
	v_add_f32_e32 v59, v59, v61
	v_cvt_pk_f32_fp8_sdwa v[60:61], v52 src0_sel:WORD_1
	s_lshl_b64 s[0:1], s[0:1], 10
	v_mul_f32_e32 v51, v216, v51
	v_fmac_f32_e32 v51, v214, v50
	v_fmac_f32_e32 v51, v211, v60
	v_fmac_f32_e32 v51, v224, v61
	v_add_f32_e32 v59, v59, v51
	v_cvt_pk_f32_fp8_e32 v[50:51], v53
	v_cvt_pk_f32_fp8_sdwa v[52:53], v53 src0_sel:WORD_1
	s_waitcnt vmcnt(4)
; __device__ void phase_experts(const Params& p, int l) {
;     ...
;         const int nb = (bi + 1) & 7;
;         const int idv = bi == 7 ? idn0 : (nb < 4 ? id0 : id1);
; #pragma unroll
;         for (int j = 0; j < 16; ++j) {
;           const int row = __builtin_amdgcn_readlane(idv, (nb & 3) * 16 + j);
;           rbuf[(bi + 1) & 1][j] = *(const u32x4*)(U + (size_t)row * 1024 + lane * 16);
;         }
;       }
;       u32x4 (&ru)[16] = rbuf[bi & 1];
;       float sj[16];
; #pragma unroll
;       for (int j = 0; j < 16; ++j) {
;         float acc = 0.f;
; #pragma unroll
;         for (int c = 0; c < 4; ++c) {
;           const f32x2 a = __builtin_amdgcn_cvt_pk_f32_fp8((int)ru[j][c], false), b2 = __builtin_amdgcn_cvt_pk_f32_fp8((int)ru[j][c], true);
;           acc += a.x * hv[c * 4] + a.y * hv[c * 4 + 1] + b2.x * hv[c * 4 + 2] + b2.y * hv[c * 4 + 3];
;         }
;         sj[j] = acc;
;       }
; #pragma unroll
;       for (int hw = 8; hw >= 1; hw >>= 1) {
;         const bool up = (lane & hw) != 0;
; #pragma unroll
;         for (int k = 0; k < hw; ++k) {
;           const float send = up ? sj[k] : sj[k + hw], keep = up ? sj[k + hw] : sj[k];
;           sj[k] = keep + __shfl_xor(send, hw);
;         }
;       }
	v_cvt_pk_f32_fp8_sdwa v[60:61], v42 src0_sel:WORD_1
	global_load_dwordx4 v[162:165], v[30:31], off
	v_mul_f32_e32 v51, v221, v51
	v_fmac_f32_e32 v51, v219, v50
	v_fmac_f32_e32 v51, v212, v52
	v_fmac_f32_e32 v51, v213, v53
	v_cvt_pk_f32_fp8_e32 v[52:53], v42
	v_add_f32_e32 v50, v59, v51
	v_lshl_add_u64 v[30:31], v[182:183], 0, s[0:1]
	global_load_dwordx4 v[154:157], v[30:31], off
	v_mul_f32_e32 v42, v226, v53
	v_fmac_f32_e32 v42, v225, v52
	v_fmac_f32_e32 v42, v220, v60
	v_cvt_pk_f32_fp8_e32 v[52:53], v43
	v_fmac_f32_e32 v42, v223, v61
	v_add_f32_e32 v51, 0, v42
	v_cvt_pk_f32_fp8_sdwa v[42:43], v43 src0_sel:WORD_1
	v_mul_f32_e32 v53, v222, v53
	v_fmac_f32_e32 v53, v218, v52
	v_readlane_b32 s0, v227, 36
	v_fmac_f32_e32 v53, v215, v42
	v_fmac_f32_e32 v53, v217, v43
	v_cvt_pk_f32_fp8_e32 v[42:43], v44
	v_add_f32_e32 v51, v51, v53
	v_cvt_pk_f32_fp8_sdwa v[52:53], v44 src0_sel:WORD_1
	s_ashr_i32 s1, s0, 31
	v_mul_f32_e32 v43, v216, v43
	v_fmac_f32_e32 v43, v214, v42
	v_fmac_f32_e32 v43, v211, v52
	v_fmac_f32_e32 v43, v224, v53
	v_add_f32_e32 v51, v51, v43
	v_cvt_pk_f32_fp8_e32 v[42:43], v45
	v_cvt_pk_f32_fp8_sdwa v[44:45], v45 src0_sel:WORD_1
	s_waitcnt vmcnt(5)
	v_cvt_pk_f32_fp8_sdwa v[52:53], v34 src0_sel:WORD_1
	s_lshl_b64 s[0:1], s[0:1], 10
	v_mul_f32_e32 v43, v221, v43
	v_fmac_f32_e32 v43, v219, v42
	v_fmac_f32_e32 v43, v212, v44
	v_fmac_f32_e32 v43, v213, v45
	v_cvt_pk_f32_fp8_e32 v[44:45], v34
	v_add_f32_e32 v42, v51, v43
	v_lshl_add_u64 v[30:31], v[182:183], 0, s[0:1]
	v_readlane_b32 s0, v227, 37
	v_mul_f32_e32 v34, v226, v45
	v_fmac_f32_e32 v34, v225, v44
	v_fmac_f32_e32 v34, v220, v52
	v_cvt_pk_f32_fp8_e32 v[44:45], v35
	v_fmac_f32_e32 v34, v223, v53
	v_add_f32_e32 v43, 0, v34
	v_cvt_pk_f32_fp8_sdwa v[34:35], v35 src0_sel:WORD_1
	v_mul_f32_e32 v45, v222, v45
	v_fmac_f32_e32 v45, v218, v44
	s_ashr_i32 s1, s0, 31
	v_fmac_f32_e32 v45, v215, v34
	v_fmac_f32_e32 v45, v217, v35
	v_cvt_pk_f32_fp8_e32 v[34:35], v36
	v_add_f32_e32 v43, v43, v45
	v_cvt_pk_f32_fp8_sdwa v[44:45], v36 src0_sel:WORD_1
	s_lshl_b64 s[0:1], s[0:1], 10
	v_mul_f32_e32 v35, v216, v35
	v_fmac_f32_e32 v35, v214, v34
	v_fmac_f32_e32 v35, v211, v44
	v_fmac_f32_e32 v35, v224, v45
	v_add_f32_e32 v43, v43, v35
	v_cvt_pk_f32_fp8_e32 v[34:35], v37
	v_cvt_pk_f32_fp8_sdwa v[36:37], v37 src0_sel:WORD_1
	global_load_dwordx4 v[146:149], v[30:31], off
	v_lshl_add_u64 v[30:31], v[182:183], 0, s[0:1]
	v_mul_f32_e32 v35, v221, v35
	v_fmac_f32_e32 v35, v219, v34
	v_cndmask_b32_e32 v34, v81, v86, vcc
	ds_bpermute_b32 v34, v205, v34
	v_fmac_f32_e32 v35, v212, v36
	v_fmac_f32_e32 v35, v213, v37
	v_add_f32_e32 v36, v43, v35
	v_cndmask_b32_e32 v35, v86, v81, vcc
	s_waitcnt lgkmcnt(0)
	v_add_f32_e32 v37, v35, v34
	s_waitcnt vmcnt(5)
	v_cvt_pk_f32_fp8_e32 v[34:35], v26
	v_readlane_b32 s0, v227, 38
	s_ashr_i32 s1, s0, 31
	s_lshl_b64 s[0:1], s[0:1], 10
	v_mul_f32_e32 v43, v226, v35
	v_fmac_f32_e32 v43, v225, v34
	v_cvt_pk_f32_fp8_sdwa v[34:35], v26 src0_sel:WORD_1
	global_load_dwordx4 v[138:141], v[30:31], off
	v_lshl_add_u64 v[30:31], v[182:183], 0, s[0:1]
	v_readlane_b32 s0, v227, 39
	v_fmac_f32_e32 v43, v220, v34
	v_fmac_f32_e32 v43, v223, v35
	v_cvt_pk_f32_fp8_e32 v[34:35], v27
	v_cvt_pk_f32_fp8_sdwa v[26:27], v27 src0_sel:WORD_1
	v_add_f32_e32 v43, 0, v43
	s_ashr_i32 s1, s0, 31
	v_mul_f32_e32 v35, v222, v35
	v_fmac_f32_e32 v35, v218, v34
	v_fmac_f32_e32 v35, v215, v26
	v_fmac_f32_e32 v35, v217, v27
	v_cvt_pk_f32_fp8_e32 v[26:27], v28
	v_add_f32_e32 v34, v43, v35
	s_lshl_b64 s[0:1], s[0:1], 10
	global_load_dwordx4 v[130:133], v[30:31], off
	v_mul_f32_e32 v35, v216, v27
	v_fmac_f32_e32 v35, v214, v26
	v_cvt_pk_f32_fp8_sdwa v[26:27], v28 src0_sel:WORD_1
	v_lshl_add_u64 v[30:31], v[182:183], 0, s[0:1]
	v_readlane_b32 s0, v227, 40
	s_ashr_i32 s1, s0, 31
	v_fmac_f32_e32 v35, v211, v26
	v_fmac_f32_e32 v35, v224, v27
	v_cvt_pk_f32_fp8_e32 v[26:27], v29
	v_add_f32_e32 v28, v34, v35
	s_lshl_b64 s[0:1], s[0:1], 10
	global_load_dwordx4 v[122:125], v[30:31], off
	v_mul_f32_e32 v34, v221, v27
	v_fmac_f32_e32 v34, v219, v26
	v_cvt_pk_f32_fp8_sdwa v[26:27], v29 src0_sel:WORD_1
	v_lshl_add_u64 v[30:31], v[182:183], 0, s[0:1]
	v_readlane_b32 s0, v227, 41
	s_ashr_i32 s1, s0, 31
	v_fmac_f32_e32 v34, v212, v26
	v_fmac_f32_e32 v34, v213, v27
	s_waitcnt vmcnt(7)
	v_cvt_pk_f32_fp8_e32 v[26:27], v18
	v_add_f32_e32 v28, v28, v34
	s_lshl_b64 s[0:1], s[0:1], 10
	global_load_dwordx4 v[114:117], v[30:31], off
	v_mul_f32_e32 v29, v226, v27
	v_fmac_f32_e32 v29, v225, v26
	v_cvt_pk_f32_fp8_sdwa v[26:27], v18 src0_sel:WORD_1
	v_lshl_add_u64 v[30:31], v[182:183], 0, s[0:1]
	v_readlane_b32 s0, v227, 42
	s_ashr_i32 s1, s0, 31
	v_fmac_f32_e32 v29, v220, v26
	v_fmac_f32_e32 v29, v223, v27
	v_cvt_pk_f32_fp8_e32 v[26:27], v19
	v_cvt_pk_f32_fp8_sdwa v[18:19], v19 src0_sel:WORD_1
	v_add_f32_e32 v29, 0, v29
	s_lshl_b64 s[0:1], s[0:1], 10
	v_mul_f32_e32 v27, v222, v27
	v_fmac_f32_e32 v27, v218, v26
	v_fmac_f32_e32 v27, v215, v18
	v_fmac_f32_e32 v27, v217, v19
	v_cvt_pk_f32_fp8_e32 v[18:19], v20
	v_add_f32_e32 v26, v29, v27
	v_cndmask_b32_e32 v29, v36, v90, vcc
	v_lshl_add_u64 v[38:39], v[182:183], 0, s[0:1]
	v_mul_f32_e32 v27, v216, v19
	v_fmac_f32_e32 v27, v214, v18
	v_cvt_pk_f32_fp8_sdwa v[18:19], v20 src0_sel:WORD_1
	v_readlane_b32 s0, v227, 43
	s_ashr_i32 s1, s0, 31
	s_lshl_b64 s[0:1], s[0:1], 10
	v_fmac_f32_e32 v27, v211, v18
	v_fmac_f32_e32 v27, v224, v19
	v_cvt_pk_f32_fp8_e32 v[18:19], v21
	v_add_f32_e32 v20, v26, v27
	v_cndmask_b32_e32 v27, v50, v94, vcc
	global_load_dwordx4 v[82:85], v[38:39], off
	v_mul_f32_e32 v26, v221, v19
	v_fmac_f32_e32 v26, v219, v18
	v_cvt_pk_f32_fp8_sdwa v[18:19], v21 src0_sel:WORD_1
	v_cndmask_b32_e32 v21, v66, v79, vcc
	v_lshl_add_u64 v[38:39], v[182:183], 0, s[0:1]
	v_readlane_b32 s0, v227, 44
	v_fmac_f32_e32 v26, v212, v18
	v_fmac_f32_e32 v26, v213, v19
	v_add_f32_e32 v18, v20, v26
	v_cndmask_b32_e32 v19, v18, v28, vcc
	ds_bpermute_b32 v19, v205, v19
	v_cndmask_b32_e32 v18, v28, v18, vcc
	v_cndmask_b32_e32 v20, v74, v78, vcc
	v_cndmask_b32_e32 v26, v58, v80, vcc
	v_cndmask_b32_e32 v28, v42, v95, vcc
	s_waitcnt lgkmcnt(0)
; __device__ void phase_experts(const Params& p, int l) {
;     ...
;         const int nb = (bi + 1) & 7;
;         const int idv = bi == 7 ? idn0 : (nb < 4 ? id0 : id1);
; #pragma unroll
;         for (int j = 0; j < 16; ++j) {
;           const int row = __builtin_amdgcn_readlane(idv, (nb & 3) * 16 + j);
;           rbuf[(bi + 1) & 1][j] = *(const u32x4*)(U + (size_t)row * 1024 + lane * 16);
;         }
;     ...
; #pragma unroll
;       for (int hw = 8; hw >= 1; hw >>= 1) {
;         const bool up = (lane & hw) != 0;
; #pragma unroll
;         for (int k = 0; k < hw; ++k) {
;           const float send = up ? sj[k] : sj[k + hw], keep = up ? sj[k + hw] : sj[k];
;           sj[k] = keep + __shfl_xor(send, hw);
;         }
;       }
;       float tot = sj[0];
;       tot = xsum_rows(tot);
	v_add_f32_e32 v18, v18, v19
	v_cndmask_b32_e32 v19, v78, v74, vcc
	ds_bpermute_b32 v19, v205, v19
	s_ashr_i32 s1, s0, 31
	s_lshl_b64 s[0:1], s[0:1], 10
	global_load_dwordx4 v[70:73], v[38:39], off
	v_lshl_add_u64 v[38:39], v[182:183], 0, s[0:1]
	s_waitcnt lgkmcnt(0)
	v_add_f32_e32 v19, v20, v19
	v_cndmask_b32_e32 v20, v79, v66, vcc
	ds_bpermute_b32 v20, v205, v20
	v_readlane_b32 s0, v227, 45
	s_ashr_i32 s1, s0, 31
	s_lshl_b64 s[0:1], s[0:1], 10
	global_load_dwordx4 v[62:65], v[38:39], off
	s_waitcnt lgkmcnt(0)
	v_add_f32_e32 v20, v21, v20
	v_cndmask_b32_e32 v21, v80, v58, vcc
	ds_bpermute_b32 v21, v205, v21
	v_lshl_add_u64 v[38:39], v[182:183], 0, s[0:1]
	v_readlane_b32 s0, v227, 46
	s_ashr_i32 s1, s0, 31
	s_lshl_b64 s[0:1], s[0:1], 10
	s_waitcnt lgkmcnt(0)
	v_add_f32_e32 v21, v26, v21
	v_cndmask_b32_e32 v26, v94, v50, vcc
	ds_bpermute_b32 v26, v205, v26
	global_load_dwordx4 v[54:57], v[38:39], off
	v_lshl_add_u64 v[38:39], v[182:183], 0, s[0:1]
	v_readlane_b32 s0, v227, 47
	s_ashr_i32 s1, s0, 31
	s_waitcnt lgkmcnt(0)
	v_add_f32_e32 v26, v27, v26
	v_cndmask_b32_e32 v27, v95, v42, vcc
	ds_bpermute_b32 v27, v205, v27
	s_lshl_b64 s[0:1], s[0:1], 10
	global_load_dwordx4 v[46:49], v[38:39], off
	v_lshl_add_u64 v[38:39], v[182:183], 0, s[0:1]
	v_readlane_b32 s0, v227, 48
	s_waitcnt lgkmcnt(0)
	v_add_f32_e32 v27, v28, v27
	v_cndmask_b32_e32 v28, v90, v36, vcc
	ds_bpermute_b32 v28, v205, v28
	s_ashr_i32 s1, s0, 31
	s_lshl_b64 s[0:1], s[0:1], 10
	global_load_dwordx4 v[22:25], v[22:23], off
	v_mov_b32_e32 v230, v229
	s_waitcnt lgkmcnt(0)
	v_add_f32_e32 v28, v29, v28
	v_cndmask_b32_e64 v29, v37, v21, s[4:5]
	ds_bpermute_b32 v29, v206, v29
	v_cndmask_b32_e64 v21, v21, v37, s[4:5]
	global_load_dwordx4 v[30:33], v[30:31], off
	v_permlane32_swap_b32_e32 v229, v230
	s_waitcnt lgkmcnt(0)
	v_add_f32_e32 v21, v21, v29
	v_cndmask_b32_e64 v29, v18, v26, s[4:5]
	v_cndmask_b32_e64 v18, v26, v18, s[4:5]
	ds_bpermute_b32 v26, v206, v29
	global_load_dwordx4 v[38:41], v[38:39], off
	s_waitcnt lgkmcnt(0)
	v_add_f32_e32 v18, v18, v26
	v_cndmask_b32_e64 v26, v19, v27, s[4:5]
	ds_bpermute_b32 v26, v206, v26
	v_cndmask_b32_e64 v19, v27, v19, s[4:5]
	s_waitcnt lgkmcnt(0)
	v_add_f32_e32 v19, v19, v26
	v_cndmask_b32_e64 v26, v20, v28, s[4:5]
	ds_bpermute_b32 v26, v206, v26
	v_cndmask_b32_e64 v20, v28, v20, s[4:5]
	s_waitcnt vmcnt(13)
	v_cvt_pk_f32_fp8_sdwa v[28:29], v154 src0_sel:WORD_1
	s_waitcnt vmcnt(7)
	v_cvt_pk_f32_fp8_sdwa v[42:43], v82 src0_sel:WORD_1
	s_waitcnt lgkmcnt(0)
	v_add_f32_e32 v20, v20, v26
	v_cndmask_b32_e64 v26, v21, v19, s[6:7]
	v_cndmask_b32_e64 v19, v19, v21, s[6:7]
	ds_bpermute_b32 v21, v207, v26
	s_waitcnt lgkmcnt(0)
	v_add_f32_e32 v19, v19, v21
	v_cndmask_b32_e64 v21, v18, v20, s[6:7]
	ds_bpermute_b32 v21, v207, v21
	v_cndmask_b32_e64 v18, v20, v18, s[6:7]
	s_waitcnt lgkmcnt(0)
	v_add_f32_e32 v18, v18, v21
	v_cndmask_b32_e64 v20, v19, v18, s[8:9]
	v_cndmask_b32_e64 v18, v18, v19, s[8:9]
	ds_bpermute_b32 v19, v208, v20
	v_cvt_pk_f32_fp8_sdwa v[20:21], v170 src0_sel:WORD_1
	s_waitcnt vmcnt(5)
	v_cvt_pk_f32_fp8_sdwa v[44:45], v62 src0_sel:WORD_1
	s_waitcnt lgkmcnt(0)
	v_add_f32_e32 v18, v18, v19
	v_mov_b32_e32 v19, v18
	s_nop 1
	v_permlane16_swap_b32_e32 v18, v19
	v_add_f32_e32 v231, v18, v19
	v_lshl_add_u64 v[18:19], v[182:183], 0, s[0:1]
	v_readlane_b32 s0, v227, 49
	s_ashr_i32 s1, s0, 31
	s_lshl_b64 s[0:1], s[0:1], 10
	global_load_dwordx4 v[174:177], v[18:19], off
	v_lshl_add_u64 v[18:19], v[182:183], 0, s[0:1]
	v_readlane_b32 s0, v227, 50
	s_ashr_i32 s1, s0, 31
	s_lshl_b64 s[0:1], s[0:1], 10
	global_load_dwordx4 v[78:81], v[18:19], off
	v_lshl_add_u64 v[18:19], v[182:183], 0, s[0:1]
	v_readlane_b32 s0, v227, 51
	s_ashr_i32 s1, s0, 31
	s_lshl_b64 s[0:1], s[0:1], 10
	global_load_dwordx4 v[166:169], v[18:19], off
	v_lshl_add_u64 v[18:19], v[182:183], 0, s[0:1]
	v_readlane_b32 s0, v227, 52
	s_ashr_i32 s1, s0, 31
	s_lshl_b64 s[0:1], s[0:1], 10
	global_load_dwordx4 v[158:161], v[18:19], off
	v_lshl_add_u64 v[18:19], v[182:183], 0, s[0:1]
	v_readlane_b32 s0, v227, 53
	s_ashr_i32 s1, s0, 31
	s_lshl_b64 s[0:1], s[0:1], 10
	global_load_dwordx4 v[150:153], v[18:19], off
	v_lshl_add_u64 v[18:19], v[182:183], 0, s[0:1]
	v_readlane_b32 s0, v227, 54
	s_ashr_i32 s1, s0, 31
	s_lshl_b64 s[0:1], s[0:1], 10
	global_load_dwordx4 v[142:145], v[18:19], off
	v_lshl_add_u64 v[18:19], v[182:183], 0, s[0:1]
	v_readlane_b32 s0, v227, 55
	s_ashr_i32 s1, s0, 31
	s_lshl_b64 s[0:1], s[0:1], 10
	global_load_dwordx4 v[134:137], v[18:19], off
	v_lshl_add_u64 v[18:19], v[182:183], 0, s[0:1]
	v_readlane_b32 s0, v227, 56
	s_ashr_i32 s1, s0, 31
	s_lshl_b64 s[0:1], s[0:1], 10
	global_load_dwordx4 v[126:129], v[18:19], off
	v_lshl_add_u64 v[18:19], v[182:183], 0, s[0:1]
	v_readlane_b32 s0, v227, 57
	s_ashr_i32 s1, s0, 31
	s_lshl_b64 s[0:1], s[0:1], 10
	global_load_dwordx4 v[118:121], v[18:19], off
	v_lshl_add_u64 v[18:19], v[182:183], 0, s[0:1]
	v_readlane_b32 s0, v227, 58
	s_ashr_i32 s1, s0, 31
	s_lshl_b64 s[0:1], s[0:1], 10
	global_load_dwordx4 v[86:89], v[18:19], off
	v_lshl_add_u64 v[18:19], v[182:183], 0, s[0:1]
	v_readlane_b32 s0, v227, 59
	s_ashr_i32 s1, s0, 31
	s_lshl_b64 s[0:1], s[0:1], 10
	global_load_dwordx4 v[110:113], v[18:19], off
	v_lshl_add_u64 v[18:19], v[182:183], 0, s[0:1]
	v_readlane_b32 s0, v227, 60
	s_ashr_i32 s1, s0, 31
	s_lshl_b64 s[0:1], s[0:1], 10
	global_load_dwordx4 v[106:109], v[18:19], off
	v_lshl_add_u64 v[18:19], v[182:183], 0, s[0:1]
	v_readlane_b32 s0, v227, 61
	s_ashr_i32 s1, s0, 31
	s_lshl_b64 s[0:1], s[0:1], 10
	global_load_dwordx4 v[102:105], v[18:19], off
	v_lshl_add_u64 v[18:19], v[182:183], 0, s[0:1]
	v_readlane_b32 s0, v227, 62
	s_ashr_i32 s1, s0, 31
; __device__ void phase_experts(const Params& p, int l) {
;     ...
;         for (int j = 0; j < 16; ++j) {
;           const int row = __builtin_amdgcn_readlane(idv, (nb & 3) * 16 + j);
;           rbuf[(bi + 1) & 1][j] = *(const u32x4*)(U + (size_t)row * 1024 + lane * 16);
;         }
;       }
;       u32x4 (&ru)[16] = rbuf[bi & 1];
;       float sj[16];
; #pragma unroll
;       for (int j = 0; j < 16; ++j) {
;         float acc = 0.f;
; #pragma unroll
;         for (int c = 0; c < 4; ++c) {
;           const f32x2 a = __builtin_amdgcn_cvt_pk_f32_fp8((int)ru[j][c], false), b2 = __builtin_amdgcn_cvt_pk_f32_fp8((int)ru[j][c], true);
;           acc += a.x * hv[c * 4] + a.y * hv[c * 4 + 1] + b2.x * hv[c * 4 + 2] + b2.y * hv[c * 4 + 3];
;         }
;         sj[j] = acc;
	s_lshl_b64 s[0:1], s[0:1], 10
	global_load_dwordx4 v[98:101], v[18:19], off
	v_lshl_add_u64 v[18:19], v[182:183], 0, s[0:1]
	v_readlane_b32 s0, v227, 63
	s_ashr_i32 s1, s0, 31
	s_lshl_b64 s[0:1], s[0:1], 10
	global_load_dwordx4 v[94:97], v[18:19], off
	v_lshl_add_u64 v[18:19], v[182:183], 0, s[0:1]
	global_load_dwordx4 v[90:93], v[18:19], off
	v_cvt_pk_f32_fp8_e32 v[18:19], v170
	v_readlane_b32 s0, v203, 0
	s_ashr_i32 s1, s0, 31
	s_lshl_b64 s[0:1], s[0:1], 10
	v_mul_f32_e32 v19, v226, v19
	v_fmac_f32_e32 v19, v225, v18
	v_fmac_f32_e32 v19, v220, v20
	v_fmac_f32_e32 v19, v223, v21
	v_add_f32_e32 v26, 0, v19
	v_cvt_pk_f32_fp8_e32 v[18:19], v171
	v_cvt_pk_f32_fp8_sdwa v[20:21], v171 src0_sel:WORD_1
	v_mov_b32_e32 v232, v231
	s_nop 1
	v_permlane32_swap_b32_e32 v231, v232
	v_mul_f32_e32 v19, v222, v19
	v_fmac_f32_e32 v19, v218, v18
	v_fmac_f32_e32 v19, v215, v20
	v_fmac_f32_e32 v19, v217, v21
	v_add_f32_e32 v26, v26, v19
	v_cvt_pk_f32_fp8_e32 v[18:19], v172
	v_cvt_pk_f32_fp8_sdwa v[20:21], v172 src0_sel:WORD_1
	v_mul_f32_e32 v19, v216, v19
	v_fmac_f32_e32 v19, v214, v18
	v_fmac_f32_e32 v19, v211, v20
	v_fmac_f32_e32 v19, v224, v21
	v_add_f32_e32 v26, v26, v19
	v_cvt_pk_f32_fp8_e32 v[18:19], v173
	v_cvt_pk_f32_fp8_sdwa v[20:21], v173 src0_sel:WORD_1
	v_mul_f32_e32 v19, v221, v19
	v_fmac_f32_e32 v19, v219, v18
	v_fmac_f32_e32 v19, v212, v20
	v_fmac_f32_e32 v19, v213, v21
	v_add_f32_e32 v21, v26, v19
	v_cvt_pk_f32_fp8_e32 v[18:19], v162
	v_cvt_pk_f32_fp8_sdwa v[26:27], v162 src0_sel:WORD_1
	v_mul_f32_e32 v19, v226, v19
	v_fmac_f32_e32 v19, v225, v18
	v_fmac_f32_e32 v19, v220, v26
	v_fmac_f32_e32 v19, v223, v27
	v_add_f32_e32 v20, 0, v19
	v_cvt_pk_f32_fp8_e32 v[18:19], v163
	v_cvt_pk_f32_fp8_sdwa v[26:27], v163 src0_sel:WORD_1
	v_mul_f32_e32 v19, v222, v19
	v_fmac_f32_e32 v19, v218, v18
	v_fmac_f32_e32 v19, v215, v26
	v_fmac_f32_e32 v19, v217, v27
	v_add_f32_e32 v20, v20, v19
	v_cvt_pk_f32_fp8_e32 v[18:19], v164
	v_cvt_pk_f32_fp8_sdwa v[26:27], v164 src0_sel:WORD_1
	v_mul_f32_e32 v19, v216, v19
	v_fmac_f32_e32 v19, v214, v18
	v_fmac_f32_e32 v19, v211, v26
	v_fmac_f32_e32 v19, v224, v27
	v_add_f32_e32 v20, v20, v19
	v_cvt_pk_f32_fp8_e32 v[18:19], v165
	v_cvt_pk_f32_fp8_sdwa v[26:27], v165 src0_sel:WORD_1
	v_mul_f32_e32 v19, v221, v19
	v_fmac_f32_e32 v19, v219, v18
	v_fmac_f32_e32 v19, v212, v26
	v_fmac_f32_e32 v19, v213, v27
	v_cvt_pk_f32_fp8_e32 v[26:27], v154
	v_add_f32_e32 v18, v20, v19
	v_mul_f32_e32 v19, v226, v27
	v_fmac_f32_e32 v19, v225, v26
	v_cvt_pk_f32_fp8_e32 v[26:27], v155
	v_fmac_f32_e32 v19, v220, v28
	v_fmac_f32_e32 v19, v223, v29
	v_cvt_pk_f32_fp8_sdwa v[28:29], v155 src0_sel:WORD_1
	v_mul_f32_e32 v20, v222, v27
	v_fmac_f32_e32 v20, v218, v26
	v_cvt_pk_f32_fp8_e32 v[26:27], v156
	v_fmac_f32_e32 v20, v215, v28
	v_fmac_f32_e32 v20, v217, v29
	v_cvt_pk_f32_fp8_sdwa v[28:29], v156 src0_sel:WORD_1
	v_add_f32_e32 v19, 0, v19
	v_add_f32_e32 v19, v19, v20
	v_mul_f32_e32 v20, v216, v27
	v_fmac_f32_e32 v20, v214, v26
	v_cvt_pk_f32_fp8_e32 v[26:27], v157
	v_fmac_f32_e32 v20, v211, v28
	v_fmac_f32_e32 v20, v224, v29
	v_cvt_pk_f32_fp8_sdwa v[28:29], v157 src0_sel:WORD_1
	v_add_f32_e32 v19, v19, v20
	v_mul_f32_e32 v20, v221, v27
	v_fmac_f32_e32 v20, v219, v26
	v_cvt_pk_f32_fp8_e32 v[26:27], v146
	v_fmac_f32_e32 v20, v212, v28
	v_fmac_f32_e32 v20, v213, v29
	v_cvt_pk_f32_fp8_sdwa v[28:29], v146 src0_sel:WORD_1
	v_add_f32_e32 v19, v19, v20
	v_mul_f32_e32 v20, v226, v27
	v_fmac_f32_e32 v20, v225, v26
	v_cvt_pk_f32_fp8_e32 v[26:27], v147
	v_fmac_f32_e32 v20, v220, v28
	v_fmac_f32_e32 v20, v223, v29
	v_cvt_pk_f32_fp8_sdwa v[28:29], v147 src0_sel:WORD_1
	v_mul_f32_e32 v27, v222, v27
	v_fmac_f32_e32 v27, v218, v26
	v_add_f32_e32 v20, 0, v20
	v_fmac_f32_e32 v27, v215, v28
	v_fmac_f32_e32 v27, v217, v29
	v_add_f32_e32 v20, v20, v27
	v_cvt_pk_f32_fp8_e32 v[26:27], v148
	v_cvt_pk_f32_fp8_sdwa v[28:29], v148 src0_sel:WORD_1
	v_mul_f32_e32 v27, v216, v27
	v_fmac_f32_e32 v27, v214, v26
	v_fmac_f32_e32 v27, v211, v28
	v_fmac_f32_e32 v27, v224, v29
	v_add_f32_e32 v20, v20, v27
	v_cvt_pk_f32_fp8_e32 v[26:27], v149
	v_cvt_pk_f32_fp8_sdwa v[28:29], v149 src0_sel:WORD_1
	v_mul_f32_e32 v27, v221, v27
	v_fmac_f32_e32 v27, v219, v26
	v_fmac_f32_e32 v27, v212, v28
	v_fmac_f32_e32 v27, v213, v29
	v_add_f32_e32 v20, v20, v27
	v_cvt_pk_f32_fp8_e32 v[26:27], v138
	v_cvt_pk_f32_fp8_sdwa v[28:29], v138 src0_sel:WORD_1
	v_mul_f32_e32 v27, v226, v27
	v_fmac_f32_e32 v27, v225, v26
	v_fmac_f32_e32 v27, v220, v28
	v_fmac_f32_e32 v27, v223, v29
	v_add_f32_e32 v34, 0, v27
	v_cvt_pk_f32_fp8_e32 v[26:27], v139
	v_cvt_pk_f32_fp8_sdwa v[28:29], v139 src0_sel:WORD_1
	v_mul_f32_e32 v27, v222, v27
	v_fmac_f32_e32 v27, v218, v26
	v_fmac_f32_e32 v27, v215, v28
	v_fmac_f32_e32 v27, v217, v29
	v_add_f32_e32 v34, v34, v27
	v_cvt_pk_f32_fp8_e32 v[26:27], v140
	v_cvt_pk_f32_fp8_sdwa v[28:29], v140 src0_sel:WORD_1
	v_mul_f32_e32 v27, v216, v27
	v_fmac_f32_e32 v27, v214, v26
	v_fmac_f32_e32 v27, v211, v28
	v_fmac_f32_e32 v27, v224, v29
	v_add_f32_e32 v34, v34, v27
	v_cvt_pk_f32_fp8_e32 v[26:27], v141
	v_cvt_pk_f32_fp8_sdwa v[28:29], v141 src0_sel:WORD_1
	v_mul_f32_e32 v27, v221, v27
	v_fmac_f32_e32 v27, v219, v26
	v_fmac_f32_e32 v27, v212, v28
	v_fmac_f32_e32 v27, v213, v29
	v_cvt_pk_f32_fp8_e32 v[28:29], v130
	v_add_f32_e32 v26, v34, v27
	v_cvt_pk_f32_fp8_sdwa v[34:35], v130 src0_sel:WORD_1
	v_mul_f32_e32 v27, v226, v29
	v_fmac_f32_e32 v27, v225, v28
	v_cvt_pk_f32_fp8_e32 v[28:29], v131
	v_fmac_f32_e32 v27, v220, v34
	v_fmac_f32_e32 v27, v223, v35
	v_cvt_pk_f32_fp8_sdwa v[34:35], v131 src0_sel:WORD_1
	v_mul_f32_e32 v29, v222, v29
	v_fmac_f32_e32 v29, v218, v28
	v_add_f32_e32 v27, 0, v27
	v_fmac_f32_e32 v29, v215, v34
	v_fmac_f32_e32 v29, v217, v35
	v_add_f32_e32 v27, v27, v29
	v_cvt_pk_f32_fp8_e32 v[28:29], v132
	v_cvt_pk_f32_fp8_sdwa v[34:35], v132 src0_sel:WORD_1
	s_waitcnt vmcnt(12)
; __device__ void phase_experts(const Params& p, int l) {
;     ...
; #pragma unroll
;       for (int j = 0; j < 16; ++j) {
;         float acc = 0.f;
; #pragma unroll
;         for (int c = 0; c < 4; ++c) {
;           const f32x2 a = __builtin_amdgcn_cvt_pk_f32_fp8((int)ru[j][c], false), b2 = __builtin_amdgcn_cvt_pk_f32_fp8((int)ru[j][c], true);
;           acc += a.x * hv[c * 4] + a.y * hv[c * 4 + 1] + b2.x * hv[c * 4 + 2] + b2.y * hv[c * 4 + 3];
;         }
;         sj[j] = acc;
;       }
	v_cvt_pk_f32_fp8_sdwa v[130:131], v158 src0_sel:WORD_1
	v_mul_f32_e32 v29, v216, v29
	v_fmac_f32_e32 v29, v214, v28
	v_fmac_f32_e32 v29, v211, v34
	v_fmac_f32_e32 v29, v224, v35
	v_add_f32_e32 v27, v27, v29
	v_cvt_pk_f32_fp8_e32 v[28:29], v133
	v_cvt_pk_f32_fp8_sdwa v[34:35], v133 src0_sel:WORD_1
	v_mul_f32_e32 v29, v221, v29
	v_fmac_f32_e32 v29, v219, v28
	v_fmac_f32_e32 v29, v212, v34
	v_fmac_f32_e32 v29, v213, v35
	v_add_f32_e32 v27, v27, v29
	v_cvt_pk_f32_fp8_e32 v[28:29], v122
	v_cvt_pk_f32_fp8_sdwa v[34:35], v122 src0_sel:WORD_1
	v_mul_f32_e32 v29, v226, v29
	v_fmac_f32_e32 v29, v225, v28
	v_fmac_f32_e32 v29, v220, v34
	v_fmac_f32_e32 v29, v223, v35
	v_add_f32_e32 v36, 0, v29
	v_cvt_pk_f32_fp8_e32 v[28:29], v123
	v_cvt_pk_f32_fp8_sdwa v[34:35], v123 src0_sel:WORD_1
	v_cvt_pk_f32_fp8_sdwa v[122:123], v174 src0_sel:WORD_1
	v_mul_f32_e32 v29, v222, v29
	v_fmac_f32_e32 v29, v218, v28
	v_fmac_f32_e32 v29, v215, v34
	v_fmac_f32_e32 v29, v217, v35
	v_add_f32_e32 v36, v36, v29
	v_cvt_pk_f32_fp8_e32 v[28:29], v124
	v_cvt_pk_f32_fp8_sdwa v[34:35], v124 src0_sel:WORD_1
	v_mul_f32_e32 v29, v216, v29
	v_fmac_f32_e32 v29, v214, v28
	v_fmac_f32_e32 v29, v211, v34
	v_fmac_f32_e32 v29, v224, v35
	v_add_f32_e32 v36, v36, v29
	v_cvt_pk_f32_fp8_e32 v[28:29], v125
	v_cvt_pk_f32_fp8_sdwa v[34:35], v125 src0_sel:WORD_1
	v_mul_f32_e32 v29, v221, v29
	v_fmac_f32_e32 v29, v219, v28
	v_fmac_f32_e32 v29, v212, v34
	v_fmac_f32_e32 v29, v213, v35
	v_cvt_pk_f32_fp8_e32 v[34:35], v114
	v_add_f32_e32 v28, v36, v29
	v_cvt_pk_f32_fp8_sdwa v[36:37], v114 src0_sel:WORD_1
	v_mul_f32_e32 v29, v226, v35
	v_fmac_f32_e32 v29, v225, v34
	v_cvt_pk_f32_fp8_e32 v[34:35], v115
	v_fmac_f32_e32 v29, v220, v36
	v_fmac_f32_e32 v29, v223, v37
	v_cvt_pk_f32_fp8_sdwa v[36:37], v115 src0_sel:WORD_1
	v_mul_f32_e32 v35, v222, v35
	v_fmac_f32_e32 v35, v218, v34
	v_add_f32_e32 v29, 0, v29
	v_fmac_f32_e32 v35, v215, v36
	v_fmac_f32_e32 v35, v217, v37
	v_add_f32_e32 v29, v29, v35
	v_cvt_pk_f32_fp8_e32 v[34:35], v116
	v_cvt_pk_f32_fp8_sdwa v[36:37], v116 src0_sel:WORD_1
	v_mul_f32_e32 v35, v216, v35
	v_fmac_f32_e32 v35, v214, v34
	v_fmac_f32_e32 v35, v211, v36
	v_fmac_f32_e32 v35, v224, v37
	v_add_f32_e32 v29, v29, v35
	v_cvt_pk_f32_fp8_e32 v[34:35], v117
	v_cvt_pk_f32_fp8_sdwa v[36:37], v117 src0_sel:WORD_1
	v_cvt_pk_f32_fp8_e32 v[116:117], v174
	v_mul_f32_e32 v35, v221, v35
	v_fmac_f32_e32 v35, v219, v34
	v_mul_f32_e32 v117, v226, v117
	v_fmac_f32_e32 v117, v225, v116
	v_fmac_f32_e32 v117, v220, v122
	v_fmac_f32_e32 v117, v223, v123
	v_add_f32_e32 v124, 0, v117
	v_cvt_pk_f32_fp8_e32 v[116:117], v175
	v_cvt_pk_f32_fp8_sdwa v[122:123], v175 src0_sel:WORD_1
	v_fmac_f32_e32 v35, v212, v36
	v_fmac_f32_e32 v35, v213, v37
	v_mul_f32_e32 v117, v222, v117
	v_fmac_f32_e32 v117, v218, v116
	v_fmac_f32_e32 v117, v215, v122
	v_fmac_f32_e32 v117, v217, v123
	v_add_f32_e32 v124, v124, v117
	v_cvt_pk_f32_fp8_e32 v[116:117], v176
	v_cvt_pk_f32_fp8_sdwa v[122:123], v176 src0_sel:WORD_1
	v_add_f32_e32 v36, v29, v35
	v_cvt_pk_f32_fp8_e32 v[34:35], v82
	v_mul_f32_e32 v117, v216, v117
	v_fmac_f32_e32 v117, v214, v116
	v_fmac_f32_e32 v117, v211, v122
	v_fmac_f32_e32 v117, v224, v123
	v_add_f32_e32 v124, v124, v117
	v_cvt_pk_f32_fp8_e32 v[116:117], v177
	v_cvt_pk_f32_fp8_sdwa v[122:123], v177 src0_sel:WORD_1
	v_mul_f32_e32 v29, v226, v35
	v_fmac_f32_e32 v29, v225, v34
	v_mul_f32_e32 v117, v221, v117
	v_fmac_f32_e32 v117, v219, v116
	v_fmac_f32_e32 v117, v212, v122
	v_fmac_f32_e32 v117, v213, v123
	v_add_f32_e32 v123, v124, v117
	v_cvt_pk_f32_fp8_e32 v[116:117], v166
	v_cvt_pk_f32_fp8_sdwa v[124:125], v166 src0_sel:WORD_1
	v_cvt_pk_f32_fp8_e32 v[34:35], v83
	v_fmac_f32_e32 v29, v220, v42
	v_mul_f32_e32 v117, v226, v117
	v_fmac_f32_e32 v117, v225, v116
	v_fmac_f32_e32 v117, v220, v124
	v_fmac_f32_e32 v117, v223, v125
	v_add_f32_e32 v122, 0, v117
	v_cvt_pk_f32_fp8_e32 v[116:117], v167
	v_cvt_pk_f32_fp8_sdwa v[124:125], v167 src0_sel:WORD_1
	v_fmac_f32_e32 v29, v223, v43
	v_cvt_pk_f32_fp8_sdwa v[42:43], v83 src0_sel:WORD_1
	v_mul_f32_e32 v117, v222, v117
	v_fmac_f32_e32 v117, v218, v116
	v_fmac_f32_e32 v117, v215, v124
	v_fmac_f32_e32 v117, v217, v125
	v_add_f32_e32 v122, v122, v117
	v_cvt_pk_f32_fp8_e32 v[116:117], v168
	v_cvt_pk_f32_fp8_sdwa v[124:125], v168 src0_sel:WORD_1
	v_mul_f32_e32 v35, v222, v35
	v_fmac_f32_e32 v35, v218, v34
	v_mul_f32_e32 v117, v216, v117
	v_fmac_f32_e32 v117, v214, v116
	v_fmac_f32_e32 v117, v211, v124
	v_fmac_f32_e32 v117, v224, v125
	v_add_f32_e32 v122, v122, v117
	v_cvt_pk_f32_fp8_e32 v[116:117], v169
	v_cvt_pk_f32_fp8_sdwa v[124:125], v169 src0_sel:WORD_1
	v_fmac_f32_e32 v35, v215, v42
	v_add_f32_e32 v29, 0, v29
	v_mul_f32_e32 v117, v221, v117
	v_fmac_f32_e32 v117, v219, v116
	v_fmac_f32_e32 v117, v212, v124
	v_fmac_f32_e32 v117, v213, v125
	v_cvt_pk_f32_fp8_e32 v[124:125], v158
	v_add_f32_e32 v116, v122, v117
	v_fmac_f32_e32 v35, v217, v43
	v_add_f32_e32 v29, v29, v35
	v_mul_f32_e32 v117, v226, v125
	v_fmac_f32_e32 v117, v225, v124
	v_cvt_pk_f32_fp8_e32 v[124:125], v159
	v_fmac_f32_e32 v117, v220, v130
	v_fmac_f32_e32 v117, v223, v131
	v_cvt_pk_f32_fp8_sdwa v[130:131], v159 src0_sel:WORD_1
	v_mul_f32_e32 v122, v222, v125
	v_fmac_f32_e32 v122, v218, v124
	v_cvt_pk_f32_fp8_e32 v[124:125], v160
	v_fmac_f32_e32 v122, v215, v130
	v_fmac_f32_e32 v122, v217, v131
	v_cvt_pk_f32_fp8_sdwa v[130:131], v160 src0_sel:WORD_1
	v_add_f32_e32 v117, 0, v117
	v_add_f32_e32 v117, v117, v122
	v_mul_f32_e32 v122, v216, v125
	v_fmac_f32_e32 v122, v214, v124
	v_cvt_pk_f32_fp8_e32 v[124:125], v161
	v_fmac_f32_e32 v122, v211, v130
	v_fmac_f32_e32 v122, v224, v131
	v_cvt_pk_f32_fp8_sdwa v[130:131], v161 src0_sel:WORD_1
	v_add_f32_e32 v117, v117, v122
	v_mul_f32_e32 v122, v221, v125
	v_fmac_f32_e32 v122, v219, v124
	s_waitcnt vmcnt(11)
; __device__ void phase_experts(const Params& p, int l) {
;     ...
; #pragma unroll
;       for (int j = 0; j < 16; ++j) {
;         float acc = 0.f;
; #pragma unroll
;         for (int c = 0; c < 4; ++c) {
;           const f32x2 a = __builtin_amdgcn_cvt_pk_f32_fp8((int)ru[j][c], false), b2 = __builtin_amdgcn_cvt_pk_f32_fp8((int)ru[j][c], true);
;           acc += a.x * hv[c * 4] + a.y * hv[c * 4 + 1] + b2.x * hv[c * 4 + 2] + b2.y * hv[c * 4 + 3];
;         }
;         sj[j] = acc;
;       }
	v_cvt_pk_f32_fp8_e32 v[124:125], v150
	v_fmac_f32_e32 v122, v212, v130
	v_fmac_f32_e32 v122, v213, v131
	v_cvt_pk_f32_fp8_sdwa v[130:131], v150 src0_sel:WORD_1
	v_add_f32_e32 v117, v117, v122
	v_mul_f32_e32 v122, v226, v125
	v_fmac_f32_e32 v122, v225, v124
	v_cvt_pk_f32_fp8_e32 v[124:125], v151
	v_fmac_f32_e32 v122, v220, v130
	v_fmac_f32_e32 v122, v223, v131
	v_cvt_pk_f32_fp8_sdwa v[130:131], v151 src0_sel:WORD_1
	v_mul_f32_e32 v125, v222, v125
	v_fmac_f32_e32 v125, v218, v124
	v_add_f32_e32 v122, 0, v122
	v_fmac_f32_e32 v125, v215, v130
	v_fmac_f32_e32 v125, v217, v131
	v_add_f32_e32 v122, v122, v125
	v_cvt_pk_f32_fp8_e32 v[124:125], v152
	v_cvt_pk_f32_fp8_sdwa v[130:131], v152 src0_sel:WORD_1
	v_cvt_pk_f32_fp8_e32 v[34:35], v84
	v_cvt_pk_f32_fp8_sdwa v[42:43], v84 src0_sel:WORD_1
	v_mul_f32_e32 v125, v216, v125
	v_fmac_f32_e32 v125, v214, v124
	v_fmac_f32_e32 v125, v211, v130
	v_fmac_f32_e32 v125, v224, v131
	v_add_f32_e32 v122, v122, v125
	v_cvt_pk_f32_fp8_e32 v[124:125], v153
	v_cvt_pk_f32_fp8_sdwa v[130:131], v153 src0_sel:WORD_1
	v_mul_f32_e32 v35, v216, v35
	v_fmac_f32_e32 v35, v214, v34
	v_mul_f32_e32 v125, v221, v125
	v_fmac_f32_e32 v125, v219, v124
	v_fmac_f32_e32 v125, v212, v130
	v_fmac_f32_e32 v125, v213, v131
	v_add_f32_e32 v122, v122, v125
	s_waitcnt vmcnt(10)
	v_cvt_pk_f32_fp8_e32 v[124:125], v142
	v_cvt_pk_f32_fp8_sdwa v[130:131], v142 src0_sel:WORD_1
	v_fmac_f32_e32 v35, v211, v42
	v_fmac_f32_e32 v35, v224, v43
	v_mul_f32_e32 v125, v226, v125
	v_fmac_f32_e32 v125, v225, v124
	v_fmac_f32_e32 v125, v220, v130
	v_fmac_f32_e32 v125, v223, v131
	v_add_f32_e32 v132, 0, v125
	v_cvt_pk_f32_fp8_e32 v[124:125], v143
	v_cvt_pk_f32_fp8_sdwa v[130:131], v143 src0_sel:WORD_1
	v_add_f32_e32 v29, v29, v35
	v_cvt_pk_f32_fp8_e32 v[34:35], v85
	v_mul_f32_e32 v125, v222, v125
	v_fmac_f32_e32 v125, v218, v124
	v_fmac_f32_e32 v125, v215, v130
	v_fmac_f32_e32 v125, v217, v131
	v_add_f32_e32 v132, v132, v125
	v_cvt_pk_f32_fp8_e32 v[124:125], v144
	v_cvt_pk_f32_fp8_sdwa v[130:131], v144 src0_sel:WORD_1
	v_cvt_pk_f32_fp8_sdwa v[42:43], v85 src0_sel:WORD_1
	v_mul_f32_e32 v35, v221, v35
	v_mul_f32_e32 v125, v216, v125
	v_fmac_f32_e32 v125, v214, v124
	v_fmac_f32_e32 v35, v219, v34
	v_fmac_f32_e32 v125, v211, v130
	v_fmac_f32_e32 v35, v212, v42
	v_fmac_f32_e32 v125, v224, v131
	v_fmac_f32_e32 v35, v213, v43
	v_add_f32_e32 v132, v132, v125
	v_cvt_pk_f32_fp8_e32 v[124:125], v145
	v_add_f32_e32 v29, v29, v35
	v_cvt_pk_f32_fp8_e32 v[34:35], v70
	v_cvt_pk_f32_fp8_sdwa v[130:131], v145 src0_sel:WORD_1
	v_cvt_pk_f32_fp8_sdwa v[42:43], v70 src0_sel:WORD_1
	v_mul_f32_e32 v125, v221, v125
	v_mul_f32_e32 v35, v226, v35
	v_fmac_f32_e32 v125, v219, v124
	v_fmac_f32_e32 v35, v225, v34
	v_fmac_f32_e32 v125, v212, v130
	v_fmac_f32_e32 v35, v220, v42
	v_fmac_f32_e32 v125, v213, v131
	s_waitcnt vmcnt(9)
	v_cvt_pk_f32_fp8_e32 v[130:131], v134
	v_fmac_f32_e32 v35, v223, v43
	v_add_f32_e32 v37, 0, v35
	v_cvt_pk_f32_fp8_e32 v[34:35], v71
	v_add_f32_e32 v124, v132, v125
	v_cvt_pk_f32_fp8_sdwa v[132:133], v134 src0_sel:WORD_1
	v_cvt_pk_f32_fp8_sdwa v[42:43], v71 src0_sel:WORD_1
	v_mul_f32_e32 v125, v226, v131
	v_fmac_f32_e32 v125, v225, v130
	v_cvt_pk_f32_fp8_e32 v[130:131], v135
	v_mul_f32_e32 v35, v222, v35
	v_fmac_f32_e32 v125, v220, v132
	v_fmac_f32_e32 v35, v218, v34
	v_fmac_f32_e32 v125, v223, v133
	v_cvt_pk_f32_fp8_sdwa v[132:133], v135 src0_sel:WORD_1
	v_fmac_f32_e32 v35, v215, v42
	v_fmac_f32_e32 v35, v217, v43
	v_mul_f32_e32 v131, v222, v131
	v_add_f32_e32 v37, v37, v35
	v_cvt_pk_f32_fp8_e32 v[34:35], v72
	v_fmac_f32_e32 v131, v218, v130
	v_fmac_f32_e32 v131, v215, v132
	v_cvt_pk_f32_fp8_sdwa v[42:43], v72 src0_sel:WORD_1
	v_add_f32_e32 v125, 0, v125
	v_fmac_f32_e32 v131, v217, v133
	v_add_f32_e32 v125, v125, v131
	v_cvt_pk_f32_fp8_e32 v[130:131], v136
	v_mul_f32_e32 v35, v216, v35
	v_fmac_f32_e32 v35, v214, v34
	v_cvt_pk_f32_fp8_sdwa v[132:133], v136 src0_sel:WORD_1
	v_fmac_f32_e32 v35, v211, v42
	v_fmac_f32_e32 v35, v224, v43
	v_mul_f32_e32 v131, v216, v131
	v_add_f32_e32 v37, v37, v35
	v_cvt_pk_f32_fp8_e32 v[34:35], v73
	v_fmac_f32_e32 v131, v214, v130
	v_fmac_f32_e32 v131, v211, v132
	v_cvt_pk_f32_fp8_sdwa v[42:43], v73 src0_sel:WORD_1
	v_fmac_f32_e32 v131, v224, v133
	v_add_f32_e32 v125, v125, v131
	v_cvt_pk_f32_fp8_e32 v[130:131], v137
	v_mul_f32_e32 v35, v221, v35
	v_fmac_f32_e32 v35, v219, v34
	v_cvt_pk_f32_fp8_sdwa v[132:133], v137 src0_sel:WORD_1
	v_fmac_f32_e32 v35, v212, v42
	v_fmac_f32_e32 v35, v213, v43
	v_cvt_pk_f32_fp8_e32 v[42:43], v62
	v_mul_f32_e32 v131, v221, v131
	v_fmac_f32_e32 v131, v219, v130
	v_fmac_f32_e32 v131, v212, v132
	v_fmac_f32_e32 v131, v213, v133
	v_add_f32_e32 v34, v37, v35
	v_mul_f32_e32 v35, v226, v43
	v_add_f32_e32 v125, v125, v131
	s_waitcnt vmcnt(8)
; __device__ void phase_experts(const Params& p, int l) {
;     ...
; #pragma unroll
;       for (int j = 0; j < 16; ++j) {
;         float acc = 0.f;
; #pragma unroll
;         for (int c = 0; c < 4; ++c) {
;           const f32x2 a = __builtin_amdgcn_cvt_pk_f32_fp8((int)ru[j][c], false), b2 = __builtin_amdgcn_cvt_pk_f32_fp8((int)ru[j][c], true);
;           acc += a.x * hv[c * 4] + a.y * hv[c * 4 + 1] + b2.x * hv[c * 4 + 2] + b2.y * hv[c * 4 + 3];
;         }
;         sj[j] = acc;
;       }
	v_cvt_pk_f32_fp8_e32 v[130:131], v126
	v_fmac_f32_e32 v35, v225, v42
	v_cvt_pk_f32_fp8_e32 v[42:43], v63
	v_fmac_f32_e32 v35, v220, v44
	v_cvt_pk_f32_fp8_sdwa v[132:133], v126 src0_sel:WORD_1
	v_fmac_f32_e32 v35, v223, v45
	v_cvt_pk_f32_fp8_sdwa v[44:45], v63 src0_sel:WORD_1
	v_mul_f32_e32 v126, v226, v131
	v_mul_f32_e32 v37, v222, v43
	v_fmac_f32_e32 v126, v225, v130
	v_fmac_f32_e32 v37, v218, v42
	v_cvt_pk_f32_fp8_e32 v[42:43], v64
	v_fmac_f32_e32 v126, v220, v132
	v_cvt_pk_f32_fp8_e32 v[130:131], v127
	v_fmac_f32_e32 v37, v215, v44
	v_fmac_f32_e32 v126, v223, v133
	v_fmac_f32_e32 v37, v217, v45
	v_cvt_pk_f32_fp8_sdwa v[44:45], v64 src0_sel:WORD_1
	v_add_f32_e32 v132, 0, v126
	v_cvt_pk_f32_fp8_sdwa v[126:127], v127 src0_sel:WORD_1
	v_add_f32_e32 v35, 0, v35
	v_add_f32_e32 v35, v35, v37
	v_mul_f32_e32 v37, v216, v43
	v_mul_f32_e32 v131, v222, v131
	v_fmac_f32_e32 v37, v214, v42
	v_cvt_pk_f32_fp8_e32 v[42:43], v65
	v_fmac_f32_e32 v131, v218, v130
	v_fmac_f32_e32 v37, v211, v44
	v_fmac_f32_e32 v131, v215, v126
	v_fmac_f32_e32 v37, v224, v45
	v_cvt_pk_f32_fp8_sdwa v[44:45], v65 src0_sel:WORD_1
	v_fmac_f32_e32 v131, v217, v127
	v_cvt_pk_f32_fp8_e32 v[126:127], v128
	v_add_f32_e32 v35, v35, v37
	v_mul_f32_e32 v37, v221, v43
	v_add_f32_e32 v132, v132, v131
	v_cvt_pk_f32_fp8_sdwa v[130:131], v128 src0_sel:WORD_1
	v_fmac_f32_e32 v37, v219, v42
	v_cvt_pk_f32_fp8_e32 v[42:43], v54
	v_fmac_f32_e32 v37, v212, v44
	v_mul_f32_e32 v127, v216, v127
	v_fmac_f32_e32 v37, v213, v45
	v_cvt_pk_f32_fp8_sdwa v[44:45], v54 src0_sel:WORD_1
	v_fmac_f32_e32 v127, v214, v126
	v_fmac_f32_e32 v127, v211, v130
	v_add_f32_e32 v35, v35, v37
	v_mul_f32_e32 v37, v226, v43
	v_fmac_f32_e32 v127, v224, v131
	v_fmac_f32_e32 v37, v225, v42
	v_cvt_pk_f32_fp8_e32 v[42:43], v55
	v_add_f32_e32 v130, v132, v127
	v_cvt_pk_f32_fp8_e32 v[126:127], v129
	v_fmac_f32_e32 v37, v220, v44
	v_fmac_f32_e32 v37, v223, v45
	v_cvt_pk_f32_fp8_sdwa v[44:45], v55 src0_sel:WORD_1
	v_cvt_pk_f32_fp8_sdwa v[128:129], v129 src0_sel:WORD_1
	v_mul_f32_e32 v43, v222, v43
	v_mul_f32_e32 v127, v221, v127
	v_fmac_f32_e32 v43, v218, v42
	v_fmac_f32_e32 v127, v219, v126
	v_fmac_f32_e32 v43, v215, v44
	v_fmac_f32_e32 v127, v212, v128
	v_add_f32_e32 v37, 0, v37
	v_fmac_f32_e32 v43, v217, v45
	v_fmac_f32_e32 v127, v213, v129
	s_waitcnt vmcnt(7)
	v_cvt_pk_f32_fp8_e32 v[128:129], v118
	v_add_f32_e32 v37, v37, v43
	v_cvt_pk_f32_fp8_e32 v[42:43], v56
	v_add_f32_e32 v126, v130, v127
	v_cvt_pk_f32_fp8_sdwa v[130:131], v118 src0_sel:WORD_1
	v_cvt_pk_f32_fp8_sdwa v[44:45], v56 src0_sel:WORD_1
	v_mul_f32_e32 v118, v226, v129
	v_mul_f32_e32 v43, v216, v43
	v_fmac_f32_e32 v118, v225, v128
	v_fmac_f32_e32 v43, v214, v42
	v_fmac_f32_e32 v118, v220, v130
	v_cvt_pk_f32_fp8_e32 v[128:129], v119
	v_fmac_f32_e32 v43, v211, v44
	v_fmac_f32_e32 v118, v223, v131
	v_fmac_f32_e32 v43, v224, v45
	v_add_f32_e32 v127, 0, v118
	v_cvt_pk_f32_fp8_sdwa v[118:119], v119 src0_sel:WORD_1
	v_add_f32_e32 v37, v37, v43
	v_cvt_pk_f32_fp8_e32 v[42:43], v57
	v_mul_f32_e32 v129, v222, v129
	v_cvt_pk_f32_fp8_sdwa v[44:45], v57 src0_sel:WORD_1
	v_fmac_f32_e32 v129, v218, v128
	v_fmac_f32_e32 v129, v215, v118
	v_mul_f32_e32 v43, v221, v43
	v_fmac_f32_e32 v129, v217, v119
	v_cvt_pk_f32_fp8_e32 v[118:119], v120
	v_fmac_f32_e32 v43, v219, v42
	v_fmac_f32_e32 v43, v212, v44
	v_add_f32_e32 v127, v127, v129
	v_cvt_pk_f32_fp8_sdwa v[128:129], v120 src0_sel:WORD_1
	v_fmac_f32_e32 v43, v213, v45
	v_add_f32_e32 v37, v37, v43
	v_cvt_pk_f32_fp8_e32 v[42:43], v46
	v_mul_f32_e32 v119, v216, v119
	v_fmac_f32_e32 v119, v214, v118
	v_cvt_pk_f32_fp8_sdwa v[44:45], v46 src0_sel:WORD_1
	v_fmac_f32_e32 v119, v211, v128
	v_fmac_f32_e32 v119, v224, v129
	v_mul_f32_e32 v43, v226, v43
	v_add_f32_e32 v127, v127, v119
	v_cvt_pk_f32_fp8_e32 v[118:119], v121
	v_fmac_f32_e32 v43, v225, v42
	v_fmac_f32_e32 v43, v220, v44
	v_cvt_pk_f32_fp8_sdwa v[120:121], v121 src0_sel:WORD_1
	v_fmac_f32_e32 v43, v223, v45
	v_add_f32_e32 v46, 0, v43
	v_cvt_pk_f32_fp8_e32 v[42:43], v47
	v_mul_f32_e32 v119, v221, v119
	v_fmac_f32_e32 v119, v219, v118
	v_cvt_pk_f32_fp8_sdwa v[44:45], v47 src0_sel:WORD_1
	v_fmac_f32_e32 v119, v212, v120
	v_fmac_f32_e32 v119, v213, v121
	s_waitcnt vmcnt(5)
	v_cvt_pk_f32_fp8_e32 v[120:121], v110
	v_mul_f32_e32 v43, v222, v43
	v_fmac_f32_e32 v43, v218, v42
	v_cvt_pk_f32_fp8_sdwa v[128:129], v110 src0_sel:WORD_1
	v_fmac_f32_e32 v43, v215, v44
	v_fmac_f32_e32 v43, v217, v45
	v_mul_f32_e32 v110, v226, v121
	v_add_f32_e32 v46, v46, v43
	v_cvt_pk_f32_fp8_e32 v[42:43], v48
	v_fmac_f32_e32 v110, v225, v120
	v_fmac_f32_e32 v110, v220, v128
	v_cvt_pk_f32_fp8_e32 v[120:121], v111
	v_cvt_pk_f32_fp8_sdwa v[44:45], v48 src0_sel:WORD_1
	v_fmac_f32_e32 v110, v223, v129
	v_add_f32_e32 v118, v127, v119
	v_add_f32_e32 v119, 0, v110
	v_cvt_pk_f32_fp8_sdwa v[110:111], v111 src0_sel:WORD_1
	v_mul_f32_e32 v43, v216, v43
	v_fmac_f32_e32 v43, v214, v42
	v_mul_f32_e32 v121, v222, v121
	v_fmac_f32_e32 v43, v211, v44
	v_fmac_f32_e32 v121, v218, v120
	v_fmac_f32_e32 v43, v224, v45
	v_fmac_f32_e32 v121, v215, v110
	v_add_f32_e32 v46, v46, v43
	v_cvt_pk_f32_fp8_e32 v[42:43], v49
	v_fmac_f32_e32 v121, v217, v111
	v_cvt_pk_f32_fp8_e32 v[110:111], v112
	v_cvt_pk_f32_fp8_sdwa v[44:45], v49 src0_sel:WORD_1
	v_add_f32_e32 v119, v119, v121
	v_cvt_pk_f32_fp8_sdwa v[120:121], v112 src0_sel:WORD_1
	v_mul_f32_e32 v43, v221, v43
	v_mul_f32_e32 v111, v216, v111
	v_fmac_f32_e32 v43, v219, v42
	v_fmac_f32_e32 v111, v214, v110
	v_fmac_f32_e32 v43, v212, v44
	v_fmac_f32_e32 v111, v211, v120
	v_fmac_f32_e32 v43, v213, v45
	v_cvt_pk_f32_fp8_e32 v[44:45], v38
	v_fmac_f32_e32 v111, v224, v121
	v_add_f32_e32 v119, v119, v111
	v_cvt_pk_f32_fp8_e32 v[110:111], v113
	v_add_f32_e32 v42, v46, v43
	v_cvt_pk_f32_fp8_sdwa v[46:47], v38 src0_sel:WORD_1
	v_cvt_pk_f32_fp8_sdwa v[112:113], v113 src0_sel:WORD_1
	v_mul_f32_e32 v38, v226, v45
	v_fmac_f32_e32 v38, v225, v44
	v_mul_f32_e32 v111, v221, v111
	v_fmac_f32_e32 v38, v220, v46
	v_cvt_pk_f32_fp8_e32 v[44:45], v39
	v_fmac_f32_e32 v111, v219, v110
	v_fmac_f32_e32 v38, v223, v47
	v_fmac_f32_e32 v111, v212, v112
	v_add_f32_e32 v43, 0, v38
	v_cvt_pk_f32_fp8_sdwa v[38:39], v39 src0_sel:WORD_1
	v_fmac_f32_e32 v111, v213, v113
	s_waitcnt vmcnt(4)
; __device__ void phase_experts(const Params& p, int l) {
;     ...
; #pragma unroll
;       for (int j = 0; j < 16; ++j) {
;         float acc = 0.f;
; #pragma unroll
;         for (int c = 0; c < 4; ++c) {
;           const f32x2 a = __builtin_amdgcn_cvt_pk_f32_fp8((int)ru[j][c], false), b2 = __builtin_amdgcn_cvt_pk_f32_fp8((int)ru[j][c], true);
;           acc += a.x * hv[c * 4] + a.y * hv[c * 4 + 1] + b2.x * hv[c * 4 + 2] + b2.y * hv[c * 4 + 3];
;         }
;         sj[j] = acc;
;       }
; #pragma unroll
;       for (int hw = 8; hw >= 1; hw >>= 1) {
;         const bool up = (lane & hw) != 0;
; #pragma unroll
;         for (int k = 0; k < hw; ++k) {
;           const float send = up ? sj[k] : sj[k + hw], keep = up ? sj[k + hw] : sj[k];
;           sj[k] = keep + __shfl_xor(send, hw);
;         }
;       }
	v_cvt_pk_f32_fp8_e32 v[112:113], v106
	v_mul_f32_e32 v45, v222, v45
	v_cvt_pk_f32_fp8_sdwa v[120:121], v106 src0_sel:WORD_1
	v_fmac_f32_e32 v45, v218, v44
	v_fmac_f32_e32 v45, v215, v38
	v_mul_f32_e32 v106, v226, v113
	v_fmac_f32_e32 v45, v217, v39
	v_cvt_pk_f32_fp8_e32 v[38:39], v40
	v_fmac_f32_e32 v106, v225, v112
	v_fmac_f32_e32 v106, v220, v120
	v_cvt_pk_f32_fp8_e32 v[112:113], v107
	v_add_f32_e32 v43, v43, v45
	v_cvt_pk_f32_fp8_sdwa v[44:45], v40 src0_sel:WORD_1
	v_fmac_f32_e32 v106, v223, v121
	v_add_f32_e32 v110, v119, v111
	v_add_f32_e32 v111, 0, v106
	v_cvt_pk_f32_fp8_sdwa v[106:107], v107 src0_sel:WORD_1
	v_mul_f32_e32 v39, v216, v39
	v_fmac_f32_e32 v39, v214, v38
	v_mul_f32_e32 v113, v222, v113
	v_fmac_f32_e32 v39, v211, v44
	v_fmac_f32_e32 v113, v218, v112
	v_fmac_f32_e32 v39, v224, v45
	v_fmac_f32_e32 v113, v215, v106
	v_add_f32_e32 v43, v43, v39
	v_cvt_pk_f32_fp8_e32 v[38:39], v41
	v_fmac_f32_e32 v113, v217, v107
	v_cvt_pk_f32_fp8_e32 v[106:107], v108
	v_cvt_pk_f32_fp8_sdwa v[40:41], v41 src0_sel:WORD_1
	v_add_f32_e32 v111, v111, v113
	v_cvt_pk_f32_fp8_sdwa v[112:113], v108 src0_sel:WORD_1
	v_mul_f32_e32 v39, v221, v39
	v_mul_f32_e32 v107, v216, v107
	v_fmac_f32_e32 v39, v219, v38
	v_fmac_f32_e32 v107, v214, v106
	v_fmac_f32_e32 v39, v212, v40
	v_cndmask_b32_e32 v38, v21, v36, vcc
	v_fmac_f32_e32 v107, v211, v112
	v_fmac_f32_e32 v39, v213, v41
	v_cndmask_b32_e32 v21, v36, v21, vcc
	ds_bpermute_b32 v36, v205, v38
	v_fmac_f32_e32 v107, v224, v113
	v_add_f32_e32 v40, v43, v39
	v_cvt_pk_f32_fp8_e32 v[38:39], v30
	v_add_f32_e32 v111, v111, v107
	v_cvt_pk_f32_fp8_e32 v[106:107], v109
	v_cvt_pk_f32_fp8_sdwa v[108:109], v109 src0_sel:WORD_1
	s_waitcnt lgkmcnt(0)
	v_add_f32_e32 v21, v21, v36
	v_mul_f32_e32 v36, v226, v39
	v_mul_f32_e32 v107, v221, v107
	v_fmac_f32_e32 v36, v225, v38
	v_cvt_pk_f32_fp8_sdwa v[38:39], v30 src0_sel:WORD_1
	v_fmac_f32_e32 v107, v219, v106
	v_fmac_f32_e32 v107, v212, v108
	v_fmac_f32_e32 v107, v213, v109
	s_waitcnt vmcnt(3)
	v_cvt_pk_f32_fp8_e32 v[108:109], v102
	v_fmac_f32_e32 v36, v220, v38
	v_cvt_pk_f32_fp8_sdwa v[112:113], v102 src0_sel:WORD_1
	v_fmac_f32_e32 v36, v223, v39
	v_cvt_pk_f32_fp8_e32 v[38:39], v31
	v_mul_f32_e32 v102, v226, v109
	v_cvt_pk_f32_fp8_sdwa v[30:31], v31 src0_sel:WORD_1
	v_fmac_f32_e32 v102, v225, v108
	v_fmac_f32_e32 v102, v220, v112
	v_cvt_pk_f32_fp8_e32 v[108:109], v103
	v_mul_f32_e32 v39, v222, v39
	v_fmac_f32_e32 v102, v223, v113
	v_fmac_f32_e32 v39, v218, v38
	v_add_f32_e32 v106, v111, v107
	v_add_f32_e32 v107, 0, v102
	v_cvt_pk_f32_fp8_sdwa v[102:103], v103 src0_sel:WORD_1
	v_fmac_f32_e32 v39, v215, v30
	v_fmac_f32_e32 v39, v217, v31
	v_cvt_pk_f32_fp8_e32 v[30:31], v32
	v_mul_f32_e32 v109, v222, v109
	v_fmac_f32_e32 v109, v218, v108
	v_fmac_f32_e32 v109, v215, v102
	v_fmac_f32_e32 v109, v217, v103
	v_cvt_pk_f32_fp8_e32 v[102:103], v104
	v_mul_f32_e32 v38, v216, v31
	v_fmac_f32_e32 v38, v214, v30
	v_cvt_pk_f32_fp8_sdwa v[30:31], v32 src0_sel:WORD_1
	v_add_f32_e32 v107, v107, v109
	v_cvt_pk_f32_fp8_sdwa v[108:109], v104 src0_sel:WORD_1
	v_mul_f32_e32 v103, v216, v103
	v_fmac_f32_e32 v103, v214, v102
	v_fmac_f32_e32 v38, v211, v30
	v_fmac_f32_e32 v103, v211, v108
	v_fmac_f32_e32 v38, v224, v31
	v_cvt_pk_f32_fp8_e32 v[30:31], v33
	v_fmac_f32_e32 v103, v224, v109
	v_add_f32_e32 v107, v107, v103
	v_cvt_pk_f32_fp8_e32 v[102:103], v105
	v_add_f32_e32 v36, 0, v36
	v_add_f32_e32 v36, v36, v39
	v_cvt_pk_f32_fp8_sdwa v[104:105], v105 src0_sel:WORD_1
	v_add_f32_e32 v32, v36, v38
	v_mul_f32_e32 v36, v221, v31
	v_fmac_f32_e32 v36, v219, v30
	v_cvt_pk_f32_fp8_sdwa v[30:31], v33 src0_sel:WORD_1
	v_mul_f32_e32 v103, v221, v103
	v_fmac_f32_e32 v103, v219, v102
	v_fmac_f32_e32 v103, v212, v104
	v_fmac_f32_e32 v103, v213, v105
	s_waitcnt vmcnt(2)
	v_cvt_pk_f32_fp8_e32 v[104:105], v98
	v_fmac_f32_e32 v36, v212, v30
	v_fmac_f32_e32 v36, v213, v31
	v_cvt_pk_f32_fp8_e32 v[30:31], v22
	v_cvt_pk_f32_fp8_sdwa v[108:109], v98 src0_sel:WORD_1
	v_mul_f32_e32 v98, v226, v105
	v_fmac_f32_e32 v98, v225, v104
	v_mul_f32_e32 v33, v226, v31
	v_fmac_f32_e32 v98, v220, v108
	v_cvt_pk_f32_fp8_e32 v[104:105], v99
	v_fmac_f32_e32 v33, v225, v30
	v_cvt_pk_f32_fp8_sdwa v[30:31], v22 src0_sel:WORD_1
	v_fmac_f32_e32 v98, v223, v109
	v_add_f32_e32 v102, v107, v103
	v_add_f32_e32 v103, 0, v98
	v_cvt_pk_f32_fp8_sdwa v[98:99], v99 src0_sel:WORD_1
	v_mul_f32_e32 v105, v222, v105
	v_fmac_f32_e32 v33, v220, v30
	v_fmac_f32_e32 v105, v218, v104
	v_fmac_f32_e32 v33, v223, v31
	v_cvt_pk_f32_fp8_e32 v[30:31], v23
	v_fmac_f32_e32 v105, v215, v98
	v_fmac_f32_e32 v105, v217, v99
	v_cvt_pk_f32_fp8_e32 v[98:99], v100
	v_cvt_pk_f32_fp8_sdwa v[22:23], v23 src0_sel:WORD_1
	v_add_f32_e32 v103, v103, v105
	v_cvt_pk_f32_fp8_sdwa v[104:105], v100 src0_sel:WORD_1
	v_mul_f32_e32 v31, v222, v31
	v_fmac_f32_e32 v31, v218, v30
	v_mul_f32_e32 v99, v216, v99
	v_fmac_f32_e32 v31, v215, v22
	v_fmac_f32_e32 v99, v214, v98
	v_fmac_f32_e32 v31, v217, v23
	v_cvt_pk_f32_fp8_e32 v[22:23], v24
	v_fmac_f32_e32 v99, v211, v104
	v_fmac_f32_e32 v99, v224, v105
	v_add_f32_e32 v103, v103, v99
	v_cvt_pk_f32_fp8_e32 v[98:99], v101
	v_add_f32_e32 v33, 0, v33
	v_add_f32_e32 v30, v33, v31
	v_mul_f32_e32 v31, v216, v23
	v_cvt_pk_f32_fp8_sdwa v[100:101], v101 src0_sel:WORD_1
	v_fmac_f32_e32 v31, v214, v22
	v_cvt_pk_f32_fp8_sdwa v[22:23], v24 src0_sel:WORD_1
	v_mul_f32_e32 v99, v221, v99
	v_fmac_f32_e32 v99, v219, v98
	v_fmac_f32_e32 v99, v212, v100
	v_fmac_f32_e32 v31, v211, v22
	v_fmac_f32_e32 v99, v213, v101
	s_waitcnt vmcnt(1)
; __device__ void phase_experts(const Params& p, int l) {
;     ...
; #pragma unroll
;       for (int j = 0; j < 16; ++j) {
;         float acc = 0.f;
; #pragma unroll
;         for (int c = 0; c < 4; ++c) {
;           const f32x2 a = __builtin_amdgcn_cvt_pk_f32_fp8((int)ru[j][c], false), b2 = __builtin_amdgcn_cvt_pk_f32_fp8((int)ru[j][c], true);
;           acc += a.x * hv[c * 4] + a.y * hv[c * 4 + 1] + b2.x * hv[c * 4 + 2] + b2.y * hv[c * 4 + 3];
;         }
;         sj[j] = acc;
;       }
; #pragma unroll
;       for (int hw = 8; hw >= 1; hw >>= 1) {
;         const bool up = (lane & hw) != 0;
; #pragma unroll
;         for (int k = 0; k < hw; ++k) {
;           const float send = up ? sj[k] : sj[k + hw], keep = up ? sj[k + hw] : sj[k];
;           sj[k] = keep + __shfl_xor(send, hw);
;         }
;       }
	v_cvt_pk_f32_fp8_e32 v[100:101], v94
	v_fmac_f32_e32 v31, v224, v23
	v_cvt_pk_f32_fp8_e32 v[22:23], v25
	v_cvt_pk_f32_fp8_sdwa v[104:105], v94 src0_sel:WORD_1
	v_mul_f32_e32 v94, v226, v101
	v_add_f32_e32 v24, v30, v31
	v_mul_f32_e32 v30, v221, v23
	v_fmac_f32_e32 v94, v225, v100
	v_fmac_f32_e32 v30, v219, v22
	v_cvt_pk_f32_fp8_sdwa v[22:23], v25 src0_sel:WORD_1
	v_fmac_f32_e32 v94, v220, v104
	v_cvt_pk_f32_fp8_e32 v[100:101], v95
	v_fmac_f32_e32 v94, v223, v105
	v_add_f32_e32 v98, v103, v99
	v_add_f32_e32 v99, 0, v94
	v_cvt_pk_f32_fp8_sdwa v[94:95], v95 src0_sel:WORD_1
	v_fmac_f32_e32 v30, v212, v22
	v_mul_f32_e32 v101, v222, v101
	v_fmac_f32_e32 v30, v213, v23
	v_fmac_f32_e32 v101, v218, v100
	v_add_f32_e32 v32, v32, v36
	v_add_f32_e32 v22, v24, v30
	v_fmac_f32_e32 v101, v215, v94
	v_cndmask_b32_e32 v23, v22, v32, vcc
	v_fmac_f32_e32 v101, v217, v95
	v_cvt_pk_f32_fp8_e32 v[94:95], v96
	ds_bpermute_b32 v23, v205, v23
	v_add_f32_e32 v99, v99, v101
	v_cvt_pk_f32_fp8_sdwa v[100:101], v96 src0_sel:WORD_1
	v_mul_f32_e32 v95, v216, v95
	v_cndmask_b32_e32 v22, v32, v22, vcc
	v_fmac_f32_e32 v95, v214, v94
	s_waitcnt lgkmcnt(0)
	v_add_f32_e32 v22, v22, v23
	v_cndmask_b32_e32 v23, v18, v29, vcc
	v_fmac_f32_e32 v95, v211, v100
	ds_bpermute_b32 v23, v205, v23
	v_fmac_f32_e32 v95, v224, v101
	v_add_f32_e32 v99, v99, v95
	v_cvt_pk_f32_fp8_e32 v[94:95], v97
	v_cvt_pk_f32_fp8_sdwa v[96:97], v97 src0_sel:WORD_1
	v_cndmask_b32_e32 v18, v29, v18, vcc
	s_waitcnt lgkmcnt(0)
	v_add_f32_e32 v18, v18, v23
	v_cndmask_b32_e32 v23, v19, v34, vcc
	v_mul_f32_e32 v95, v221, v95
	ds_bpermute_b32 v23, v205, v23
	v_fmac_f32_e32 v95, v219, v94
	v_fmac_f32_e32 v95, v212, v96
	v_fmac_f32_e32 v95, v213, v97
	s_waitcnt vmcnt(0)
	v_cvt_pk_f32_fp8_e32 v[96:97], v90
	v_cndmask_b32_e32 v19, v34, v19, vcc
	v_cvt_pk_f32_fp8_sdwa v[100:101], v90 src0_sel:WORD_1
	s_waitcnt lgkmcnt(0)
	v_add_f32_e32 v19, v19, v23
	v_cndmask_b32_e32 v23, v20, v35, vcc
	ds_bpermute_b32 v23, v205, v23
	v_mul_f32_e32 v90, v226, v97
	v_fmac_f32_e32 v90, v225, v96
	v_fmac_f32_e32 v90, v220, v100
	v_cvt_pk_f32_fp8_e32 v[96:97], v91
	v_fmac_f32_e32 v90, v223, v101
	v_cndmask_b32_e32 v20, v35, v20, vcc
	v_add_f32_e32 v94, v99, v95
	v_add_f32_e32 v95, 0, v90
	v_cvt_pk_f32_fp8_sdwa v[90:91], v91 src0_sel:WORD_1
	s_waitcnt lgkmcnt(0)
	v_add_f32_e32 v20, v20, v23
	v_cndmask_b32_e32 v23, v26, v37, vcc
	ds_bpermute_b32 v23, v205, v23
	v_mul_f32_e32 v97, v222, v97
	v_fmac_f32_e32 v97, v218, v96
	v_fmac_f32_e32 v97, v215, v90
	v_fmac_f32_e32 v97, v217, v91
	v_cvt_pk_f32_fp8_e32 v[90:91], v92
	v_cndmask_b32_e32 v24, v37, v26, vcc
	s_waitcnt lgkmcnt(0)
	v_add_f32_e32 v23, v24, v23
	v_cndmask_b32_e32 v24, v27, v42, vcc
	v_add_f32_e32 v95, v95, v97
	v_cvt_pk_f32_fp8_sdwa v[96:97], v92 src0_sel:WORD_1
	ds_bpermute_b32 v24, v205, v24
	v_mul_f32_e32 v91, v216, v91
	v_fmac_f32_e32 v91, v214, v90
	v_fmac_f32_e32 v91, v211, v96
	v_cndmask_b32_e32 v25, v42, v27, vcc
	v_fmac_f32_e32 v91, v224, v97
	s_waitcnt lgkmcnt(0)
	v_add_f32_e32 v24, v25, v24
	v_cndmask_b32_e32 v25, v28, v40, vcc
	v_add_f32_e32 v95, v95, v91
	v_cvt_pk_f32_fp8_e32 v[90:91], v93
	ds_bpermute_b32 v25, v205, v25
	v_cvt_pk_f32_fp8_sdwa v[92:93], v93 src0_sel:WORD_1
	v_cndmask_b32_e32 v26, v40, v28, vcc
	v_mul_f32_e32 v91, v221, v91
	v_fmac_f32_e32 v91, v219, v90
	v_cndmask_b32_e32 v90, v123, v118, vcc
	s_waitcnt lgkmcnt(0)
	v_add_f32_e32 v25, v26, v25
	v_cndmask_b32_e64 v26, v21, v20, s[4:5]
	ds_bpermute_b32 v90, v205, v90
	v_cndmask_b32_e64 v20, v20, v21, s[4:5]
	ds_bpermute_b32 v21, v206, v26
	v_fmac_f32_e32 v91, v212, v92
	v_fmac_f32_e32 v91, v213, v93
	v_add_f32_e32 v92, v95, v91
	v_cndmask_b32_e32 v91, v118, v123, vcc
	s_waitcnt lgkmcnt(1)
	v_add_f32_e32 v93, v91, v90
	v_cvt_pk_f32_fp8_e32 v[90:91], v86
	s_waitcnt lgkmcnt(0)
	v_add_f32_e32 v20, v20, v21
	v_cndmask_b32_e64 v21, v22, v23, s[4:5]
	ds_bpermute_b32 v21, v206, v21
	v_mul_f32_e32 v95, v226, v91
	v_fmac_f32_e32 v95, v225, v90
	v_cvt_pk_f32_fp8_sdwa v[90:91], v86 src0_sel:WORD_1
	v_cndmask_b32_e64 v22, v23, v22, s[4:5]
	s_waitcnt lgkmcnt(0)
	v_add_f32_e32 v21, v22, v21
	v_cndmask_b32_e64 v22, v18, v24, s[4:5]
	ds_bpermute_b32 v22, v206, v22
	v_fmac_f32_e32 v95, v220, v90
	v_fmac_f32_e32 v95, v223, v91
	v_cvt_pk_f32_fp8_e32 v[90:91], v87
	v_cndmask_b32_e64 v18, v24, v18, s[4:5]
	v_cvt_pk_f32_fp8_sdwa v[86:87], v87 src0_sel:WORD_1
	s_waitcnt lgkmcnt(0)
	v_add_f32_e32 v18, v18, v22
	v_cndmask_b32_e64 v22, v19, v25, s[4:5]
	ds_bpermute_b32 v22, v206, v22
	v_mul_f32_e32 v91, v222, v91
	v_fmac_f32_e32 v91, v218, v90
	v_fmac_f32_e32 v91, v215, v86
	v_fmac_f32_e32 v91, v217, v87
	v_cvt_pk_f32_fp8_e32 v[86:87], v88
	v_cndmask_b32_e64 v19, v25, v19, s[4:5]
	s_waitcnt lgkmcnt(0)
	v_add_f32_e32 v19, v19, v22
	v_cndmask_b32_e64 v22, v20, v18, s[6:7]
	v_cndmask_b32_e64 v18, v18, v20, s[6:7]
	ds_bpermute_b32 v20, v207, v22
	v_add_f32_e32 v95, 0, v95
	v_add_f32_e32 v90, v95, v91
	v_mul_f32_e32 v91, v216, v87
	v_fmac_f32_e32 v91, v214, v86
	v_cvt_pk_f32_fp8_sdwa v[86:87], v88 src0_sel:WORD_1
	s_waitcnt lgkmcnt(0)
	v_add_f32_e32 v18, v18, v20
	v_cndmask_b32_e64 v20, v21, v19, s[6:7]
	ds_bpermute_b32 v20, v207, v20
	v_fmac_f32_e32 v91, v211, v86
	v_fmac_f32_e32 v91, v224, v87
	v_cvt_pk_f32_fp8_e32 v[86:87], v89
	v_cndmask_b32_e64 v19, v19, v21, s[6:7]
	s_waitcnt lgkmcnt(0)
	v_add_f32_e32 v19, v19, v20
	v_add_f32_e32 v88, v90, v91
	v_mul_f32_e32 v90, v221, v87
	v_cndmask_b32_e64 v20, v18, v19, s[8:9]
	v_fmac_f32_e32 v90, v219, v86
	v_cvt_pk_f32_fp8_sdwa v[86:87], v89 src0_sel:WORD_1
	v_cndmask_b32_e64 v18, v19, v18, s[8:9]
	ds_bpermute_b32 v19, v208, v20
	v_fmac_f32_e32 v90, v212, v86
	v_fmac_f32_e32 v90, v213, v87
	v_cvt_pk_f32_fp8_e32 v[86:87], v78
	s_waitcnt lgkmcnt(0)
; __device__ __forceinline__ float gelu_exact(float x) { return 0.5f * x * (1.f + erff(x * 0.70710678118654752f)); }
; __device__ void phase_experts(const Params& p, int l) {
;     ...
;         const int nb = (bi + 1) & 7;
;         const int idv = bi == 7 ? idn0 : (nb < 4 ? id0 : id1);
; #pragma unroll
;         for (int j = 0; j < 16; ++j) {
;           const int row = __builtin_amdgcn_readlane(idv, (nb & 3) * 16 + j);
;           rbuf[(bi + 1) & 1][j] = *(const u32x4*)(U + (size_t)row * 1024 + lane * 16);
;         }
;     ...
; #pragma unroll
;       for (int hw = 8; hw >= 1; hw >>= 1) {
;         const bool up = (lane & hw) != 0;
; #pragma unroll
;         for (int k = 0; k < hw; ++k) {
;           const float send = up ? sj[k] : sj[k + hw], keep = up ? sj[k + hw] : sj[k];
;           sj[k] = keep + __shfl_xor(send, hw);
;         }
;       }
;       float tot = sj[0];
;       tot = xsum_rows(tot);
;       if ((lane >> 4) == (bi & 3)) { if (bi < 4) d0 = tot; else d1 = tot; }
;     }
;     const float w0 = gelu_exact(d0 * (1.f / 256.f)) * g0 * (1.f / 64.f), w1 = gelu_exact(d1 * (1.f / 256.f)) * g1 * (1.f / 64.f);
	v_add_f32_e32 v18, v18, v19
	v_mov_b32_e32 v19, v18
	s_nop 1
	v_permlane16_swap_b32_e32 v18, v19
	v_add_f32_e32 v114, v18, v19
	v_lshl_add_u64 v[18:19], v[182:183], 0, s[0:1]
	v_readlane_b32 s0, v203, 1
	v_mul_f32_e32 v89, v226, v87
	s_ashr_i32 s1, s0, 31
	v_fmac_f32_e32 v89, v225, v86
	v_cvt_pk_f32_fp8_sdwa v[86:87], v78 src0_sel:WORD_1
	s_lshl_b64 s[0:1], s[0:1], 10
	global_load_dwordx4 v[82:85], v[18:19], off
	v_lshl_add_u64 v[18:19], v[182:183], 0, s[0:1]
	v_readlane_b32 s0, v203, 2
	s_ashr_i32 s1, s0, 31
	s_lshl_b64 s[0:1], s[0:1], 10
	v_fmac_f32_e32 v89, v220, v86
	v_lshl_add_u64 v[22:23], v[182:183], 0, s[0:1]
	v_readlane_b32 s0, v203, 3
	v_fmac_f32_e32 v89, v223, v87
	v_cvt_pk_f32_fp8_e32 v[86:87], v79
	s_ashr_i32 s1, s0, 31
	s_lshl_b64 s[0:1], s[0:1], 10
	v_cvt_pk_f32_fp8_sdwa v[78:79], v79 src0_sel:WORD_1
	global_load_dwordx4 v[18:21], v[18:19], off
	v_mul_f32_e32 v87, v222, v87
	global_load_dwordx4 v[74:77], v[22:23], off
	v_lshl_add_u64 v[22:23], v[182:183], 0, s[0:1]
	v_readlane_b32 s0, v203, 4
	s_ashr_i32 s1, s0, 31
	s_lshl_b64 s[0:1], s[0:1], 10
	v_fmac_f32_e32 v87, v218, v86
	global_load_dwordx4 v[70:73], v[22:23], off
	v_lshl_add_u64 v[22:23], v[182:183], 0, s[0:1]
	v_readlane_b32 s0, v203, 5
	v_fmac_f32_e32 v87, v215, v78
	s_ashr_i32 s1, s0, 31
	v_fmac_f32_e32 v87, v217, v79
	v_cvt_pk_f32_fp8_e32 v[78:79], v80
	s_lshl_b64 s[0:1], s[0:1], 10
	global_load_dwordx4 v[66:69], v[22:23], off
	v_lshl_add_u64 v[22:23], v[182:183], 0, s[0:1]
	v_readlane_b32 s0, v203, 6
	s_ashr_i32 s1, s0, 31
	v_add_f32_e32 v89, 0, v89
	s_lshl_b64 s[0:1], s[0:1], 10
	v_add_f32_e32 v86, v89, v87
	v_mul_f32_e32 v87, v216, v79
	global_load_dwordx4 v[62:65], v[22:23], off
	v_lshl_add_u64 v[22:23], v[182:183], 0, s[0:1]
	v_readlane_b32 s0, v203, 7
	v_fmac_f32_e32 v87, v214, v78
	v_cvt_pk_f32_fp8_sdwa v[78:79], v80 src0_sel:WORD_1
	s_ashr_i32 s1, s0, 31
	s_lshl_b64 s[0:1], s[0:1], 10
	global_load_dwordx4 v[58:61], v[22:23], off
	v_lshl_add_u64 v[22:23], v[182:183], 0, s[0:1]
	v_readlane_b32 s0, v203, 8
	s_ashr_i32 s1, s0, 31
	v_fmac_f32_e32 v87, v211, v78
	s_lshl_b64 s[0:1], s[0:1], 10
	v_fmac_f32_e32 v87, v224, v79
	v_cvt_pk_f32_fp8_e32 v[78:79], v81
	global_load_dwordx4 v[54:57], v[22:23], off
	v_lshl_add_u64 v[22:23], v[182:183], 0, s[0:1]
	v_readlane_b32 s0, v203, 9
	s_ashr_i32 s1, s0, 31
	s_lshl_b64 s[0:1], s[0:1], 10
	global_load_dwordx4 v[50:53], v[22:23], off
	v_lshl_add_u64 v[22:23], v[182:183], 0, s[0:1]
	v_readlane_b32 s0, v203, 10
	v_add_f32_e32 v80, v86, v87
	v_mul_f32_e32 v86, v221, v79
	s_ashr_i32 s1, s0, 31
	v_fmac_f32_e32 v86, v219, v78
	v_cvt_pk_f32_fp8_sdwa v[78:79], v81 src0_sel:WORD_1
	s_lshl_b64 s[0:1], s[0:1], 10
	v_lshl_add_u64 v[26:27], v[182:183], 0, s[0:1]
	v_readlane_b32 s0, v203, 11
	s_ashr_i32 s1, s0, 31
	s_lshl_b64 s[0:1], s[0:1], 10
	v_fmac_f32_e32 v86, v212, v78
	global_load_dwordx4 v[22:25], v[22:23], off
	v_fmac_f32_e32 v86, v213, v79
	global_load_dwordx4 v[46:49], v[26:27], off
	v_lshl_add_u64 v[26:27], v[182:183], 0, s[0:1]
	v_readlane_b32 s0, v203, 12
	s_ashr_i32 s1, s0, 31
	v_add_f32_e32 v88, v88, v90
	v_add_f32_e32 v78, v80, v86
	s_lshl_b64 s[0:1], s[0:1], 10
	v_cndmask_b32_e32 v79, v78, v88, vcc
	global_load_dwordx4 v[42:45], v[26:27], off
	v_lshl_add_u64 v[26:27], v[182:183], 0, s[0:1]
	v_readlane_b32 s0, v203, 13
	ds_bpermute_b32 v79, v205, v79
	s_ashr_i32 s1, s0, 31
	s_lshl_b64 s[0:1], s[0:1], 10
	global_load_dwordx4 v[38:41], v[26:27], off
	v_lshl_add_u64 v[26:27], v[182:183], 0, s[0:1]
	v_readlane_b32 s0, v203, 14
	s_ashr_i32 s1, s0, 31
	v_cndmask_b32_e32 v78, v88, v78, vcc
	s_lshl_b64 s[0:1], s[0:1], 10
	s_waitcnt lgkmcnt(0)
	v_add_f32_e32 v78, v78, v79
	v_cndmask_b32_e32 v79, v116, v110, vcc
	global_load_dwordx4 v[34:37], v[26:27], off
	v_lshl_add_u64 v[26:27], v[182:183], 0, s[0:1]
	v_readlane_b32 s0, v203, 15
	ds_bpermute_b32 v79, v205, v79
	s_ashr_i32 s1, s0, 31
	s_lshl_b64 s[0:1], s[0:1], 10
	global_load_dwordx4 v[30:33], v[26:27], off
	v_lshl_add_u64 v[26:27], v[182:183], 0, s[0:1]
	global_load_dwordx4 v[26:29], v[26:27], off
	v_cndmask_b32_e32 v80, v110, v116, vcc
	s_waitcnt lgkmcnt(0)
	v_add_f32_e32 v79, v80, v79
	v_cndmask_b32_e32 v80, v117, v106, vcc
	ds_bpermute_b32 v80, v205, v80
	v_cndmask_b32_e32 v81, v106, v117, vcc
	v_cndmask_b32_e32 v86, v102, v122, vcc
	v_cndmask_b32_e32 v87, v98, v124, vcc
	v_cndmask_b32_e32 v88, v94, v125, vcc
	s_waitcnt lgkmcnt(0)
	v_add_f32_e32 v80, v81, v80
	v_cndmask_b32_e32 v81, v122, v102, vcc
	ds_bpermute_b32 v81, v205, v81
	v_cndmask_b32_e32 v89, v92, v126, vcc
	v_mov_b32_e32 v115, v114
	s_nop 1
	v_permlane32_swap_b32_e32 v114, v115
	s_waitcnt lgkmcnt(0)
	v_add_f32_e32 v81, v86, v81
	v_cndmask_b32_e32 v86, v124, v98, vcc
	ds_bpermute_b32 v86, v205, v86
	s_waitcnt lgkmcnt(0)
	v_add_f32_e32 v86, v87, v86
	v_cndmask_b32_e32 v87, v125, v94, vcc
	ds_bpermute_b32 v87, v205, v87
	s_waitcnt lgkmcnt(0)
	v_add_f32_e32 v87, v88, v87
	v_cndmask_b32_e32 v88, v126, v92, vcc
	ds_bpermute_b32 v88, v205, v88
	s_waitcnt lgkmcnt(0)
	v_add_f32_e32 v88, v89, v88
	v_cndmask_b32_e64 v89, v93, v81, s[4:5]
	ds_bpermute_b32 v89, v206, v89
	v_cndmask_b32_e64 v81, v81, v93, s[4:5]
	s_waitcnt lgkmcnt(0)
	v_add_f32_e32 v81, v81, v89
	v_cndmask_b32_e64 v89, v78, v86, s[4:5]
	v_cndmask_b32_e64 v78, v86, v78, s[4:5]
	ds_bpermute_b32 v86, v206, v89
	s_waitcnt lgkmcnt(0)
	v_add_f32_e32 v78, v78, v86
	v_cndmask_b32_e64 v86, v79, v87, s[4:5]
	ds_bpermute_b32 v86, v206, v86
	v_cndmask_b32_e64 v79, v87, v79, s[4:5]
	s_waitcnt lgkmcnt(0)
	v_add_f32_e32 v79, v79, v86
	v_cndmask_b32_e64 v86, v80, v88, s[4:5]
	ds_bpermute_b32 v86, v206, v86
	v_cndmask_b32_e64 v80, v88, v80, s[4:5]
	s_waitcnt lgkmcnt(0)
	v_add_f32_e32 v80, v80, v86
	v_cndmask_b32_e64 v86, v81, v79, s[6:7]
	v_cndmask_b32_e64 v79, v79, v81, s[6:7]
	ds_bpermute_b32 v81, v207, v86
	s_waitcnt lgkmcnt(0)
	v_add_f32_e32 v79, v79, v81
	v_cndmask_b32_e64 v81, v78, v80, s[6:7]
	ds_bpermute_b32 v81, v207, v81
	v_cndmask_b32_e64 v78, v80, v78, s[6:7]
	s_waitcnt lgkmcnt(0)
	v_add_f32_e32 v78, v78, v81
	v_cndmask_b32_e64 v80, v79, v78, s[8:9]
	ds_bpermute_b32 v80, v208, v80
	v_cndmask_b32_e64 v78, v78, v79, s[8:9]
	s_waitcnt lgkmcnt(0)
	v_add_f32_e32 v78, v78, v80
	v_mov_b32_e32 v79, v78
	s_nop 1
	v_permlane16_swap_b32_e32 v78, v79
	v_add_f32_e32 v81, v78, v79
	v_mul_f32_e32 v79, 0x3b800000, v228
	v_mov_b32_e32 v86, v81
	v_mul_f32_e32 v78, 0x3f3504f3, v79
	s_nop 0
	v_permlane32_swap_b32_e32 v81, v86
	v_cmp_nlt_f32_e64 s[0:1], |v78|, 1.0
	s_and_saveexec_b64 s[2:3], s[0:1]
	s_xor_b64 s[0:1], exec, s[2:3]
	s_cbranch_execz .LBB0_1181
; __device__ __forceinline__ float gelu_exact(float x) { return 0.5f * x * (1.f + erff(x * 0.70710678118654752f)); }
; __device__ void phase_experts(const Params& p, int l) {
;     ...
;     const float w0 = gelu_exact(d0 * (1.f / 256.f)) * g0 * (1.f / 64.f), w1 = gelu_exact(d1 * (1.f / 256.f)) * g1 * (1.f / 64.f);
	s_mov_b32 s2, 0x378e98ab
	v_fma_f32 v80, |v78|, s2, v196
	s_mov_b32 s2, 0x3b7cd369
	v_fma_f32 v80, |v78|, v80, s2
	s_mov_b32 s2, 0xbcc618b2
	v_fma_f32 v80, |v78|, v80, s2
	s_mov_b32 s2, 0x3dda74e4
	v_fma_f32 v80, |v78|, v80, s2
	s_mov_b32 s2, 0x3f228afd
	v_fma_f32 v80, |v78|, v80, s2
	s_mov_b32 s2, 0x3e03c728
	v_fma_f32 v80, |v78|, v80, s2
	v_fma_f32 v80, |v78|, v80, |v78|
	v_mul_f32_e32 v87, 0xbfb8aa3b, v80
	s_mov_b32 s2, 0xbfb8aa3b
	v_fma_f32 v88, v80, s2, -v87
	v_rndne_f32_e32 v89, v87
	v_fmac_f32_e32 v88, 0xb2a5705f, v80
	v_sub_f32_e32 v87, v87, v89
	v_add_f32_e32 v87, v87, v88
	v_cvt_i32_f32_e32 v88, v89
	v_exp_f32_e32 v87, v87
	s_mov_b32 s2, 0x42ce8ed0
	v_cmp_nlt_f32_e64 s[18:19], s2, v80
	s_mov_b32 s2, 0xc2b17218
	v_ldexp_f32 v87, v87, v88
	v_cndmask_b32_e64 v87, 0, v87, s[18:19]
	v_cmp_ngt_f32_e64 s[18:19], s2, v80
	s_nop 1
	v_cndmask_b32_e64 v80, v193, v87, s[18:19]
	v_sub_f32_e32 v80, 1.0, v80

; __device__ void phase_experts_v(const Params& p, int l) {
;     ...
;     const f32x2 xin = *(const f32x2*)(p.xcur + (unsigned)(tok * 1024 + colb));
;     u32x4 rv[16];
; #pragma unroll
;     for (int j = 0; j < 16; ++j) rv[j] = *(const u32x4*)(Vb + (unsigned)(rows[j] * 1024 + c * 16));
;     const int tokn = min(tok + nslot, T_TOK - 1);
;     int rown[16]; float wtc[16];
; #pragma unroll
;     for (int j = 0; j < 16; ++j) { wtc[j] = wt[j]; rown[j] = p.pidx[(unsigned)(tokn * 128 + e8) + 8 * j]; wt[j] = p.pw[(unsigned)(tokn * 128 + e8) + 8 * j]; }
.LBB0_1234:
	v_lshl_or_b32 v2, v121, 10, v19
	global_load_dwordx4 v[52:55], v2, s[2:3]
	v_lshl_or_b32 v2, v120, 10, v19
	global_load_dwordx4 v[56:59], v2, s[2:3]
	v_lshl_or_b32 v2, v119, 10, v19
	global_load_dwordx4 v[60:63], v2, s[2:3]
	v_lshl_or_b32 v2, v112, 10, v19
	global_load_dwordx4 v[64:67], v2, s[2:3]
	v_lshl_or_b32 v2, v111, 10, v19
	global_load_dwordx4 v[68:71], v2, s[2:3]
	v_lshl_or_b32 v2, v109, 10, v19
	global_load_dwordx4 v[72:75], v2, s[2:3]
	v_lshl_or_b32 v2, v108, 10, v19
	global_load_dwordx4 v[76:79], v2, s[2:3]
	v_lshl_or_b32 v2, v107, 10, v19
	global_load_dwordx4 v[84:87], v2, s[2:3]
	v_readlane_b32 s16, v252, 25
	v_lshl_or_b32 v2, v106, 10, v19
	v_readlane_b32 s17, v252, 26
	global_load_dwordx4 v[92:95], v2, s[2:3]
	s_waitcnt lgkmcnt(0)
	v_lshl_or_b32 v3, v47, 10, v19
	v_lshl_add_u64 v[12:13], v[0:1], 2, s[16:17]
	v_lshl_or_b32 v4, v45, 10, v19
	v_lshl_or_b32 v5, v43, 10, v19
	v_mov_b32_e32 v44, v113
	v_mov_b32_e32 v46, v110
	v_lshl_or_b32 v11, v41, 10, v19
	global_load_dwordx2 v[20:21], v[12:13], off
	global_load_dwordx4 v[106:109], v3, s[2:3]
	global_load_dwordx4 v[110:113], v4, s[2:3]
	global_load_dwordx4 v[6:9], v5, s[2:3]
	s_nop 0
	global_load_dwordx4 v[2:5], v11, s[2:3]
	v_mov_b32_e32 v36, v117
	v_mov_b32_e32 v38, v116
	v_mov_b32_e32 v30, v123
	v_mov_b32_e32 v32, v122
	v_mov_b32_e32 v16, v129
	v_mov_b32_e32 v18, v128
	v_mov_b32_e32 v42, v114
	v_readlane_b32 s16, v252, 58
	v_mov_b32_e32 v40, v115
	v_add_u32_e32 v15, s16, v15
	v_min_i32_e32 v11, 0x3fff, v15
	v_mov_b32_e32 v49, v1
	v_lshl_or_b32 v48, v11, 7, v17
	v_readlane_b32 s16, v253, 61
	v_mov_b32_e32 v34, v118
	v_lshlrev_b64 v[48:49], 2, v[48:49]
	v_readlane_b32 s24, v254, 5
	v_readlane_b32 s25, v254, 6
	v_readlane_b32 s28, v254, 9
	v_readlane_b32 s29, v254, 10
	v_lshl_add_u64 v[114:115], s[24:25], 0, v[48:49]
	v_mov_b32_e32 v14, v80
	v_mov_b32_e32 v22, v127
	v_mov_b32_e32 v24, v126
	v_mov_b32_e32 v26, v125
	v_mov_b32_e32 v28, v124
	v_lshl_or_b32 v191, v39, 10, v19
	v_lshl_or_b32 v192, v37, 10, v19
	v_lshl_or_b32 v195, v35, 10, v19
	v_lshl_add_u64 v[80:81], s[28:29], 0, v[48:49]
	s_andn2_b64 vcc, exec, s[12:13]
	v_readlane_b32 s17, v253, 62
	v_readlane_b32 s18, v253, 63
	v_readlane_b32 s19, v254, 0
	v_readlane_b32 s20, v254, 1
	v_readlane_b32 s21, v254, 2
	v_readlane_b32 s22, v254, 3
	v_readlane_b32 s23, v254, 4
	v_readlane_b32 s26, v254, 7
	s_waitcnt vmcnt(13)
	v_cvt_pk_f32_fp8_sdwa v[116:117], v52 src0_sel:WORD_1
	v_cvt_pk_f32_fp8_e32 v[48:49], v52
	s_waitcnt vmcnt(12)
	v_cvt_pk_f32_fp8_sdwa v[122:123], v56 src0_sel:WORD_1
	v_cvt_pk_f32_fp8_e32 v[124:125], v53
	s_waitcnt vmcnt(11)
	v_cvt_pk_f32_fp8_sdwa v[128:129], v60 src0_sel:WORD_1
	v_pk_fma_f32 v[116:117], v[46:47], v[116:117], 0 op_sel_hi:[0,1,0]
	s_waitcnt vmcnt(10)
	v_cvt_pk_f32_fp8_sdwa v[130:131], v64 src0_sel:WORD_1
	v_pk_fma_f32 v[116:117], v[44:45], v[122:123], v[116:117] op_sel_hi:[0,1,1]
	s_waitcnt vmcnt(9)
	v_cvt_pk_f32_fp8_sdwa v[132:133], v68 src0_sel:WORD_1
	v_pk_fma_f32 v[116:117], v[42:43], v[128:129], v[116:117] op_sel_hi:[0,1,1]
	s_waitcnt vmcnt(8)
	v_cvt_pk_f32_fp8_sdwa v[140:141], v72 src0_sel:WORD_1
	v_pk_fma_f32 v[116:117], v[40:41], v[130:131], v[116:117] op_sel_hi:[0,1,1]
	s_waitcnt vmcnt(7)
	v_cvt_pk_f32_fp8_sdwa v[178:179], v76 src0_sel:WORD_1
	v_pk_fma_f32 v[116:117], v[38:39], v[132:133], v[116:117] op_sel_hi:[0,1,1]
	s_waitcnt vmcnt(6)
	v_cvt_pk_f32_fp8_sdwa v[202:203], v84 src0_sel:WORD_1
	v_pk_fma_f32 v[116:117], v[36:37], v[140:141], v[116:117] op_sel_hi:[0,1,1]
	v_pk_fma_f32 v[116:117], v[34:35], v[178:179], v[116:117] op_sel_hi:[0,1,1]
	v_cvt_pk_f32_fp8_sdwa v[104:105], v53 src0_sel:WORD_1
	v_cvt_pk_f32_fp8_e32 v[52:53], v54
	v_cvt_pk_f32_fp8_sdwa v[142:143], v54 src0_sel:WORD_1
	v_cvt_pk_f32_fp8_e32 v[144:145], v55
	v_cvt_pk_f32_fp8_sdwa v[146:147], v55 src0_sel:WORD_1
	v_cvt_pk_f32_fp8_e32 v[50:51], v56
	v_cvt_pk_f32_fp8_e32 v[126:127], v57
	v_cvt_pk_f32_fp8_sdwa v[148:149], v57 src0_sel:WORD_1
	v_cvt_pk_f32_fp8_e32 v[56:57], v58
	v_cvt_pk_f32_fp8_sdwa v[98:99], v58 src0_sel:WORD_1
	v_cvt_pk_f32_fp8_e32 v[88:89], v59
	v_cvt_pk_f32_fp8_sdwa v[82:83], v59 src0_sel:WORD_1
	v_cvt_pk_f32_fp8_e32 v[54:55], v60
	v_cvt_pk_f32_fp8_e32 v[134:135], v61
	v_cvt_pk_f32_fp8_sdwa v[150:151], v61 src0_sel:WORD_1
	v_cvt_pk_f32_fp8_e32 v[60:61], v62
	v_cvt_pk_f32_fp8_sdwa v[152:153], v62 src0_sel:WORD_1
	v_cvt_pk_f32_fp8_e32 v[96:97], v63
	v_cvt_pk_f32_fp8_sdwa v[90:91], v63 src0_sel:WORD_1
	v_cvt_pk_f32_fp8_e32 v[58:59], v64
	v_cvt_pk_f32_fp8_e32 v[136:137], v65
	v_cvt_pk_f32_fp8_sdwa v[154:155], v65 src0_sel:WORD_1
	v_cvt_pk_f32_fp8_e32 v[64:65], v66
	v_cvt_pk_f32_fp8_sdwa v[156:157], v66 src0_sel:WORD_1
	v_cvt_pk_f32_fp8_e32 v[158:159], v67
	v_cvt_pk_f32_fp8_sdwa v[100:101], v67 src0_sel:WORD_1
	v_cvt_pk_f32_fp8_e32 v[62:63], v68
	v_cvt_pk_f32_fp8_e32 v[138:139], v69
	v_cvt_pk_f32_fp8_sdwa v[160:161], v69 src0_sel:WORD_1
	v_cvt_pk_f32_fp8_e32 v[68:69], v70
	v_cvt_pk_f32_fp8_sdwa v[162:163], v70 src0_sel:WORD_1
	v_cvt_pk_f32_fp8_e32 v[164:165], v71
	v_cvt_pk_f32_fp8_sdwa v[166:167], v71 src0_sel:WORD_1
	v_cvt_pk_f32_fp8_e32 v[66:67], v72
	v_cvt_pk_f32_fp8_e32 v[168:169], v73
	v_cvt_pk_f32_fp8_sdwa v[170:171], v73 src0_sel:WORD_1
	v_cvt_pk_f32_fp8_e32 v[72:73], v74
	v_cvt_pk_f32_fp8_sdwa v[172:173], v74 src0_sel:WORD_1
	v_cvt_pk_f32_fp8_e32 v[174:175], v75
	v_cvt_pk_f32_fp8_sdwa v[176:177], v75 src0_sel:WORD_1
	v_cvt_pk_f32_fp8_e32 v[70:71], v76
	v_cvt_pk_f32_fp8_e32 v[180:181], v77
	v_cvt_pk_f32_fp8_sdwa v[182:183], v77 src0_sel:WORD_1
	v_cvt_pk_f32_fp8_e32 v[76:77], v78
	v_cvt_pk_f32_fp8_sdwa v[184:185], v78 src0_sel:WORD_1
	v_cvt_pk_f32_fp8_e32 v[186:187], v79
	v_cvt_pk_f32_fp8_sdwa v[188:189], v79 src0_sel:WORD_1
	v_cvt_pk_f32_fp8_e32 v[74:75], v84
	v_cvt_pk_f32_fp8_e32 v[204:205], v85
	v_cvt_pk_f32_fp8_sdwa v[206:207], v85 src0_sel:WORD_1
	v_cvt_pk_f32_fp8_e32 v[84:85], v86
	v_cvt_pk_f32_fp8_sdwa v[208:209], v86 src0_sel:WORD_1
	v_cvt_pk_f32_fp8_e32 v[210:211], v87
	v_cvt_pk_f32_fp8_sdwa v[212:213], v87 src0_sel:WORD_1
	s_waitcnt vmcnt(5)
; __device__ void phase_experts_v(const Params& p, int l) {
;     ...
;     const f32x2 xin = *(const f32x2*)(p.xcur + (unsigned)(tok * 1024 + colb));
;     u32x4 rv[16];
; #pragma unroll
;     for (int j = 0; j < 16; ++j) rv[j] = *(const u32x4*)(Vb + (unsigned)(rows[j] * 1024 + c * 16));
;     const int tokn = min(tok + nslot, T_TOK - 1);
;     int rown[16]; float wtc[16];
; #pragma unroll
;     for (int j = 0; j < 16; ++j) { wtc[j] = wt[j]; rown[j] = p.pidx[(unsigned)(tokn * 128 + e8) + 8 * j]; wt[j] = p.pw[(unsigned)(tokn * 128 + e8) + 8 * j]; }
;     float acc[16];
; #pragma unroll
;     for (int i = 0; i < 16; ++i) acc[i] = 0.f;
; #pragma unroll
;     for (int j = 0; j < 16; ++j)
; #pragma unroll
;       for (int q = 0; q < 4; ++q) {
;         const f32x2 a = __builtin_amdgcn_cvt_pk_f32_fp8((int)rv[j][q], false), b2 = __builtin_amdgcn_cvt_pk_f32_fp8((int)rv[j][q], true);
;         acc[q * 4] += wtc[j] * a.x; acc[q * 4 + 1] += wtc[j] * a.y; acc[q * 4 + 2] += wtc[j] * b2.x; acc[q * 4 + 3] += wtc[j] * b2.y;
;       }
	v_cvt_pk_f32_fp8_e32 v[78:79], v92
	v_cvt_pk_f32_fp8_sdwa v[214:215], v92 src0_sel:WORD_1
	v_cvt_pk_f32_fp8_e32 v[216:217], v93
	v_cvt_pk_f32_fp8_sdwa v[218:219], v93 src0_sel:WORD_1
	v_cvt_pk_f32_fp8_e32 v[92:93], v94
	v_cvt_pk_f32_fp8_sdwa v[220:221], v94 src0_sel:WORD_1
	v_cvt_pk_f32_fp8_e32 v[222:223], v95
	v_cvt_pk_f32_fp8_sdwa v[224:225], v95 src0_sel:WORD_1
	s_waitcnt vmcnt(3)
	v_cvt_pk_f32_fp8_e32 v[86:87], v106
	v_cvt_pk_f32_fp8_sdwa v[226:227], v106 src0_sel:WORD_1
	v_cvt_pk_f32_fp8_e32 v[228:229], v107
	v_cvt_pk_f32_fp8_sdwa v[230:231], v107 src0_sel:WORD_1
	v_cvt_pk_f32_fp8_e32 v[102:103], v108
	v_cvt_pk_f32_fp8_sdwa v[232:233], v108 src0_sel:WORD_1
	v_cvt_pk_f32_fp8_e32 v[234:235], v109
	v_cvt_pk_f32_fp8_sdwa v[236:237], v109 src0_sel:WORD_1
	s_waitcnt vmcnt(2)
	v_cvt_pk_f32_fp8_e32 v[94:95], v110
	v_cvt_pk_f32_fp8_sdwa v[238:239], v110 src0_sel:WORD_1
	v_cvt_pk_f32_fp8_e32 v[240:241], v111
	v_cvt_pk_f32_fp8_sdwa v[242:243], v111 src0_sel:WORD_1
	v_cvt_pk_f32_fp8_e32 v[244:245], v112
	v_cvt_pk_f32_fp8_sdwa v[246:247], v112 src0_sel:WORD_1
	v_cvt_pk_f32_fp8_e32 v[248:249], v113
	v_cvt_pk_f32_fp8_sdwa v[250:251], v113 src0_sel:WORD_1
	global_load_dword v121, v[114:115], off
	global_load_dword v120, v[114:115], off offset:32
	global_load_dword v119, v[114:115], off offset:64
	global_load_dword v112, v[114:115], off offset:96
	global_load_dword v111, v[114:115], off offset:128
	global_load_dword v109, v[114:115], off offset:160
	global_load_dword v108, v[114:115], off offset:192
	global_load_dword v107, v[114:115], off offset:224
	v_pk_fma_f32 v[128:129], v[32:33], v[202:203], v[116:117] op_sel_hi:[0,1,1]
	global_load_dword v106, v[114:115], off offset:256
	global_load_dword v47, v[114:115], off offset:288
	global_load_dword v45, v[114:115], off offset:320
	global_load_dword v43, v[114:115], off offset:352
	global_load_dword v41, v[114:115], off offset:384
	global_load_dword v39, v[114:115], off offset:416
	global_load_dword v37, v[114:115], off offset:448
	global_load_dword v35, v[114:115], off offset:480
	global_load_dword v110, v[80:81], off
	global_load_dword v113, v[80:81], off offset:32
	s_nop 0
	global_load_dword v114, v[80:81], off offset:64
	global_load_dword v115, v[80:81], off offset:96
	global_load_dword v116, v[80:81], off offset:128
	global_load_dword v117, v[80:81], off offset:160
	global_load_dword v118, v[80:81], off offset:192
	global_load_dword v122, v[80:81], off offset:224
	s_waitcnt vmcnt(25)
	v_cvt_pk_f32_fp8_sdwa v[130:131], v6 src0_sel:WORD_1
	v_pk_fma_f32 v[128:129], v[30:31], v[214:215], v[128:129] op_sel_hi:[0,1,1]
	v_pk_fma_f32 v[128:129], v[28:29], v[226:227], v[128:129] op_sel_hi:[0,1,1]
	v_pk_fma_f32 v[128:129], v[26:27], v[238:239], v[128:129] op_sel_hi:[0,1,1]
	v_pk_fma_f32 v[178:179], v[24:25], v[130:131], v[128:129] op_sel_hi:[0,1,1]
	global_load_dwordx4 v[130:133], v191, s[2:3]
	v_cvt_pk_f32_fp8_e32 v[202:203], v7
	v_readlane_b32 s27, v254, 8
	v_readlane_b32 s30, v254, 11
	v_readlane_b32 s31, v254, 12
	s_waitcnt vmcnt(15)
	v_pk_fma_f32 v[124:125], v[46:47], v[124:125], 0 op_sel_hi:[0,1,0]
	s_waitcnt vmcnt(14)
	v_pk_fma_f32 v[124:125], v[44:45], v[126:127], v[124:125] op_sel_hi:[0,1,1]
	s_waitcnt vmcnt(13)
	v_pk_fma_f32 v[134:135], v[42:43], v[134:135], v[124:125] op_sel_hi:[0,1,1]
	s_waitcnt vmcnt(12)
	v_pk_fma_f32 v[140:141], v[40:41], v[136:137], v[134:135] op_sel_hi:[0,1,1]
	global_load_dword v123, v[80:81], off offset:256
	global_load_dword v124, v[80:81], off offset:288
	global_load_dword v125, v[80:81], off offset:320
	global_load_dword v126, v[80:81], off offset:352
	global_load_dword v127, v[80:81], off offset:384
	global_load_dword v128, v[80:81], off offset:416
	global_load_dword v129, v[80:81], off offset:448
	s_nop 0
	global_load_dword v80, v[80:81], off offset:480
	s_waitcnt vmcnt(19)
	v_pk_fma_f32 v[138:139], v[38:39], v[138:139], v[140:141] op_sel_hi:[0,1,1]
	global_load_dwordx4 v[134:137], v192, s[2:3]
	s_waitcnt vmcnt(19)
	v_pk_fma_f32 v[168:169], v[36:37], v[168:169], v[138:139] op_sel_hi:[0,1,1]
	global_load_dwordx4 v[138:141], v195, s[2:3]
	v_pk_fma_f32 v[104:105], v[46:47], v[104:105], 0 op_sel_hi:[0,1,0]
	v_pk_fma_f32 v[104:105], v[44:45], v[148:149], v[104:105] op_sel_hi:[0,1,1]
	v_pk_fma_f32 v[104:105], v[42:43], v[150:151], v[104:105] op_sel_hi:[0,1,1]
	v_pk_fma_f32 v[104:105], v[40:41], v[154:155], v[104:105] op_sel_hi:[0,1,1]
	v_pk_fma_f32 v[146:147], v[46:47], v[146:147], 0 op_sel_hi:[0,1,0]
	v_pk_fma_f32 v[104:105], v[38:39], v[160:161], v[104:105] op_sel_hi:[0,1,1]
	v_pk_fma_f32 v[104:105], v[36:37], v[170:171], v[104:105] op_sel_hi:[0,1,1]
	v_pk_fma_f32 v[82:83], v[44:45], v[82:83], v[146:147] op_sel_hi:[0,1,1]
	v_pk_fma_f32 v[144:145], v[46:47], v[144:145], 0 op_sel_hi:[0,1,0]
	s_waitcnt vmcnt(19)
; __device__ void phase_experts_v(const Params& p, int l) {
;     ...
;     for (int j = 0; j < 16; ++j)
; #pragma unroll
;       for (int q = 0; q < 4; ++q) {
;         const f32x2 a = __builtin_amdgcn_cvt_pk_f32_fp8((int)rv[j][q], false), b2 = __builtin_amdgcn_cvt_pk_f32_fp8((int)rv[j][q], true);
;         acc[q * 4] += wtc[j] * a.x; acc[q * 4 + 1] += wtc[j] * a.y; acc[q * 4 + 2] += wtc[j] * b2.x; acc[q * 4 + 3] += wtc[j] * b2.y;
;       }
	v_pk_fma_f32 v[104:105], v[34:35], v[182:183], v[104:105] op_sel_hi:[0,1,1]
	v_pk_fma_f32 v[82:83], v[42:43], v[90:91], v[82:83] op_sel_hi:[0,1,1]
	v_pk_fma_f32 v[142:143], v[46:47], v[142:143], 0 op_sel_hi:[0,1,0]
	v_pk_fma_f32 v[168:169], v[34:35], v[180:181], v[168:169] op_sel_hi:[0,1,1]
	v_cvt_pk_f32_fp8_e32 v[180:181], v6
	v_cvt_pk_f32_fp8_sdwa v[6:7], v7 src0_sel:WORD_1
	v_pk_fma_f32 v[104:105], v[32:33], v[206:207], v[104:105] op_sel_hi:[0,1,1]
	v_pk_fma_f32 v[88:89], v[44:45], v[88:89], v[144:145] op_sel_hi:[0,1,1]
	v_pk_fma_f32 v[82:83], v[40:41], v[100:101], v[82:83] op_sel_hi:[0,1,1]
	v_pk_fma_f32 v[52:53], v[46:47], v[52:53], 0 op_sel_hi:[0,1,0]
	v_pk_fma_f32 v[48:49], v[46:47], v[48:49], 0 op_sel_hi:[0,1,0]
	v_pk_fma_f32 v[104:105], v[30:31], v[218:219], v[104:105] op_sel_hi:[0,1,1]
	v_pk_fma_f32 v[98:99], v[44:45], v[98:99], v[142:143] op_sel_hi:[0,1,1]
	v_pk_fma_f32 v[88:89], v[42:43], v[96:97], v[88:89] op_sel_hi:[0,1,1]
	v_pk_fma_f32 v[82:83], v[38:39], v[166:167], v[82:83] op_sel_hi:[0,1,1]
	v_pk_fma_f32 v[52:53], v[44:45], v[56:57], v[52:53] op_sel_hi:[0,1,1]
	v_pk_fma_f32 v[48:49], v[44:45], v[50:51], v[48:49] op_sel_hi:[0,1,1]
	v_pk_fma_f32 v[104:105], v[28:29], v[230:231], v[104:105] op_sel_hi:[0,1,1]
	v_pk_fma_f32 v[98:99], v[42:43], v[152:153], v[98:99] op_sel_hi:[0,1,1]
	v_pk_fma_f32 v[88:89], v[40:41], v[158:159], v[88:89] op_sel_hi:[0,1,1]
	v_pk_fma_f32 v[82:83], v[36:37], v[176:177], v[82:83] op_sel_hi:[0,1,1]
	v_pk_fma_f32 v[52:53], v[42:43], v[60:61], v[52:53] op_sel_hi:[0,1,1]
	v_pk_fma_f32 v[48:49], v[42:43], v[54:55], v[48:49] op_sel_hi:[0,1,1]
	v_pk_fma_f32 v[104:105], v[26:27], v[242:243], v[104:105] op_sel_hi:[0,1,1]
	v_pk_fma_f32 v[98:99], v[40:41], v[156:157], v[98:99] op_sel_hi:[0,1,1]
	v_pk_fma_f32 v[88:89], v[38:39], v[164:165], v[88:89] op_sel_hi:[0,1,1]
	v_pk_fma_f32 v[82:83], v[34:35], v[188:189], v[82:83] op_sel_hi:[0,1,1]
	v_pk_fma_f32 v[52:53], v[40:41], v[64:65], v[52:53] op_sel_hi:[0,1,1]
	v_pk_fma_f32 v[48:49], v[40:41], v[58:59], v[48:49] op_sel_hi:[0,1,1]
	v_pk_fma_f32 v[6:7], v[24:25], v[6:7], v[104:105] op_sel_hi:[0,1,1]
	v_cvt_pk_f32_fp8_e32 v[104:105], v8
	v_cvt_pk_f32_fp8_sdwa v[148:149], v8 src0_sel:WORD_1
	v_pk_fma_f32 v[98:99], v[38:39], v[162:163], v[98:99] op_sel_hi:[0,1,1]
	v_cvt_pk_f32_fp8_e32 v[142:143], v9
	v_cvt_pk_f32_fp8_sdwa v[8:9], v9 src0_sel:WORD_1
	v_pk_fma_f32 v[88:89], v[36:37], v[174:175], v[88:89] op_sel_hi:[0,1,1]
	v_pk_fma_f32 v[82:83], v[32:33], v[212:213], v[82:83] op_sel_hi:[0,1,1]
	v_pk_fma_f32 v[52:53], v[38:39], v[68:69], v[52:53] op_sel_hi:[0,1,1]
	v_pk_fma_f32 v[48:49], v[38:39], v[62:63], v[48:49] op_sel_hi:[0,1,1]
	v_pk_fma_f32 v[98:99], v[36:37], v[172:173], v[98:99] op_sel_hi:[0,1,1]
	v_pk_fma_f32 v[88:89], v[34:35], v[186:187], v[88:89] op_sel_hi:[0,1,1]
	v_pk_fma_f32 v[82:83], v[30:31], v[224:225], v[82:83] op_sel_hi:[0,1,1]
	v_pk_fma_f32 v[52:53], v[36:37], v[72:73], v[52:53] op_sel_hi:[0,1,1]
	v_pk_fma_f32 v[48:49], v[36:37], v[66:67], v[48:49] op_sel_hi:[0,1,1]
	v_pk_fma_f32 v[98:99], v[34:35], v[184:185], v[98:99] op_sel_hi:[0,1,1]
	v_pk_fma_f32 v[88:89], v[32:33], v[210:211], v[88:89] op_sel_hi:[0,1,1]
	v_pk_fma_f32 v[82:83], v[28:29], v[236:237], v[82:83] op_sel_hi:[0,1,1]
	v_pk_fma_f32 v[52:53], v[34:35], v[76:77], v[52:53] op_sel_hi:[0,1,1]
	v_pk_fma_f32 v[48:49], v[34:35], v[70:71], v[48:49] op_sel_hi:[0,1,1]
	v_pk_fma_f32 v[98:99], v[32:33], v[208:209], v[98:99] op_sel_hi:[0,1,1]
	v_pk_fma_f32 v[88:89], v[30:31], v[222:223], v[88:89] op_sel_hi:[0,1,1]
	v_pk_fma_f32 v[82:83], v[26:27], v[250:251], v[82:83] op_sel_hi:[0,1,1]
	v_pk_fma_f32 v[52:53], v[32:33], v[84:85], v[52:53] op_sel_hi:[0,1,1]
	v_pk_fma_f32 v[48:49], v[32:33], v[74:75], v[48:49] op_sel_hi:[0,1,1]
	v_pk_fma_f32 v[98:99], v[30:31], v[220:221], v[98:99] op_sel_hi:[0,1,1]
	v_pk_fma_f32 v[88:89], v[28:29], v[234:235], v[88:89] op_sel_hi:[0,1,1]
	v_pk_fma_f32 v[8:9], v[24:25], v[8:9], v[82:83] op_sel_hi:[0,1,1]
	v_cvt_pk_f32_fp8_e32 v[82:83], v2
	v_cvt_pk_f32_fp8_e32 v[100:101], v4
	v_pk_fma_f32 v[52:53], v[30:31], v[92:93], v[52:53] op_sel_hi:[0,1,1]
	v_pk_fma_f32 v[48:49], v[30:31], v[78:79], v[48:49] op_sel_hi:[0,1,1]
	v_pk_fma_f32 v[98:99], v[28:29], v[232:233], v[98:99] op_sel_hi:[0,1,1]
	v_pk_fma_f32 v[88:89], v[26:27], v[248:249], v[88:89] op_sel_hi:[0,1,1]
	s_waitcnt vmcnt(10)
	v_cvt_pk_f32_fp8_e32 v[146:147], v130
	v_cvt_pk_f32_fp8_e32 v[152:153], v132
	v_pk_fma_f32 v[52:53], v[28:29], v[102:103], v[52:53] op_sel_hi:[0,1,1]
	v_pk_fma_f32 v[48:49], v[28:29], v[86:87], v[48:49] op_sel_hi:[0,1,1]
	v_pk_fma_f32 v[98:99], v[26:27], v[246:247], v[98:99] op_sel_hi:[0,1,1]
	v_pk_fma_f32 v[88:89], v[24:25], v[142:143], v[88:89] op_sel_hi:[0,1,1]
	v_cvt_pk_f32_fp8_sdwa v[90:91], v2 src0_sel:WORD_1
	v_cvt_pk_f32_fp8_e32 v[96:97], v3
	v_cvt_pk_f32_fp8_sdwa v[2:3], v3 src0_sel:WORD_1
	v_cvt_pk_f32_fp8_sdwa v[142:143], v4 src0_sel:WORD_1
	s_waitcnt vmcnt(1)
	v_cvt_pk_f32_fp8_e32 v[158:159], v134
	v_cvt_pk_f32_fp8_e32 v[164:165], v136
	v_pk_fma_f32 v[52:53], v[26:27], v[244:245], v[52:53] op_sel_hi:[0,1,1]
	v_pk_fma_f32 v[48:49], v[26:27], v[94:95], v[48:49] op_sel_hi:[0,1,1]
	v_pk_fma_f32 v[168:169], v[32:33], v[204:205], v[168:169] op_sel_hi:[0,1,1]
	v_pk_fma_f32 v[98:99], v[24:25], v[148:149], v[98:99] op_sel_hi:[0,1,1]
	v_cvt_pk_f32_fp8_e32 v[144:145], v5
	v_cvt_pk_f32_fp8_sdwa v[4:5], v5 src0_sel:WORD_1
	v_cvt_pk_f32_fp8_sdwa v[148:149], v130 src0_sel:WORD_1
	v_cvt_pk_f32_fp8_sdwa v[154:155], v132 src0_sel:WORD_1
	s_waitcnt vmcnt(0)
; __device__ __forceinline__ unsigned pack2(float lo, float hi) { unsigned r; asm("v_cvt_pk_bf16_f32 %0, %1, %2" : "=v"(r) : "v"(lo), "v"(hi)); return r; }
; __device__ void phase_experts_v(const Params& p, int l) {
;     ...
;     for (int hw = 8; hw >= 2; hw >>= 1) {
;       const int msk = hw * 4;
;       const bool up = (lane & msk) != 0;
; #pragma unroll
;       for (int k = 0; k < hw; ++k) {
;         const float send = up ? acc[k] : acc[k + hw], keep = up ? acc[k + hw] : acc[k];
;         acc[k] = keep + __shfl_xor(send, msk);
;       }
;     }
;     const float x0 = xin[0] + acc[0], x1 = xin[1] + acc[1];
;     *(f32x2*)(p.xcur + (unsigned)(tok * 1024 + colb)) = (f32x2){x0, x1};
;     if (!last) *(unsigned*)(p.xb + (unsigned)(tok * 1024 + colb)) = pack2(x0, x1);
	v_cvt_pk_f32_fp8_e32 v[172:173], v138
	v_cvt_pk_f32_fp8_e32 v[182:183], v140
	v_pk_fma_f32 v[52:53], v[24:25], v[104:105], v[52:53] op_sel_hi:[0,1,1]
	v_pk_fma_f32 v[48:49], v[24:25], v[180:181], v[48:49] op_sel_hi:[0,1,1]
	v_pk_fma_f32 v[168:169], v[30:31], v[216:217], v[168:169] op_sel_hi:[0,1,1]
	v_cvt_pk_f32_fp8_sdwa v[160:161], v134 src0_sel:WORD_1
	v_cvt_pk_f32_fp8_sdwa v[166:167], v136 src0_sel:WORD_1
	v_pk_fma_f32 v[52:53], v[22:23], v[100:101], v[52:53] op_sel_hi:[0,1,1]
	v_pk_fma_f32 v[48:49], v[22:23], v[82:83], v[48:49] op_sel_hi:[0,1,1]
	v_pk_fma_f32 v[168:169], v[28:29], v[228:229], v[168:169] op_sel_hi:[0,1,1]
	v_cvt_pk_f32_fp8_e32 v[150:151], v131
	v_cvt_pk_f32_fp8_sdwa v[130:131], v131 src0_sel:WORD_1
	v_cvt_pk_f32_fp8_e32 v[156:157], v133
	v_cvt_pk_f32_fp8_sdwa v[132:133], v133 src0_sel:WORD_1
	v_cvt_pk_f32_fp8_sdwa v[174:175], v138 src0_sel:WORD_1
	v_cvt_pk_f32_fp8_sdwa v[184:185], v140 src0_sel:WORD_1
	v_pk_fma_f32 v[52:53], v[18:19], v[152:153], v[52:53] op_sel_hi:[0,1,1]
	v_pk_fma_f32 v[48:49], v[18:19], v[146:147], v[48:49] op_sel_hi:[0,1,1]
	v_pk_fma_f32 v[168:169], v[26:27], v[240:241], v[168:169] op_sel_hi:[0,1,1]
	v_cvt_pk_f32_fp8_e32 v[162:163], v135
	v_cvt_pk_f32_fp8_sdwa v[134:135], v135 src0_sel:WORD_1
	v_cvt_pk_f32_fp8_e32 v[170:171], v137
	v_cvt_pk_f32_fp8_sdwa v[136:137], v137 src0_sel:WORD_1
	v_pk_fma_f32 v[50:51], v[22:23], v[90:91], v[178:179] op_sel_hi:[0,1,1]
	v_pk_fma_f32 v[2:3], v[22:23], v[2:3], v[6:7] op_sel_hi:[0,1,1]
	v_pk_fma_f32 v[6:7], v[22:23], v[142:143], v[98:99] op_sel_hi:[0,1,1]
	v_pk_fma_f32 v[52:53], v[16:17], v[164:165], v[52:53] op_sel_hi:[0,1,1]
	v_pk_fma_f32 v[48:49], v[16:17], v[158:159], v[48:49] op_sel_hi:[0,1,1]
	v_pk_fma_f32 v[168:169], v[24:25], v[202:203], v[168:169] op_sel_hi:[0,1,1]
	v_cvt_pk_f32_fp8_e32 v[176:177], v139
	v_cvt_pk_f32_fp8_sdwa v[138:139], v139 src0_sel:WORD_1
	v_cvt_pk_f32_fp8_e32 v[186:187], v141
	v_cvt_pk_f32_fp8_sdwa v[140:141], v141 src0_sel:WORD_1
	v_pk_fma_f32 v[4:5], v[22:23], v[4:5], v[8:9] op_sel_hi:[0,1,1]
	v_pk_fma_f32 v[8:9], v[18:19], v[148:149], v[50:51] op_sel_hi:[0,1,1]
	v_pk_fma_f32 v[6:7], v[18:19], v[154:155], v[6:7] op_sel_hi:[0,1,1]
	v_pk_fma_f32 v[52:53], v[14:15], v[182:183], v[52:53] op_sel_hi:[0,1,1]
	v_pk_fma_f32 v[48:49], v[14:15], v[172:173], v[48:49] op_sel_hi:[0,1,1]
	v_pk_fma_f32 v[54:55], v[22:23], v[96:97], v[168:169] op_sel_hi:[0,1,1]
	v_pk_fma_f32 v[56:57], v[22:23], v[144:145], v[88:89] op_sel_hi:[0,1,1]
	v_pk_fma_f32 v[8:9], v[16:17], v[160:161], v[8:9] op_sel_hi:[0,1,1]
	v_pk_fma_f32 v[6:7], v[16:17], v[166:167], v[6:7] op_sel_hi:[0,1,1]
	v_cndmask_b32_e64 v11, v48, v52, s[6:7]
	v_pk_fma_f32 v[50:51], v[18:19], v[150:151], v[54:55] op_sel_hi:[0,1,1]
	v_pk_fma_f32 v[2:3], v[18:19], v[130:131], v[2:3] op_sel_hi:[0,1,1]
	v_pk_fma_f32 v[54:55], v[18:19], v[156:157], v[56:57] op_sel_hi:[0,1,1]
	v_pk_fma_f32 v[4:5], v[18:19], v[132:133], v[4:5] op_sel_hi:[0,1,1]
	v_pk_fma_f32 v[8:9], v[14:15], v[174:175], v[8:9] op_sel_hi:[0,1,1]
	v_pk_fma_f32 v[6:7], v[14:15], v[184:185], v[6:7] op_sel_hi:[0,1,1]
	ds_bpermute_b32 v56, v23, v11
	v_cndmask_b32_e64 v11, v49, v53, s[6:7]
	v_pk_fma_f32 v[2:3], v[16:17], v[134:135], v[2:3] op_sel_hi:[0,1,1]
	v_pk_fma_f32 v[4:5], v[16:17], v[136:137], v[4:5] op_sel_hi:[0,1,1]
	ds_bpermute_b32 v57, v23, v11
	v_cndmask_b32_e64 v11, v8, v6, s[6:7]
	v_pk_fma_f32 v[2:3], v[14:15], v[138:139], v[2:3] op_sel_hi:[0,1,1]
	v_pk_fma_f32 v[4:5], v[14:15], v[140:141], v[4:5] op_sel_hi:[0,1,1]
	ds_bpermute_b32 v58, v23, v11
	v_cndmask_b32_e64 v11, v9, v7, s[6:7]
	v_pk_fma_f32 v[50:51], v[16:17], v[162:163], v[50:51] op_sel_hi:[0,1,1]
	v_pk_fma_f32 v[54:55], v[16:17], v[170:171], v[54:55] op_sel_hi:[0,1,1]
	ds_bpermute_b32 v59, v23, v11
	v_cndmask_b32_e64 v11, v2, v4, s[6:7]
	v_pk_fma_f32 v[50:51], v[14:15], v[176:177], v[50:51] op_sel_hi:[0,1,1]
	v_pk_fma_f32 v[54:55], v[14:15], v[186:187], v[54:55] op_sel_hi:[0,1,1]
	v_cndmask_b32_e64 v48, v52, v48, s[6:7]
	ds_bpermute_b32 v52, v23, v11
	v_cndmask_b32_e64 v11, v3, v5, s[6:7]
	v_cndmask_b32_e64 v49, v53, v49, s[6:7]
	v_cndmask_b32_e64 v7, v7, v9, s[6:7]
	v_cndmask_b32_e64 v6, v6, v8, s[6:7]
	v_cndmask_b32_e64 v8, v50, v54, s[6:7]
	v_cndmask_b32_e64 v9, v51, v55, s[6:7]
	ds_bpermute_b32 v53, v23, v11
	ds_bpermute_b32 v8, v23, v8
	ds_bpermute_b32 v9, v23, v9
	v_cndmask_b32_e64 v3, v5, v3, s[6:7]
	v_cndmask_b32_e64 v2, v4, v2, s[6:7]
	s_waitcnt lgkmcnt(4)
	v_pk_add_f32 v[6:7], v[6:7], v[58:59]
	v_cndmask_b32_e64 v51, v55, v51, s[6:7]
	v_cndmask_b32_e64 v50, v54, v50, s[6:7]
	s_waitcnt lgkmcnt(2)
	v_pk_add_f32 v[2:3], v[2:3], v[52:53]
	v_pk_add_f32 v[48:49], v[48:49], v[56:57]
	s_waitcnt lgkmcnt(0)
	v_pk_add_f32 v[8:9], v[50:51], v[8:9]
	v_cndmask_b32_e64 v11, v6, v2, s[8:9]
	v_cndmask_b32_e64 v4, v48, v8, s[8:9]
	v_cndmask_b32_e64 v5, v49, v9, s[8:9]
	ds_bpermute_b32 v50, v25, v11
	v_cndmask_b32_e64 v11, v7, v3, s[8:9]
	ds_bpermute_b32 v4, v25, v4
	ds_bpermute_b32 v5, v25, v5
	ds_bpermute_b32 v51, v25, v11
	v_cndmask_b32_e64 v9, v9, v49, s[8:9]
	v_cndmask_b32_e64 v8, v8, v48, s[8:9]
	v_cndmask_b32_e64 v3, v3, v7, s[8:9]
	v_cndmask_b32_e64 v2, v2, v6, s[8:9]
	s_waitcnt lgkmcnt(1)
	v_pk_add_f32 v[4:5], v[8:9], v[4:5]
	s_waitcnt lgkmcnt(0)
	v_pk_add_f32 v[2:3], v[2:3], v[50:51]
	s_nop 0
	v_cndmask_b32_e64 v6, v4, v2, s[10:11]
	v_cndmask_b32_e64 v7, v5, v3, s[10:11]
	ds_bpermute_b32 v6, v27, v6
	ds_bpermute_b32 v7, v27, v7
	v_cndmask_b32_e64 v3, v3, v5, s[10:11]
	v_cndmask_b32_e64 v2, v2, v4, s[10:11]
	s_waitcnt lgkmcnt(0)
	v_pk_add_f32 v[2:3], v[2:3], v[6:7]
	s_nop 0
	v_pk_add_f32 v[2:3], v[20:21], v[2:3]
	global_store_dwordx2 v[12:13], v[2:3], off
	s_cbranch_vccnz .LBB0_1236
	v_readlane_b32 s16, v252, 25
	v_readlane_b32 s18, v252, 27
	v_readlane_b32 s19, v252, 28
	v_cvt_pk_bf16_f32 v6, v2, v3
	v_readlane_b32 s17, v252, 26
	v_readlane_b32 s20, v252, 29
	v_lshl_add_u64 v[4:5], v[0:1], 1, s[18:19]
	v_readlane_b32 s21, v252, 30
	v_readlane_b32 s22, v252, 31
	v_readlane_b32 s23, v252, 32
	v_readlane_b32 s24, v252, 33
	v_readlane_b32 s25, v252, 34
	v_readlane_b32 s26, v252, 35
	v_readlane_b32 s27, v252, 36
	v_readlane_b32 s28, v252, 37
	v_readlane_b32 s29, v252, 38
	v_readlane_b32 s30, v252, 39
	v_readlane_b32 s31, v252, 40
	global_store_dword v[4:5], v6, off
